# speedup vs baseline: 1.0105x; 1.0105x over previous
; template <int NK, bool BNT = false> ...
;   constexpr int NG = 4;
;   static_assert(NK % 4 == 0 && NK >= 8, "NK must be a multiple of 4");
;   const int lane = tidf & 63, wid = tidf >> 6, wr = wid >> 1, wc = wid & 1, fr = lane & 15, fq = lane >> 4;
; #pragma unroll
;   for (int m = 0; m < 4; ++m)
; #pragma unroll
;     for (int n = 0; n < 8; ++n) acc[m][n] = f32x4{0.f, 0.f, 0.f, 0.f};
;   const int sb0 = tidf * 16;
;   const int sr0 = sb0 >> 6;
;   const unsigned soff = (unsigned)(sr0 * 64 + ((((sb0 >> 4) & 3) ^ (((sr0 >> 3) & 1) << 1)) * 16));
;   const unsigned char* Abase = reinterpret_cast<const unsigned char*>(A);
;   const unsigned char* Bbase = reinterpret_cast<const unsigned char*>(B);
;   auto stage = [&](int kt, int bufc) {
;     unsigned char* sa = smem + bufc * BIG_STAGE;
;     const unsigned char* Ab = Abase + (long)kt * 8192 + soff;
;     const unsigned char* Bb = Bbase + (long)kt * 8192 + soff;
;     glds16(Ab, sa + sb0);
;     glds16(Ab + astride * 2, sa + 8192 + sb0);
;     if constexpr (BNT) {
;       glds16_nt(Bb, sa + 16384 + sb0);
;       glds16_nt(Bb + bstride * 2, sa + 24576 + sb0);
;     } else {
;       glds16(Bb, sa + 16384 + sb0);
;       glds16(Bb + bstride * 2, sa + 24576 + sb0);
;     }
;   };
;   const int rd = fr * 64 + ((fq ^ (((fr >> 3) & 1) << 1)) * 16);
; __global__ void __launch_bounds__(NTHREADS) fwd_megakernel(Params p) {
;     ...
;           for (int id = rvid; id < 4 * 320; id += Greal) {
;             int ftb, ttl;
;             tile_decode(id, 4, ftb, ttl);
;             f32x4 acc[4][8];
;             gemm_big<32>(acc, W + (long)ftb * 256 * 1024, 128 * 1024, p.mix + (long)ttl * 256 * 1024, 128 * 1024, smem_all, tid_full);
.LBB0_67:
	s_ashr_i32 s9, s15, 31
	s_lshr_b32 s9, s9, 27
	s_add_i32 s9, s15, s9
	s_ashr_i32 s10, s9, 5
	s_and_b32 s9, s9, 0xffe0
	s_sub_i32 s9, s15, s9
	s_bfe_i32 s11, s9, 0x80000
	s_bfe_u32 s11, s11, 0x2000d
	s_add_i32 s11, s9, s11
	s_bfe_i32 s14, s11, 0x80000
	s_and_b32 s11, s11, 0xfffc
	s_sext_i32_i16 s17, s14
	s_sub_i32 s14, s9, s11
	s_lshl_b32 s9, s10, 3
	s_ashr_i32 s10, s17, 2
	s_bfe_i64 s[18:19], s[14:15], 0x80000
	s_add_i32 s10, s9, s10
	s_lshl_b64 s[18:19], s[18:19], 19
	s_add_u32 s20, s6, s18
	s_addc_u32 s21, s7, s19
	s_ashr_i32 s11, s10, 31
	v_readlane_b32 s64, v252, 4
	s_lshl_b64 s[22:23], s[10:11], 19
	v_readlane_b32 s76, v252, 16
	v_readfirstlane_b32 s9, v166
	v_add_u32_e32 v146, 0x2000, v166
	v_readlane_b32 s77, v252, 17
	s_add_u32 s24, s76, s22
	v_lshl_add_u64 v[130:131], s[20:21], 0, v[132:133]
	s_mov_b32 m0, s9
	s_mov_b64 s[20:21], 0x40000
	v_readfirstlane_b32 s9, v146
	v_add_u32_e32 v147, 0x4000, v166
	s_addc_u32 s25, s77, s23
	global_load_lds_dwordx4 v[130:131], off
	v_lshl_add_u64 v[0:1], v[130:131], 0, s[20:21]
	s_mov_b32 m0, s9
	v_readfirstlane_b32 s9, v147
	v_add_u32_e32 v148, 0x6000, v166
	v_lshl_add_u64 v[128:129], s[24:25], 0, v[132:133]
	global_load_lds_dwordx4 v[0:1], off
	s_mov_b32 m0, s9
	v_readfirstlane_b32 s9, v148
	v_add_u32_e32 v149, 0x8000, v166
	global_load_lds_dwordx4 v[128:129], off
	v_lshl_add_u64 v[0:1], v[128:129], 0, s[20:21]
	s_mov_b32 m0, s9
	s_mov_b64 s[20:21], 0x2000
	v_readfirstlane_b32 s9, v149
	v_add_u32_e32 v150, 0xa000, v166
	global_load_lds_dwordx4 v[0:1], off
	v_lshl_add_u64 v[0:1], v[130:131], 0, s[20:21]
	v_lshl_add_u64 v[2:3], v[128:129], 0, s[20:21]
	s_mov_b32 m0, s9
	s_mov_b64 s[20:21], 0x42000
	v_readfirstlane_b32 s9, v150
	v_add_u32_e32 v151, 0xc000, v166
	global_load_lds_dwordx4 v[0:1], off
	v_lshl_add_u64 v[0:1], v[130:131], 0, s[20:21]
	s_mov_b32 m0, s9
	v_readfirstlane_b32 s9, v151
	v_add_u32_e32 v152, 0xe000, v166
	global_load_lds_dwordx4 v[0:1], off
	s_mov_b32 m0, s9
	v_readfirstlane_b32 s9, v152
	v_add_u32_e32 v154, 0x10000, v166
	global_load_lds_dwordx4 v[2:3], off
	v_lshl_add_u64 v[0:1], v[128:129], 0, s[20:21]
	s_mov_b32 m0, s9
	v_readfirstlane_b32 s9, v154
	v_add_u32_e32 v155, 0x12000, v166
	global_load_lds_dwordx4 v[0:1], off
	v_lshl_add_u64 v[0:1], v[130:131], 0, s[94:95]
	s_mov_b32 m0, s9
	s_mov_b64 s[20:21], 0x44000
	v_readfirstlane_b32 s9, v155
	v_add_u32_e32 v156, 0x14000, v166
	global_load_lds_dwordx4 v[0:1], off
	v_lshl_add_u64 v[0:1], v[130:131], 0, s[20:21]
	s_mov_b32 m0, s9
	v_readfirstlane_b32 s9, v156
	v_add_u32_e32 v157, 0x16000, v166
	v_lshl_add_u64 v[2:3], v[128:129], 0, s[94:95]
	global_load_lds_dwordx4 v[0:1], off
	s_mov_b32 m0, s9
	v_readfirstlane_b32 s9, v157
	global_load_lds_dwordx4 v[2:3], off
	v_lshl_add_u64 v[0:1], v[128:129], 0, s[20:21]
	s_mov_b32 m0, s9
	v_lshl_add_u64 v[138:139], v[134:135], 0, s[18:19]
	global_load_lds_dwordx4 v[0:1], off
	v_mov_b32_e32 v0, 0
	v_lshl_add_u64 v[140:141], v[136:137], 0, s[22:23]
	s_mov_b64 s[36:37], 0
	v_mov_b32_e32 v1, v0
	v_mov_b32_e32 v2, v0
	v_mov_b32_e32 v3, v0
	v_mov_b32_e32 v4, v0
	s_waitcnt lgkmcnt(0)
	v_mov_b32_e32 v5, v0
	v_mov_b32_e32 v6, v0
	v_mov_b32_e32 v7, v0
	v_mov_b32_e32 v8, v0
	v_mov_b32_e32 v9, v0
	v_mov_b32_e32 v10, v0
	v_mov_b32_e32 v11, v0
	v_mov_b32_e32 v12, v0
	v_mov_b32_e32 v13, v0
	v_mov_b32_e32 v14, v0
	v_mov_b32_e32 v15, v0
	v_mov_b32_e32 v32, v0
	v_mov_b32_e32 v33, v0
	v_mov_b32_e32 v34, v0
	v_mov_b32_e32 v35, v0
	v_mov_b32_e32 v36, v0
	v_mov_b32_e32 v37, v0
	v_mov_b32_e32 v38, v0
	v_mov_b32_e32 v39, v0
	v_mov_b32_e32 v40, v0
	v_mov_b32_e32 v41, v0
	v_mov_b32_e32 v42, v0
	v_mov_b32_e32 v43, v0
	v_mov_b32_e32 v44, v0
	v_mov_b32_e32 v45, v0
	v_mov_b32_e32 v46, v0
	v_mov_b32_e32 v47, v0
	v_mov_b32_e32 v16, v0
	v_mov_b32_e32 v17, v0
	v_mov_b32_e32 v18, v0
	v_mov_b32_e32 v19, v0
	v_mov_b32_e32 v20, v0
	v_mov_b32_e32 v21, v0
	v_mov_b32_e32 v22, v0
	v_mov_b32_e32 v23, v0
	v_mov_b32_e32 v24, v0
	v_mov_b32_e32 v25, v0
	v_mov_b32_e32 v26, v0
	v_mov_b32_e32 v27, v0
	v_mov_b32_e32 v28, v0
	v_mov_b32_e32 v29, v0
	v_mov_b32_e32 v30, v0
	v_mov_b32_e32 v31, v0
	v_mov_b32_e32 v64, v0
	v_mov_b32_e32 v65, v0
	v_mov_b32_e32 v66, v0
	v_mov_b32_e32 v67, v0
	v_mov_b32_e32 v68, v0
	v_mov_b32_e32 v69, v0
	v_mov_b32_e32 v70, v0
	v_mov_b32_e32 v71, v0
	v_mov_b32_e32 v76, v0
	v_mov_b32_e32 v77, v0
	v_mov_b32_e32 v78, v0
	v_mov_b32_e32 v79, v0
	v_mov_b32_e32 v88, v0
	v_mov_b32_e32 v89, v0
	v_mov_b32_e32 v90, v0
	v_mov_b32_e32 v91, v0
	v_mov_b32_e32 v48, v0
	v_mov_b32_e32 v49, v0
	v_mov_b32_e32 v50, v0
	v_mov_b32_e32 v51, v0
	v_mov_b32_e32 v52, v0
	v_mov_b32_e32 v53, v0
	v_mov_b32_e32 v54, v0
	v_mov_b32_e32 v55, v0
	v_mov_b32_e32 v56, v0
	v_mov_b32_e32 v57, v0
	v_mov_b32_e32 v58, v0
	v_mov_b32_e32 v59, v0
	v_mov_b32_e32 v60, v0
	v_mov_b32_e32 v61, v0
	v_mov_b32_e32 v62, v0
	v_mov_b32_e32 v63, v0
	v_mov_b32_e32 v96, v0
	v_mov_b32_e32 v97, v0
	v_mov_b32_e32 v98, v0
	v_mov_b32_e32 v99, v0
	v_mov_b32_e32 v100, v0
	v_mov_b32_e32 v101, v0
	v_mov_b32_e32 v102, v0
	v_mov_b32_e32 v103, v0
	v_mov_b32_e32 v104, v0
	v_mov_b32_e32 v105, v0
	v_mov_b32_e32 v106, v0
	v_mov_b32_e32 v107, v0
	v_mov_b32_e32 v108, v0
	v_mov_b32_e32 v109, v0
	v_mov_b32_e32 v110, v0
	v_mov_b32_e32 v111, v0
	v_mov_b32_e32 v72, v0
	v_mov_b32_e32 v73, v0
	v_mov_b32_e32 v74, v0
	v_mov_b32_e32 v75, v0
	v_mov_b32_e32 v80, v0
	v_mov_b32_e32 v81, v0
	v_mov_b32_e32 v82, v0
	v_mov_b32_e32 v83, v0
	v_mov_b32_e32 v84, v0
	v_mov_b32_e32 v85, v0
	v_mov_b32_e32 v86, v0
	v_mov_b32_e32 v87, v0
	v_mov_b32_e32 v92, v0
	v_mov_b32_e32 v93, v0
	v_mov_b32_e32 v94, v0
	v_mov_b32_e32 v95, v0
	v_mov_b32_e32 v112, v0
	v_mov_b32_e32 v113, v0
	v_mov_b32_e32 v114, v0
	v_mov_b32_e32 v115, v0
	v_mov_b32_e32 v116, v0
	v_mov_b32_e32 v117, v0
	v_mov_b32_e32 v118, v0
	v_mov_b32_e32 v119, v0
	v_mov_b32_e32 v120, v0
	v_mov_b32_e32 v121, v0
	v_mov_b32_e32 v122, v0
	v_mov_b32_e32 v123, v0
	v_mov_b32_e32 v124, v0
	v_mov_b32_e32 v125, v0
	v_mov_b32_e32 v126, v0
	v_mov_b32_e32 v127, v0
	v_readlane_b32 s65, v252, 5
	v_readlane_b32 s66, v252, 6
	v_readlane_b32 s67, v252, 7
	v_readlane_b32 s68, v252, 8
	v_readlane_b32 s69, v252, 9
	v_readlane_b32 s70, v252, 10
	v_readlane_b32 s71, v252, 11
	v_readlane_b32 s72, v252, 12
	v_readlane_b32 s73, v252, 13
	v_readlane_b32 s74, v252, 14
	v_readlane_b32 s75, v252, 15
	v_readlane_b32 s78, v252, 18
	v_readlane_b32 s79, v252, 19
	s_waitcnt vmcnt(8)
	s_barrier
	v_add_u32_e32 v162, 0x10000, v167
	v_or_b32_e32 v163, 0x10000, v169
	v_add_u32_e32 v176, 0x18000, v167
	v_or_b32_e32 v179, 0x18000, v169
	v_add_u32_e32 v210, 0x10000, v167
	v_or_b32_e32 v211, 0x10000, v169
	v_add_u32_e32 v212, 0x18000, v167
	v_or_b32_e32 v213, 0x18000, v169
	ds_read_b128 v[216:219], v167
	ds_read_b128 v[220:223], v167 offset:1024
	ds_read_b128 v[224:227], v167 offset:2048
	ds_read_b128 v[228:231], v167 offset:3072
	ds_read_b128 v[232:235], v168 offset:16384
	ds_read_b128 v[236:239], v168 offset:17408
	ds_read_b128 v[240:243], v168 offset:18432
	ds_read_b128 v[244:247], v168 offset:19456
; #define BIG_SYNC(N)                                              \
;   asm volatile("s_waitcnt vmcnt(%0)" ::"n"(N) : "memory");       \
;   __builtin_amdgcn_s_barrier();                                  \
;   asm volatile("" ::: "memory");                                 \
;   __builtin_amdgcn_sched_barrier(0);
; template <int NK, bool BNT = false> ...
;     ...
;   auto kstep = [&](int T, int cur, int nxt, bool do_stage) {
;     const unsigned char* sa = smem + cur * BIG_STAGE;
;     bf16x8 af[4], bfr[4];
; #pragma unroll
;     for (int m = 0; m < 4; ++m) af[m] = *reinterpret_cast<const bf16x8*>(sa + aoff + m * 1024);
; #pragma unroll
;     for (int n = 0; n < 4; ++n) bfr[n] = *reinterpret_cast<const bf16x8*>(sa + boff + n * 1024);
;     __builtin_amdgcn_sched_barrier(0);
;     if (do_stage) stage(T + 3, nxt);
; #pragma unroll
;     for (int m = 0; m < 4; ++m)
; #pragma unroll
;       for (int n = 0; n < 4; ++n) acc[m][n] = __builtin_amdgcn_mfma_f32_16x16x32_bf16(af[m], bfr[n], acc[m][n], 0, 0, 0);
;     if (do_stage) {
; #pragma unroll
;       for (int q = 0; q < NG; ++q) {
;         __builtin_amdgcn_sched_group_barrier(0x008, 3, 0);
;         __builtin_amdgcn_sched_group_barrier(0x010, 1, 0);
;       }
;       __builtin_amdgcn_sched_group_barrier(0x008, 16 - 3 * NG, 0);
;     }
;     __builtin_amdgcn_sched_barrier(0);
; #pragma unroll
;     for (int n = 0; n < 4; ++n) bfr[n] = *reinterpret_cast<const bf16x8*>(sa + boff + (4 + n) * 1024);
; #pragma unroll
;     for (int m = 0; m < 4; ++m)
; #pragma unroll
;       for (int n = 0; n < 4; ++n)
;         acc[m][4 + n] = __builtin_amdgcn_mfma_f32_16x16x32_bf16(af[m], bfr[n], acc[m][4 + n], 0, 0, 0);
;     __builtin_amdgcn_sched_barrier(0);
;   };
;     ...
;   stage(0, 0);
;   stage(1, 1);
;   stage(2, 2);
;   for (int it = 0; it < NK / 4 - 1; ++it) {
;     const int t = it * 4;
;     BIG_SYNC(2 * NG); kstep(t, 0, 3, true);
;     BIG_SYNC(2 * NG); kstep(t + 1, 1, 0, true);
;     BIG_SYNC(2 * NG); kstep(t + 2, 2, 1, true);
;     BIG_SYNC(2 * NG); kstep(t + 3, 3, 2, true);
;   }
.LBB0_68:
	s_waitcnt lgkmcnt(3)
	v_mfma_f32_16x16x32_bf16 v[124:127], v[216:219], v[232:235], v[124:127]
	v_mfma_f32_16x16x32_bf16 v[108:111], v[220:223], v[232:235], v[108:111]
	v_mfma_f32_16x16x32_bf16 v[88:91], v[224:227], v[232:235], v[88:91]
	s_waitcnt vmcnt(4)
	s_barrier
	v_add_u32_e32 v158, 0x18000, v166
	v_lshl_add_u64 v[144:145], v[138:139], 0, s[36:37]
	v_mfma_f32_16x16x32_bf16 v[44:47], v[228:231], v[232:235], v[44:47]
	v_readfirstlane_b32 s9, v158
	v_add_u32_e32 v159, 0x1a000, v166
	s_waitcnt lgkmcnt(2)
	v_mfma_f32_16x16x32_bf16 v[120:123], v[216:219], v[236:239], v[120:123]
	ds_read_b128 v[232:235], v168 offset:20480
	v_mfma_f32_16x16x32_bf16 v[104:107], v[220:223], v[236:239], v[104:107]
	v_lshl_add_u64 v[160:161], v[144:145], 0, s[60:61]
	s_mov_b32 m0, s9
	v_mfma_f32_16x16x32_bf16 v[76:79], v[224:227], v[236:239], v[76:79]
	v_readfirstlane_b32 s9, v159
	v_mfma_f32_16x16x32_bf16 v[40:43], v[228:231], v[236:239], v[40:43]
	v_lshl_add_u64 v[142:143], v[140:141], 0, s[36:37]
	s_waitcnt lgkmcnt(2)
	v_mfma_f32_16x16x32_bf16 v[116:119], v[216:219], v[240:243], v[116:119]
	ds_read_b128 v[236:239], v168 offset:21504
	v_mfma_f32_16x16x32_bf16 v[100:103], v[220:223], v[240:243], v[100:103]
	v_lshl_add_u64 v[182:183], v[142:143], 0, s[60:61]
	v_mfma_f32_16x16x32_bf16 v[68:71], v[224:227], v[240:243], v[68:71]
	global_load_lds_dwordx4 v[160:161], off
	v_mfma_f32_16x16x32_bf16 v[36:39], v[228:231], v[240:243], v[36:39]
	v_lshl_add_u64 v[160:161], v[144:145], 0, s[80:81]
	s_waitcnt lgkmcnt(2)
	v_mfma_f32_16x16x32_bf16 v[112:115], v[216:219], v[244:247], v[112:115]
	ds_read_b128 v[240:243], v168 offset:22528
	v_mfma_f32_16x16x32_bf16 v[96:99], v[220:223], v[244:247], v[96:99]
	s_mov_b32 m0, s9
	v_mfma_f32_16x16x32_bf16 v[64:67], v[224:227], v[244:247], v[64:67]
	global_load_lds_dwordx4 v[160:161], off
	v_mfma_f32_16x16x32_bf16 v[32:35], v[228:231], v[244:247], v[32:35]
	v_add_u32_e32 v160, 0x1c000, v166
	s_waitcnt lgkmcnt(2)
	v_mfma_f32_16x16x32_bf16 v[92:95], v[216:219], v[232:235], v[92:95]
	ds_read_b128 v[244:247], v168 offset:23552
	v_mfma_f32_16x16x32_bf16 v[60:63], v[220:223], v[232:235], v[60:63]
	ds_read_b128 v[186:189], v167 offset:32768
	v_mfma_f32_16x16x32_bf16 v[28:31], v[224:227], v[232:235], v[28:31]
	ds_read_b128 v[190:193], v167 offset:33792
	v_mfma_f32_16x16x32_bf16 v[12:15], v[228:231], v[232:235], v[12:15]
	ds_read_b128 v[194:197], v167 offset:34816
	s_waitcnt lgkmcnt(5)
	v_mfma_f32_16x16x32_bf16 v[84:87], v[216:219], v[236:239], v[84:87]
	ds_read_b128 v[202:205], v167 offset:35840
	ds_read_b128 v[232:235], v168 offset:49152
	v_mfma_f32_16x16x32_bf16 v[56:59], v[220:223], v[236:239], v[56:59]
	v_add_u32_e32 v161, 0x1e000, v166
	v_mfma_f32_16x16x32_bf16 v[24:27], v[224:227], v[236:239], v[24:27]
	v_readfirstlane_b32 s9, v160
	v_mfma_f32_16x16x32_bf16 v[8:11], v[228:231], v[236:239], v[8:11]
	s_mov_b32 m0, s9
	s_waitcnt lgkmcnt(6)
	v_mfma_f32_16x16x32_bf16 v[80:83], v[216:219], v[240:243], v[80:83]
	ds_read_b128 v[236:239], v168 offset:50176
	v_mfma_f32_16x16x32_bf16 v[52:55], v[220:223], v[240:243], v[52:55]
	v_readfirstlane_b32 s9, v161
	v_mfma_f32_16x16x32_bf16 v[20:23], v[224:227], v[240:243], v[20:23]
	global_load_lds_dwordx4 v[182:183], off
	v_mfma_f32_16x16x32_bf16 v[4:7], v[228:231], v[240:243], v[4:7]
	v_lshl_add_u64 v[182:183], v[142:143], 0, s[80:81]
	s_waitcnt lgkmcnt(6)
	v_mfma_f32_16x16x32_bf16 v[72:75], v[216:219], v[244:247], v[72:75]
	ds_read_b128 v[240:243], v168 offset:51200
	v_mfma_f32_16x16x32_bf16 v[48:51], v[220:223], v[244:247], v[48:51]
	s_mov_b32 m0, s9
	v_mfma_f32_16x16x32_bf16 v[16:19], v[224:227], v[244:247], v[16:19]
	global_load_lds_dwordx4 v[182:183], off
	v_mfma_f32_16x16x32_bf16 v[0:3], v[228:231], v[244:247], v[0:3]
	ds_read_b128 v[244:247], v168 offset:52224
	s_waitcnt lgkmcnt(3)
	v_mfma_f32_16x16x32_bf16 v[124:127], v[186:189], v[232:235], v[124:127]
	v_mfma_f32_16x16x32_bf16 v[108:111], v[190:193], v[232:235], v[108:111]
	v_mfma_f32_16x16x32_bf16 v[88:91], v[194:197], v[232:235], v[88:91]
	s_waitcnt vmcnt(4)
	s_barrier
	v_readfirstlane_b32 s9, v166
	v_mfma_f32_16x16x32_bf16 v[44:47], v[202:205], v[232:235], v[44:47]
	v_lshl_add_u64 v[182:183], v[144:145], 0, s[62:63]
	s_waitcnt lgkmcnt(2)
	v_mfma_f32_16x16x32_bf16 v[120:123], v[186:189], v[236:239], v[120:123]
	ds_read_b128 v[232:235], v168 offset:53248
	v_mfma_f32_16x16x32_bf16 v[104:107], v[190:193], v[236:239], v[104:107]
	s_mov_b32 m0, s9
	v_mfma_f32_16x16x32_bf16 v[76:79], v[194:197], v[236:239], v[76:79]
	v_readfirstlane_b32 s9, v146
	v_mfma_f32_16x16x32_bf16 v[40:43], v[202:205], v[236:239], v[40:43]
	v_lshl_add_u64 v[198:199], v[142:143], 0, s[62:63]
	s_waitcnt lgkmcnt(2)
	v_mfma_f32_16x16x32_bf16 v[116:119], v[186:189], v[240:243], v[116:119]
	ds_read_b128 v[236:239], v168 offset:54272
	v_mfma_f32_16x16x32_bf16 v[100:103], v[190:193], v[240:243], v[100:103]
	global_load_lds_dwordx4 v[182:183], off
	v_mfma_f32_16x16x32_bf16 v[68:71], v[194:197], v[240:243], v[68:71]
	v_lshl_add_u64 v[182:183], v[144:145], 0, s[0:1]
	v_mfma_f32_16x16x32_bf16 v[36:39], v[202:205], v[240:243], v[36:39]
	s_mov_b32 m0, s9
	s_waitcnt lgkmcnt(2)
	v_mfma_f32_16x16x32_bf16 v[112:115], v[186:189], v[244:247], v[112:115]
	ds_read_b128 v[240:243], v168 offset:55296
	v_mfma_f32_16x16x32_bf16 v[96:99], v[190:193], v[244:247], v[96:99]
	v_readfirstlane_b32 s9, v147
	v_mfma_f32_16x16x32_bf16 v[64:67], v[194:197], v[244:247], v[64:67]
	global_load_lds_dwordx4 v[182:183], off
	v_mfma_f32_16x16x32_bf16 v[32:35], v[202:205], v[244:247], v[32:35]
	s_mov_b32 m0, s9
	s_waitcnt lgkmcnt(2)
; #define BIG_SYNC(N)                                              \
;   asm volatile("s_waitcnt vmcnt(%0)" ::"n"(N) : "memory");       \
;   __builtin_amdgcn_s_barrier();                                  \
;   asm volatile("" ::: "memory");                                 \
;   __builtin_amdgcn_sched_barrier(0);
; template <int NK, bool BNT = false> ...
;     ...
;   auto kstep = [&](int T, int cur, int nxt, bool do_stage) {
;     const unsigned char* sa = smem + cur * BIG_STAGE;
;     bf16x8 af[4], bfr[4];
; #pragma unroll
;     for (int m = 0; m < 4; ++m) af[m] = *reinterpret_cast<const bf16x8*>(sa + aoff + m * 1024);
; #pragma unroll
;     for (int n = 0; n < 4; ++n) bfr[n] = *reinterpret_cast<const bf16x8*>(sa + boff + n * 1024);
;     __builtin_amdgcn_sched_barrier(0);
;     if (do_stage) stage(T + 3, nxt);
; #pragma unroll
;     for (int m = 0; m < 4; ++m)
; #pragma unroll
;       for (int n = 0; n < 4; ++n) acc[m][n] = __builtin_amdgcn_mfma_f32_16x16x32_bf16(af[m], bfr[n], acc[m][n], 0, 0, 0);
;     if (do_stage) {
; #pragma unroll
;       for (int q = 0; q < NG; ++q) {
;         __builtin_amdgcn_sched_group_barrier(0x008, 3, 0);
;         __builtin_amdgcn_sched_group_barrier(0x010, 1, 0);
;       }
;       __builtin_amdgcn_sched_group_barrier(0x008, 16 - 3 * NG, 0);
;     }
;     __builtin_amdgcn_sched_barrier(0);
; #pragma unroll
;     for (int n = 0; n < 4; ++n) bfr[n] = *reinterpret_cast<const bf16x8*>(sa + boff + (4 + n) * 1024);
; #pragma unroll
;     for (int m = 0; m < 4; ++m)
; #pragma unroll
;       for (int n = 0; n < 4; ++n)
;         acc[m][4 + n] = __builtin_amdgcn_mfma_f32_16x16x32_bf16(af[m], bfr[n], acc[m][4 + n], 0, 0, 0);
;     __builtin_amdgcn_sched_barrier(0);
;   };
;     ...
;   stage(0, 0);
;   stage(1, 1);
;   stage(2, 2);
;   for (int it = 0; it < NK / 4 - 1; ++it) {
;     const int t = it * 4;
;     BIG_SYNC(2 * NG); kstep(t, 0, 3, true);
;     BIG_SYNC(2 * NG); kstep(t + 1, 1, 0, true);
;     BIG_SYNC(2 * NG); kstep(t + 2, 2, 1, true);
;     BIG_SYNC(2 * NG); kstep(t + 3, 3, 2, true);
;   }
	v_mfma_f32_16x16x32_bf16 v[92:95], v[186:189], v[232:235], v[92:95]
	ds_read_b128 v[244:247], v168 offset:56320
	v_mfma_f32_16x16x32_bf16 v[60:63], v[190:193], v[232:235], v[60:63]
	ds_read_b128 v[216:219], v210
	v_mfma_f32_16x16x32_bf16 v[28:31], v[194:197], v[232:235], v[28:31]
	ds_read_b128 v[220:223], v210 offset:1024
	v_mfma_f32_16x16x32_bf16 v[12:15], v[202:205], v[232:235], v[12:15]
	ds_read_b128 v[224:227], v210 offset:2048
	s_waitcnt lgkmcnt(5)
	v_mfma_f32_16x16x32_bf16 v[84:87], v[186:189], v[236:239], v[84:87]
	ds_read_b128 v[228:231], v210 offset:3072
	ds_read_b128 v[232:235], v211
	v_mfma_f32_16x16x32_bf16 v[56:59], v[190:193], v[236:239], v[56:59]
	v_readfirstlane_b32 s9, v148
	v_mfma_f32_16x16x32_bf16 v[24:27], v[194:197], v[236:239], v[24:27]
	v_lshl_add_u64 v[182:183], v[142:143], 0, s[0:1]
	v_mfma_f32_16x16x32_bf16 v[8:11], v[202:205], v[236:239], v[8:11]
	global_load_lds_dwordx4 v[198:199], off
	s_waitcnt lgkmcnt(6)
	v_mfma_f32_16x16x32_bf16 v[80:83], v[186:189], v[240:243], v[80:83]
	ds_read_b128 v[236:239], v211 offset:1024
	v_mfma_f32_16x16x32_bf16 v[52:55], v[190:193], v[240:243], v[52:55]
	s_mov_b32 m0, s9
	v_mfma_f32_16x16x32_bf16 v[20:23], v[194:197], v[240:243], v[20:23]
	global_load_lds_dwordx4 v[182:183], off
	v_mfma_f32_16x16x32_bf16 v[4:7], v[202:205], v[240:243], v[4:7]
	s_waitcnt lgkmcnt(6)
	v_mfma_f32_16x16x32_bf16 v[72:75], v[186:189], v[244:247], v[72:75]
	ds_read_b128 v[240:243], v211 offset:2048
	v_mfma_f32_16x16x32_bf16 v[48:51], v[190:193], v[244:247], v[48:51]
	v_mfma_f32_16x16x32_bf16 v[16:19], v[194:197], v[244:247], v[16:19]
	v_mfma_f32_16x16x32_bf16 v[0:3], v[202:205], v[244:247], v[0:3]
	ds_read_b128 v[244:247], v211 offset:3072
	s_waitcnt lgkmcnt(3)
	v_mfma_f32_16x16x32_bf16 v[124:127], v[216:219], v[232:235], v[124:127]
	v_mfma_f32_16x16x32_bf16 v[108:111], v[220:223], v[232:235], v[108:111]
	v_mfma_f32_16x16x32_bf16 v[88:91], v[224:227], v[232:235], v[88:91]
	s_waitcnt vmcnt(4)
	s_barrier
	v_add_u32_e32 v162, 0x10000, v167
	v_or_b32_e32 v163, 0x10000, v169
	v_mfma_f32_16x16x32_bf16 v[44:47], v[228:231], v[232:235], v[44:47]
	v_add_u32_e32 v164, 0x10400, v169
	v_add_u32_e32 v165, 0x10800, v169
	s_waitcnt lgkmcnt(2)
	v_mfma_f32_16x16x32_bf16 v[120:123], v[216:219], v[236:239], v[120:123]
	ds_read_b128 v[232:235], v211 offset:4096
	v_mfma_f32_16x16x32_bf16 v[104:107], v[220:223], v[236:239], v[104:107]
	v_add_u32_e32 v172, 0x10c00, v169
	v_mfma_f32_16x16x32_bf16 v[76:79], v[224:227], v[236:239], v[76:79]
	v_readfirstlane_b32 s9, v149
	v_mfma_f32_16x16x32_bf16 v[40:43], v[228:231], v[236:239], v[40:43]
	v_lshl_add_u64 v[174:175], v[144:145], 0, s[2:3]
	s_waitcnt lgkmcnt(2)
	v_mfma_f32_16x16x32_bf16 v[116:119], v[216:219], v[240:243], v[116:119]
	ds_read_b128 v[236:239], v211 offset:5120
	v_mfma_f32_16x16x32_bf16 v[100:103], v[220:223], v[240:243], v[100:103]
	s_mov_b32 m0, s9
	v_mfma_f32_16x16x32_bf16 v[68:71], v[224:227], v[240:243], v[68:71]
	v_readfirstlane_b32 s9, v150
	v_mfma_f32_16x16x32_bf16 v[36:39], v[228:231], v[240:243], v[36:39]
	v_lshl_add_u64 v[178:179], v[142:143], 0, s[2:3]
	s_waitcnt lgkmcnt(2)
	v_mfma_f32_16x16x32_bf16 v[112:115], v[216:219], v[244:247], v[112:115]
	ds_read_b128 v[240:243], v211 offset:6144
	v_mfma_f32_16x16x32_bf16 v[96:99], v[220:223], v[244:247], v[96:99]
	global_load_lds_dwordx4 v[174:175], off
	v_mfma_f32_16x16x32_bf16 v[64:67], v[224:227], v[244:247], v[64:67]
	v_lshl_add_u64 v[174:175], v[144:145], 0, s[52:53]
	v_mfma_f32_16x16x32_bf16 v[32:35], v[228:231], v[244:247], v[32:35]
	s_mov_b32 m0, s9
	s_waitcnt lgkmcnt(2)
	v_mfma_f32_16x16x32_bf16 v[92:95], v[216:219], v[232:235], v[92:95]
	ds_read_b128 v[244:247], v211 offset:7168
	v_mfma_f32_16x16x32_bf16 v[60:63], v[220:223], v[232:235], v[60:63]
	ds_read_b128 v[186:189], v210 offset:32768
	v_mfma_f32_16x16x32_bf16 v[28:31], v[224:227], v[232:235], v[28:31]
	ds_read_b128 v[190:193], v210 offset:33792
	v_mfma_f32_16x16x32_bf16 v[12:15], v[228:231], v[232:235], v[12:15]
	ds_read_b128 v[194:197], v210 offset:34816
	s_waitcnt lgkmcnt(5)
	v_mfma_f32_16x16x32_bf16 v[84:87], v[216:219], v[236:239], v[84:87]
	ds_read_b128 v[202:205], v210 offset:35840
	ds_read_b128 v[232:235], v211 offset:32768
	v_mfma_f32_16x16x32_bf16 v[56:59], v[220:223], v[236:239], v[56:59]
	v_readfirstlane_b32 s9, v151
	v_mfma_f32_16x16x32_bf16 v[24:27], v[224:227], v[236:239], v[24:27]
	global_load_lds_dwordx4 v[174:175], off
	v_mfma_f32_16x16x32_bf16 v[8:11], v[228:231], v[236:239], v[8:11]
	s_mov_b32 m0, s9
	s_waitcnt lgkmcnt(6)
	v_mfma_f32_16x16x32_bf16 v[80:83], v[216:219], v[240:243], v[80:83]
	ds_read_b128 v[236:239], v211 offset:33792
	v_mfma_f32_16x16x32_bf16 v[52:55], v[220:223], v[240:243], v[52:55]
	v_readfirstlane_b32 s9, v152
	v_mfma_f32_16x16x32_bf16 v[20:23], v[224:227], v[240:243], v[20:23]
	v_lshl_add_u64 v[174:175], v[142:143], 0, s[52:53]
	v_mfma_f32_16x16x32_bf16 v[4:7], v[228:231], v[240:243], v[4:7]
	global_load_lds_dwordx4 v[178:179], off
	s_waitcnt lgkmcnt(6)
	v_mfma_f32_16x16x32_bf16 v[72:75], v[216:219], v[244:247], v[72:75]
	ds_read_b128 v[240:243], v211 offset:34816
	v_mfma_f32_16x16x32_bf16 v[48:51], v[220:223], v[244:247], v[48:51]
	s_mov_b32 m0, s9
	v_mfma_f32_16x16x32_bf16 v[16:19], v[224:227], v[244:247], v[16:19]
	global_load_lds_dwordx4 v[174:175], off
	v_mfma_f32_16x16x32_bf16 v[0:3], v[228:231], v[244:247], v[0:3]
	ds_read_b128 v[244:247], v211 offset:35840
	v_add_u32_e32 v173, 0x11000, v169
	v_add_u32_e32 v174, 0x11400, v169
	v_add_u32_e32 v175, 0x11800, v169
	v_add_u32_e32 v178, 0x11c00, v169
	s_waitcnt lgkmcnt(3)
	v_mfma_f32_16x16x32_bf16 v[124:127], v[186:189], v[232:235], v[124:127]
	v_mfma_f32_16x16x32_bf16 v[108:111], v[190:193], v[232:235], v[108:111]
	v_mfma_f32_16x16x32_bf16 v[88:91], v[194:197], v[232:235], v[88:91]
	s_waitcnt vmcnt(4)
	s_barrier
; #define BIG_SYNC(N)                                              \
;   asm volatile("s_waitcnt vmcnt(%0)" ::"n"(N) : "memory");       \
;   __builtin_amdgcn_s_barrier();                                  \
;   asm volatile("" ::: "memory");                                 \
;   __builtin_amdgcn_sched_barrier(0);
; template <int NK, bool BNT = false> ...
;     ...
;   auto kstep = [&](int T, int cur, int nxt, bool do_stage) {
;     const unsigned char* sa = smem + cur * BIG_STAGE;
;     bf16x8 af[4], bfr[4];
; #pragma unroll
;     for (int m = 0; m < 4; ++m) af[m] = *reinterpret_cast<const bf16x8*>(sa + aoff + m * 1024);
; #pragma unroll
;     for (int n = 0; n < 4; ++n) bfr[n] = *reinterpret_cast<const bf16x8*>(sa + boff + n * 1024);
;     __builtin_amdgcn_sched_barrier(0);
;     if (do_stage) stage(T + 3, nxt);
; #pragma unroll
;     for (int m = 0; m < 4; ++m)
; #pragma unroll
;       for (int n = 0; n < 4; ++n) acc[m][n] = __builtin_amdgcn_mfma_f32_16x16x32_bf16(af[m], bfr[n], acc[m][n], 0, 0, 0);
;     if (do_stage) {
; #pragma unroll
;       for (int q = 0; q < NG; ++q) {
;         __builtin_amdgcn_sched_group_barrier(0x008, 3, 0);
;         __builtin_amdgcn_sched_group_barrier(0x010, 1, 0);
;       }
;       __builtin_amdgcn_sched_group_barrier(0x008, 16 - 3 * NG, 0);
;     }
;     __builtin_amdgcn_sched_barrier(0);
; #pragma unroll
;     for (int n = 0; n < 4; ++n) bfr[n] = *reinterpret_cast<const bf16x8*>(sa + boff + (4 + n) * 1024);
; #pragma unroll
;     for (int m = 0; m < 4; ++m)
; #pragma unroll
;       for (int n = 0; n < 4; ++n)
;         acc[m][4 + n] = __builtin_amdgcn_mfma_f32_16x16x32_bf16(af[m], bfr[n], acc[m][4 + n], 0, 0, 0);
;     __builtin_amdgcn_sched_barrier(0);
;   };
;     ...
;   stage(0, 0);
;   stage(1, 1);
;   stage(2, 2);
;   for (int it = 0; it < NK / 4 - 1; ++it) {
;     const int t = it * 4;
;     BIG_SYNC(2 * NG); kstep(t, 0, 3, true);
;     BIG_SYNC(2 * NG); kstep(t + 1, 1, 0, true);
;     BIG_SYNC(2 * NG); kstep(t + 2, 2, 1, true);
;     BIG_SYNC(2 * NG); kstep(t + 3, 3, 2, true);
;   }
;   BIG_SYNC(2 * NG); kstep(NK - 4, 0, 3, true);
	v_add_u32_e32 v176, 0x18000, v167
	v_or_b32_e32 v179, 0x18000, v169
	v_mfma_f32_16x16x32_bf16 v[44:47], v[202:205], v[232:235], v[44:47]
	v_add_u32_e32 v180, 0x18400, v169
	v_add_u32_e32 v181, 0x18800, v169
	s_waitcnt lgkmcnt(2)
	v_mfma_f32_16x16x32_bf16 v[120:123], v[186:189], v[236:239], v[120:123]
	ds_read_b128 v[232:235], v211 offset:36864
	v_mfma_f32_16x16x32_bf16 v[104:107], v[190:193], v[236:239], v[104:107]
	v_add_u32_e32 v182, 0x18c00, v169
	v_mfma_f32_16x16x32_bf16 v[76:79], v[194:197], v[236:239], v[76:79]
	v_readfirstlane_b32 s9, v154
	v_mfma_f32_16x16x32_bf16 v[40:43], v[202:205], v[236:239], v[40:43]
	v_lshl_add_u64 v[248:249], v[144:145], 0, s[54:55]
	s_waitcnt lgkmcnt(2)
	v_mfma_f32_16x16x32_bf16 v[116:119], v[186:189], v[240:243], v[116:119]
	ds_read_b128 v[236:239], v211 offset:37888
	v_mfma_f32_16x16x32_bf16 v[100:103], v[190:193], v[240:243], v[100:103]
	s_mov_b32 m0, s9
	v_mfma_f32_16x16x32_bf16 v[68:71], v[194:197], v[240:243], v[68:71]
	v_readfirstlane_b32 s9, v155
	v_mfma_f32_16x16x32_bf16 v[36:39], v[202:205], v[240:243], v[36:39]
	v_lshl_add_u64 v[144:145], v[144:145], 0, s[56:57]
	s_waitcnt lgkmcnt(2)
	v_mfma_f32_16x16x32_bf16 v[112:115], v[186:189], v[244:247], v[112:115]
	ds_read_b128 v[240:243], v211 offset:38912
	v_mfma_f32_16x16x32_bf16 v[96:99], v[190:193], v[244:247], v[96:99]
	v_lshl_add_u64 v[250:251], v[142:143], 0, s[54:55]
	v_mfma_f32_16x16x32_bf16 v[64:67], v[194:197], v[244:247], v[64:67]
	v_lshl_add_u64 v[142:143], v[142:143], 0, s[56:57]
	v_mfma_f32_16x16x32_bf16 v[32:35], v[202:205], v[244:247], v[32:35]
	global_load_lds_dwordx4 v[248:249], off
	s_waitcnt lgkmcnt(2)
	v_mfma_f32_16x16x32_bf16 v[92:95], v[186:189], v[232:235], v[92:95]
	ds_read_b128 v[244:247], v211 offset:39936
	v_mfma_f32_16x16x32_bf16 v[60:63], v[190:193], v[232:235], v[60:63]
	ds_read_b128 v[216:219], v167
	v_mfma_f32_16x16x32_bf16 v[28:31], v[194:197], v[232:235], v[28:31]
	ds_read_b128 v[220:223], v167 offset:1024
	v_mfma_f32_16x16x32_bf16 v[12:15], v[202:205], v[232:235], v[12:15]
	ds_read_b128 v[224:227], v167 offset:2048
	s_waitcnt lgkmcnt(5)
	v_mfma_f32_16x16x32_bf16 v[84:87], v[186:189], v[236:239], v[84:87]
	ds_read_b128 v[228:231], v167 offset:3072
	ds_read_b128 v[232:235], v168 offset:16384
	v_mfma_f32_16x16x32_bf16 v[56:59], v[190:193], v[236:239], v[56:59]
	s_mov_b32 m0, s9
	v_mfma_f32_16x16x32_bf16 v[24:27], v[194:197], v[236:239], v[24:27]
	v_readfirstlane_b32 s9, v156
	v_mfma_f32_16x16x32_bf16 v[8:11], v[202:205], v[236:239], v[8:11]
	global_load_lds_dwordx4 v[144:145], off
	s_waitcnt lgkmcnt(6)
	v_mfma_f32_16x16x32_bf16 v[80:83], v[186:189], v[240:243], v[80:83]
	ds_read_b128 v[236:239], v168 offset:17408
	v_mfma_f32_16x16x32_bf16 v[52:55], v[190:193], v[240:243], v[52:55]
	s_mov_b32 m0, s9
	v_mfma_f32_16x16x32_bf16 v[20:23], v[194:197], v[240:243], v[20:23]
	v_readfirstlane_b32 s9, v157
	v_mfma_f32_16x16x32_bf16 v[4:7], v[202:205], v[240:243], v[4:7]
	global_load_lds_dwordx4 v[250:251], off
	s_waitcnt lgkmcnt(6)
	v_mfma_f32_16x16x32_bf16 v[72:75], v[186:189], v[244:247], v[72:75]
	ds_read_b128 v[240:243], v168 offset:18432
	v_mfma_f32_16x16x32_bf16 v[48:51], v[190:193], v[244:247], v[48:51]
	s_mov_b32 m0, s9
	v_mfma_f32_16x16x32_bf16 v[16:19], v[194:197], v[244:247], v[16:19]
	global_load_lds_dwordx4 v[142:143], off
	v_mfma_f32_16x16x32_bf16 v[0:3], v[202:205], v[244:247], v[0:3]
	ds_read_b128 v[244:247], v168 offset:19456
	v_add_u32_e32 v142, 0x19000, v169
	v_add_u32_e32 v143, 0x19400, v169
	v_add_u32_e32 v144, 0x19800, v169
	v_add_u32_e32 v145, 0x19c00, v169
	s_add_u32 s36, s36, 0x8000
	s_addc_u32 s37, s37, 0
	s_cmp_lg_u32 s36, 0x38000
	s_cbranch_scc1 .LBB0_68
	s_waitcnt lgkmcnt(3)
	v_mfma_f32_16x16x32_bf16 v[124:127], v[216:219], v[232:235], v[124:127]
	v_mfma_f32_16x16x32_bf16 v[108:111], v[220:223], v[232:235], v[108:111]
	v_mfma_f32_16x16x32_bf16 v[88:91], v[224:227], v[232:235], v[88:91]
	s_waitcnt vmcnt(4)
	s_barrier
	s_sext_i32_i8 s9, s14
	v_mfma_f32_16x16x32_bf16 v[44:47], v[228:231], v[232:235], v[44:47]
	s_mov_b64 s[18:19], 0x3e000
	s_waitcnt lgkmcnt(2)
	v_mfma_f32_16x16x32_bf16 v[120:123], v[216:219], v[236:239], v[120:123]
	ds_read_b128 v[232:235], v168 offset:20480
	v_mfma_f32_16x16x32_bf16 v[104:107], v[220:223], v[236:239], v[104:107]
	v_readfirstlane_b32 s11, v158
	v_mfma_f32_16x16x32_bf16 v[76:79], v[224:227], v[236:239], v[76:79]
	v_lshl_add_u64 v[150:151], v[130:131], 0, s[18:19]
	v_mfma_f32_16x16x32_bf16 v[40:43], v[228:231], v[236:239], v[40:43]
	v_lshl_add_u64 v[198:199], v[128:129], 0, s[18:19]
	s_waitcnt lgkmcnt(2)
	v_mfma_f32_16x16x32_bf16 v[116:119], v[216:219], v[240:243], v[116:119]
	ds_read_b128 v[236:239], v168 offset:21504
	v_mfma_f32_16x16x32_bf16 v[100:103], v[220:223], v[240:243], v[100:103]
	s_mov_b32 m0, s11
	v_mfma_f32_16x16x32_bf16 v[68:71], v[224:227], v[240:243], v[68:71]
	s_mov_b64 s[18:19], 0x7e000
	v_mfma_f32_16x16x32_bf16 v[36:39], v[228:231], v[240:243], v[36:39]
	v_readfirstlane_b32 s11, v159
	s_waitcnt lgkmcnt(2)
	v_mfma_f32_16x16x32_bf16 v[112:115], v[216:219], v[244:247], v[112:115]
	ds_read_b128 v[240:243], v168 offset:22528
	v_mfma_f32_16x16x32_bf16 v[96:99], v[220:223], v[244:247], v[96:99]
	v_lshl_add_u64 v[130:131], v[130:131], 0, s[18:19]
	v_mfma_f32_16x16x32_bf16 v[64:67], v[224:227], v[244:247], v[64:67]
	v_lshl_add_u64 v[128:129], v[128:129], 0, s[18:19]
	v_mfma_f32_16x16x32_bf16 v[32:35], v[228:231], v[244:247], v[32:35]
	global_load_lds_dwordx4 v[150:151], off
	s_waitcnt lgkmcnt(2)
; #define BIG_SYNC(N)                                              \
;   asm volatile("s_waitcnt vmcnt(%0)" ::"n"(N) : "memory");       \
;   __builtin_amdgcn_s_barrier();                                  \
;   asm volatile("" ::: "memory");                                 \
;   __builtin_amdgcn_sched_barrier(0);
; template <int NK, bool BNT = false> ...
;     ...
;   auto kstep = [&](int T, int cur, int nxt, bool do_stage) {
;     const unsigned char* sa = smem + cur * BIG_STAGE;
;     bf16x8 af[4], bfr[4];
; #pragma unroll
;     for (int m = 0; m < 4; ++m) af[m] = *reinterpret_cast<const bf16x8*>(sa + aoff + m * 1024);
; #pragma unroll
;     for (int n = 0; n < 4; ++n) bfr[n] = *reinterpret_cast<const bf16x8*>(sa + boff + n * 1024);
;     __builtin_amdgcn_sched_barrier(0);
;     if (do_stage) stage(T + 3, nxt);
; #pragma unroll
;     for (int m = 0; m < 4; ++m)
; #pragma unroll
;       for (int n = 0; n < 4; ++n) acc[m][n] = __builtin_amdgcn_mfma_f32_16x16x32_bf16(af[m], bfr[n], acc[m][n], 0, 0, 0);
;     if (do_stage) {
; #pragma unroll
;       for (int q = 0; q < NG; ++q) {
;         __builtin_amdgcn_sched_group_barrier(0x008, 3, 0);
;         __builtin_amdgcn_sched_group_barrier(0x010, 1, 0);
;       }
;       __builtin_amdgcn_sched_group_barrier(0x008, 16 - 3 * NG, 0);
;     }
;     __builtin_amdgcn_sched_barrier(0);
; #pragma unroll
;     for (int n = 0; n < 4; ++n) bfr[n] = *reinterpret_cast<const bf16x8*>(sa + boff + (4 + n) * 1024);
; #pragma unroll
;     for (int m = 0; m < 4; ++m)
; #pragma unroll
;       for (int n = 0; n < 4; ++n)
;         acc[m][4 + n] = __builtin_amdgcn_mfma_f32_16x16x32_bf16(af[m], bfr[n], acc[m][4 + n], 0, 0, 0);
;     __builtin_amdgcn_sched_barrier(0);
;   };
;     ...
;   stage(0, 0);
;   stage(1, 1);
;   stage(2, 2);
;   for (int it = 0; it < NK / 4 - 1; ++it) {
;     const int t = it * 4;
;     BIG_SYNC(2 * NG); kstep(t, 0, 3, true);
;     BIG_SYNC(2 * NG); kstep(t + 1, 1, 0, true);
;     BIG_SYNC(2 * NG); kstep(t + 2, 2, 1, true);
;     BIG_SYNC(2 * NG); kstep(t + 3, 3, 2, true);
;   }
;   BIG_SYNC(2 * NG); kstep(NK - 4, 0, 3, true);
;   BIG_SYNC(2 * NG); kstep(NK - 3, 1, 0, false);
;   BIG_SYNC(NG);     kstep(NK - 2, 2, 0, false);
	v_mfma_f32_16x16x32_bf16 v[92:95], v[216:219], v[232:235], v[92:95]
	ds_read_b128 v[244:247], v168 offset:23552
	v_mfma_f32_16x16x32_bf16 v[60:63], v[220:223], v[232:235], v[60:63]
	ds_read_b128 v[186:189], v167 offset:32768
	v_mfma_f32_16x16x32_bf16 v[28:31], v[224:227], v[232:235], v[28:31]
	ds_read_b128 v[190:193], v167 offset:33792
	v_mfma_f32_16x16x32_bf16 v[12:15], v[228:231], v[232:235], v[12:15]
	ds_read_b128 v[194:197], v167 offset:34816
	s_waitcnt lgkmcnt(5)
	v_mfma_f32_16x16x32_bf16 v[84:87], v[216:219], v[236:239], v[84:87]
	ds_read_b128 v[202:205], v167 offset:35840
	ds_read_b128 v[232:235], v168 offset:49152
	v_mfma_f32_16x16x32_bf16 v[56:59], v[220:223], v[236:239], v[56:59]
	s_mov_b32 m0, s11
	v_mfma_f32_16x16x32_bf16 v[24:27], v[224:227], v[236:239], v[24:27]
	v_readfirstlane_b32 s11, v160
	v_mfma_f32_16x16x32_bf16 v[8:11], v[228:231], v[236:239], v[8:11]
	global_load_lds_dwordx4 v[130:131], off
	s_waitcnt lgkmcnt(6)
	v_mfma_f32_16x16x32_bf16 v[80:83], v[216:219], v[240:243], v[80:83]
	ds_read_b128 v[236:239], v168 offset:50176
	v_mfma_f32_16x16x32_bf16 v[52:55], v[220:223], v[240:243], v[52:55]
	s_mov_b32 m0, s11
	v_mfma_f32_16x16x32_bf16 v[20:23], v[224:227], v[240:243], v[20:23]
	v_readfirstlane_b32 s11, v161
	v_mfma_f32_16x16x32_bf16 v[4:7], v[228:231], v[240:243], v[4:7]
	global_load_lds_dwordx4 v[198:199], off
	s_waitcnt lgkmcnt(6)
	v_mfma_f32_16x16x32_bf16 v[72:75], v[216:219], v[244:247], v[72:75]
	ds_read_b128 v[240:243], v168 offset:51200
	v_mfma_f32_16x16x32_bf16 v[48:51], v[220:223], v[244:247], v[48:51]
	s_mov_b32 m0, s11
	v_mfma_f32_16x16x32_bf16 v[16:19], v[224:227], v[244:247], v[16:19]
	global_load_lds_dwordx4 v[128:129], off
	v_mfma_f32_16x16x32_bf16 v[0:3], v[228:231], v[244:247], v[0:3]
	ds_read_b128 v[244:247], v168 offset:52224
	s_waitcnt lgkmcnt(3)
	v_mfma_f32_16x16x32_bf16 v[124:127], v[186:189], v[232:235], v[124:127]
	v_mfma_f32_16x16x32_bf16 v[108:111], v[190:193], v[232:235], v[108:111]
	v_mfma_f32_16x16x32_bf16 v[88:91], v[194:197], v[232:235], v[88:91]
	v_mfma_f32_16x16x32_bf16 v[44:47], v[202:205], v[232:235], v[44:47]
	s_waitcnt vmcnt(4)
	s_barrier
	s_waitcnt lgkmcnt(2)
	v_mfma_f32_16x16x32_bf16 v[120:123], v[186:189], v[236:239], v[120:123]
	ds_read_b128 v[232:235], v168 offset:53248
	v_mfma_f32_16x16x32_bf16 v[104:107], v[190:193], v[236:239], v[104:107]
	v_mfma_f32_16x16x32_bf16 v[76:79], v[194:197], v[236:239], v[76:79]
	v_mfma_f32_16x16x32_bf16 v[40:43], v[202:205], v[236:239], v[40:43]
	s_waitcnt lgkmcnt(2)
	v_mfma_f32_16x16x32_bf16 v[116:119], v[186:189], v[240:243], v[116:119]
	ds_read_b128 v[236:239], v168 offset:54272
	v_mfma_f32_16x16x32_bf16 v[100:103], v[190:193], v[240:243], v[100:103]
	v_mfma_f32_16x16x32_bf16 v[68:71], v[194:197], v[240:243], v[68:71]
	v_mfma_f32_16x16x32_bf16 v[36:39], v[202:205], v[240:243], v[36:39]
	s_waitcnt lgkmcnt(2)
	v_mfma_f32_16x16x32_bf16 v[112:115], v[186:189], v[244:247], v[112:115]
	ds_read_b128 v[240:243], v168 offset:55296
	v_mfma_f32_16x16x32_bf16 v[96:99], v[190:193], v[244:247], v[96:99]
	v_mfma_f32_16x16x32_bf16 v[64:67], v[194:197], v[244:247], v[64:67]
	v_mfma_f32_16x16x32_bf16 v[32:35], v[202:205], v[244:247], v[32:35]
	s_waitcnt lgkmcnt(2)
	v_mfma_f32_16x16x32_bf16 v[92:95], v[186:189], v[232:235], v[92:95]
	ds_read_b128 v[244:247], v168 offset:56320
	v_mfma_f32_16x16x32_bf16 v[60:63], v[190:193], v[232:235], v[60:63]
	v_mfma_f32_16x16x32_bf16 v[28:31], v[194:197], v[232:235], v[28:31]
	v_mfma_f32_16x16x32_bf16 v[12:15], v[202:205], v[232:235], v[12:15]
	s_waitcnt lgkmcnt(2)
	v_mfma_f32_16x16x32_bf16 v[84:87], v[186:189], v[236:239], v[84:87]
	v_mfma_f32_16x16x32_bf16 v[56:59], v[190:193], v[236:239], v[56:59]
	v_mfma_f32_16x16x32_bf16 v[24:27], v[194:197], v[236:239], v[24:27]
	v_mfma_f32_16x16x32_bf16 v[8:11], v[202:205], v[236:239], v[8:11]
	s_waitcnt lgkmcnt(1)
	v_mfma_f32_16x16x32_bf16 v[80:83], v[186:189], v[240:243], v[80:83]
	v_mfma_f32_16x16x32_bf16 v[52:55], v[190:193], v[240:243], v[52:55]
	v_mfma_f32_16x16x32_bf16 v[20:23], v[194:197], v[240:243], v[20:23]
	v_mfma_f32_16x16x32_bf16 v[4:7], v[202:205], v[240:243], v[4:7]
	s_waitcnt lgkmcnt(0)
	v_mfma_f32_16x16x32_bf16 v[72:75], v[186:189], v[244:247], v[72:75]
	v_mfma_f32_16x16x32_bf16 v[48:51], v[190:193], v[244:247], v[48:51]
	v_mfma_f32_16x16x32_bf16 v[16:19], v[194:197], v[244:247], v[16:19]
	v_mfma_f32_16x16x32_bf16 v[0:3], v[202:205], v[244:247], v[0:3]
	v_mov_b32_e32 v186, 0xf149f2ca
	v_mov_b32_e32 v187, 0x3c0881c4
	v_mov_b32_e32 v188, 0xbab64f3b
	v_mov_b32_e32 v189, 0x24800
	v_mov_b32_e32 v190, 1
	v_mov_b32_e32 v191, 0x24804
	v_mov_b32_e32 v192, 0xfcf
	v_mov_b32_e32 v193, 0x7cf
	v_mov_b32_e32 v194, 0xfdf
	v_mov_b32_e32 v195, 0x7df
	v_mov_b32_e32 v196, 0xfef
	v_mov_b32_e32 v197, 0x7ef
	v_mov_b32_e32 v198, 0xfff
	v_mov_b32_e32 v199, 0x7ff
	v_mov_b32_e32 v200, 0x20000
	v_mov_b32_e32 v201, 0xf8f
	v_mov_b32_e32 v202, 0x78f
	v_mov_b32_e32 v203, 0xf9f
	v_mov_b32_e32 v204, 0x79f
	v_mov_b32_e32 v205, 0xfaf
	v_mov_b32_e32 v210, 0x7f800000
	v_not_b32_e32 v211, 63
	v_not_b32_e32 v212, 31
	v_mov_b32_e32 v213, 0x7fc00000
	s_waitcnt vmcnt(4)
	s_barrier
; #define BIG_SYNC(N)                                              \
;   asm volatile("s_waitcnt vmcnt(%0)" ::"n"(N) : "memory");       \
;   __builtin_amdgcn_s_barrier();                                  \
;   asm volatile("" ::: "memory");                                 \
;   __builtin_amdgcn_sched_barrier(0);
; template <int NK, bool BNT = false> ...
;     ...
;   auto kstep = [&](int T, int cur, int nxt, bool do_stage) {
;     const unsigned char* sa = smem + cur * BIG_STAGE;
;     bf16x8 af[4], bfr[4];
; #pragma unroll
;     for (int m = 0; m < 4; ++m) af[m] = *reinterpret_cast<const bf16x8*>(sa + aoff + m * 1024);
; #pragma unroll
;     for (int n = 0; n < 4; ++n) bfr[n] = *reinterpret_cast<const bf16x8*>(sa + boff + n * 1024);
;     __builtin_amdgcn_sched_barrier(0);
;     if (do_stage) stage(T + 3, nxt);
; #pragma unroll
;     for (int m = 0; m < 4; ++m)
; #pragma unroll
;       for (int n = 0; n < 4; ++n) acc[m][n] = __builtin_amdgcn_mfma_f32_16x16x32_bf16(af[m], bfr[n], acc[m][n], 0, 0, 0);
;     if (do_stage) {
; #pragma unroll
;       for (int q = 0; q < NG; ++q) {
;         __builtin_amdgcn_sched_group_barrier(0x008, 3, 0);
;         __builtin_amdgcn_sched_group_barrier(0x010, 1, 0);
;       }
;       __builtin_amdgcn_sched_group_barrier(0x008, 16 - 3 * NG, 0);
;     }
;     __builtin_amdgcn_sched_barrier(0);
; #pragma unroll
;     for (int n = 0; n < 4; ++n) bfr[n] = *reinterpret_cast<const bf16x8*>(sa + boff + (4 + n) * 1024);
; #pragma unroll
;     for (int m = 0; m < 4; ++m)
; #pragma unroll
;       for (int n = 0; n < 4; ++n)
;         acc[m][4 + n] = __builtin_amdgcn_mfma_f32_16x16x32_bf16(af[m], bfr[n], acc[m][4 + n], 0, 0, 0);
;     __builtin_amdgcn_sched_barrier(0);
;   };
;     ...
;   stage(0, 0);
;   stage(1, 1);
;   stage(2, 2);
;   for (int it = 0; it < NK / 4 - 1; ++it) {
;     const int t = it * 4;
;     BIG_SYNC(2 * NG); kstep(t, 0, 3, true);
;     BIG_SYNC(2 * NG); kstep(t + 1, 1, 0, true);
;     BIG_SYNC(2 * NG); kstep(t + 2, 2, 1, true);
;     BIG_SYNC(2 * NG); kstep(t + 3, 3, 2, true);
;   }
;   BIG_SYNC(2 * NG); kstep(NK - 4, 0, 3, true);
;   BIG_SYNC(2 * NG); kstep(NK - 3, 1, 0, false);
;   BIG_SYNC(NG);     kstep(NK - 2, 2, 0, false);
;   BIG_SYNC(0);      kstep(NK - 1, 3, 0, false);
	ds_read_b128 v[128:131], v162
	ds_read_b128 v[138:141], v162 offset:1024
	ds_read_b128 v[146:149], v162 offset:2048
	ds_read_b128 v[154:157], v162 offset:3072
	ds_read_b128 v[158:161], v163
	ds_read_b128 v[216:219], v164
	ds_read_b128 v[162:165], v165
	ds_read_b128 v[220:223], v172
	s_waitcnt lgkmcnt(0)
	v_mfma_f32_16x16x32_bf16 v[124:127], v[128:131], v[158:161], v[124:127]
	v_mfma_f32_16x16x32_bf16 v[116:119], v[128:131], v[162:165], v[116:119]
	v_mfma_f32_16x16x32_bf16 v[112:115], v[128:131], v[220:223], v[112:115]
	v_mfma_f32_16x16x32_bf16 v[104:107], v[138:141], v[216:219], v[104:107]
	v_mfma_f32_16x16x32_bf16 v[100:103], v[138:141], v[162:165], v[100:103]
	v_mfma_f32_16x16x32_bf16 v[96:99], v[138:141], v[220:223], v[96:99]
	v_mfma_f32_16x16x32_bf16 v[68:71], v[146:149], v[162:165], v[68:71]
	v_mfma_f32_16x16x32_bf16 v[64:67], v[146:149], v[220:223], v[64:67]
	v_mfma_f32_16x16x32_bf16 v[44:47], v[154:157], v[158:161], v[44:47]
	v_mfma_f32_16x16x32_bf16 v[40:43], v[154:157], v[216:219], v[40:43]
	v_mfma_f32_16x16x32_bf16 v[36:39], v[154:157], v[162:165], v[36:39]
	v_mfma_f32_16x16x32_bf16 v[32:35], v[154:157], v[220:223], v[32:35]
	v_mfma_f32_16x16x32_bf16 v[120:123], v[128:131], v[216:219], v[120:123]
	v_mfma_f32_16x16x32_bf16 v[224:227], v[138:141], v[158:161], v[108:111]
	v_mfma_f32_16x16x32_bf16 v[228:231], v[146:149], v[158:161], v[88:91]
	v_mfma_f32_16x16x32_bf16 v[232:235], v[146:149], v[216:219], v[76:79]
	s_nop 2
	ds_read_b128 v[76:79], v173
	ds_read_b128 v[88:91], v174
	s_waitcnt lgkmcnt(0)
	v_mfma_f32_16x16x32_bf16 v[158:161], v[128:131], v[76:79], v[92:95]
	s_nop 2
	ds_read_b128 v[92:95], v178
	v_mfma_f32_16x16x32_bf16 v[162:165], v[128:131], v[88:91], v[84:87]
	s_nop 2
	ds_read_b128 v[84:87], v175
	s_waitcnt lgkmcnt(0)
	v_mfma_f32_16x16x32_bf16 v[172:175], v[128:131], v[84:87], v[80:83]
	v_mfma_f32_16x16x32_bf16 v[128:131], v[128:131], v[92:95], v[72:75]
	v_mfma_f32_16x16x32_bf16 v[216:219], v[138:141], v[76:79], v[60:63]
	v_mfma_f32_16x16x32_bf16 v[220:223], v[138:141], v[88:91], v[56:59]
	v_mfma_f32_16x16x32_bf16 v[52:55], v[138:141], v[84:87], v[52:55]
	v_mfma_f32_16x16x32_bf16 v[48:51], v[138:141], v[92:95], v[48:51]
	v_mfma_f32_16x16x32_bf16 v[138:141], v[146:149], v[76:79], v[28:31]
	v_mfma_f32_16x16x32_bf16 v[236:239], v[146:149], v[88:91], v[24:27]
	v_mfma_f32_16x16x32_bf16 v[20:23], v[146:149], v[84:87], v[20:23]
	v_mfma_f32_16x16x32_bf16 v[16:19], v[146:149], v[92:95], v[16:19]
	v_mfma_f32_16x16x32_bf16 v[146:149], v[154:157], v[76:79], v[12:15]
	v_mfma_f32_16x16x32_bf16 v[0:3], v[154:157], v[92:95], v[0:3]
	v_mfma_f32_16x16x32_bf16 v[240:243], v[154:157], v[88:91], v[8:11]
	v_mfma_f32_16x16x32_bf16 v[244:247], v[154:157], v[84:87], v[4:7]
	s_waitcnt vmcnt(0)
	s_barrier
	s_nop 1
	ds_read_b128 v[4:7], v176
	ds_read_b128 v[8:11], v176 offset:1024
	ds_read_b128 v[154:157], v176 offset:2048
	ds_read_b128 v[12:15], v179
	ds_read_b128 v[24:27], v180
	ds_read_b128 v[28:31], v181
	ds_read_b128 v[56:59], v182
	ds_read_b128 v[248:251], v176 offset:3072
	s_waitcnt lgkmcnt(0)
	v_mfma_f32_16x16x32_bf16 v[108:111], v[4:7], v[24:27], v[120:123]
	v_mfma_f32_16x16x32_bf16 v[92:95], v[4:7], v[28:31], v[116:119]
	v_mfma_f32_16x16x32_bf16 v[76:79], v[4:7], v[56:59], v[112:115]
	v_mfma_f32_16x16x32_bf16 v[104:107], v[8:11], v[24:27], v[104:107]
	v_mfma_f32_16x16x32_bf16 v[88:91], v[8:11], v[28:31], v[100:103]
	v_mfma_f32_16x16x32_bf16 v[72:75], v[8:11], v[56:59], v[96:99]
	v_mfma_f32_16x16x32_bf16 v[100:103], v[154:157], v[24:27], v[232:235]
	v_mfma_f32_16x16x32_bf16 v[84:87], v[154:157], v[28:31], v[68:71]
	v_mfma_f32_16x16x32_bf16 v[68:71], v[154:157], v[56:59], v[64:67]
	v_mfma_f32_16x16x32_bf16 v[116:119], v[248:251], v[12:15], v[44:47]
	v_mfma_f32_16x16x32_bf16 v[96:99], v[248:251], v[24:27], v[40:43]
	v_mfma_f32_16x16x32_bf16 v[80:83], v[248:251], v[28:31], v[36:39]
	v_mfma_f32_16x16x32_bf16 v[64:67], v[248:251], v[56:59], v[32:35]
	v_mfma_f32_16x16x32_bf16 v[178:181], v[4:7], v[12:15], v[124:127]
	v_mfma_f32_16x16x32_bf16 v[224:227], v[8:11], v[12:15], v[224:227]
	v_mfma_f32_16x16x32_bf16 v[120:123], v[154:157], v[12:15], v[228:231]
	ds_read_b128 v[32:35], v142
	ds_read_b128 v[112:115], v143
	ds_read_b128 v[124:127], v144
	ds_read_b128 v[142:145], v145
	s_waitcnt lgkmcnt(0)
; __device__ __forceinline__ float bf2f(bf16_t b) { return __uint_as_float(((unsigned)b) << 16); }
; __device__ __forceinline__ int widen_off(int fq) { return ((fq & 1) << 4) + ((fq >> 1) << 3); }
; template <int MODE, int NSUB>
; __device__ __forceinline__ void epilogue(const Params& p, int layer, f32x4 (&acc)[4][NSUB], int tm, int tn, int g,
;                                          const float* s_rstd, const int tid_in) {
;     ...
;   } else if constexpr (MODE == EPI_RES) {
;     const int fb = tm * 128 + wr * 64 + fq * 4;
;     const int tb = tn * (NSUB * 32) + wc * (NSUB * 16) + fr;
;     const int fw = tm * 128 + wr * 64 + widen_off(fq);
;     u32x4 curw[2], nxtw[2];
; #pragma unroll
;     for (int mp = 0; mp < 2; ++mp) curw[mp] = *reinterpret_cast<const u32x4*>(p.xb + blk(tb, fw + mp * 32, 32));
; #pragma unroll
;     for (int n = 0; n < NSUB; ++n) {
;       if (n + 1 < NSUB) {
; #pragma unroll
;         for (int mp = 0; mp < 2; ++mp) nxtw[mp] = *reinterpret_cast<const u32x4*>(p.xb + blk(tb + (n + 1) * 16, fw + mp * 32, 32));
;       }
;       bf16x4 cur[4];
;       unwiden_pair(curw[0], cur[0], cur[1]);
;       unwiden_pair(curw[1], cur[2], cur[3]);
;       const int t = tb + n * 16;
;       float ss = 0.f;
; #pragma unroll
;       for (int mp = 0; mp < 2; ++mp) {
;         bf16x4 pk[2];
; #pragma unroll
;         for (int h2 = 0; h2 < 2; ++h2) {
;           const int m = mp * 2 + h2;
;           const float x0 = bf2f((bf16_t)cur[m][0]) + acc[m][n][0], x1 = bf2f((bf16_t)cur[m][1]) + acc[m][n][1];
;           const float x2 = bf2f((bf16_t)cur[m][2]) + acc[m][n][2], x3 = bf2f((bf16_t)cur[m][3]) + acc[m][n][3];
;           ss += x0 * x0 + x1 * x1 + x2 * x2 + x3 * x3;
;           pk[h2] = pack4(x0, x1, x2, x3);
;         }
;         const int f = tm * 128 + wr * 64 + mp * 32 + widen_off(fq);
;         *reinterpret_cast<u32x4*>(p.xb + blk(t, f, 32)) = widen_pair(pk[0], pk[1]);
;       }
;       ss = red_fq(ss);
;       if (fq == 0) p.part[(long)t * 16 + tm * 2 + wr] = ss;
;       curw[0] = nxtw[0];
;       curw[1] = nxtw[1];
;     }
	v_mfma_f32_16x16x32_bf16 v[60:63], v[4:7], v[32:35], v[158:161]
	v_mfma_f32_16x16x32_bf16 v[44:47], v[4:7], v[112:115], v[162:165]
	v_mfma_f32_16x16x32_bf16 v[28:31], v[4:7], v[124:127], v[172:175]
	v_mfma_f32_16x16x32_bf16 v[12:15], v[4:7], v[142:145], v[128:131]
	v_mfma_f32_16x16x32_bf16 v[56:59], v[8:11], v[32:35], v[216:219]
	v_mfma_f32_16x16x32_bf16 v[40:43], v[8:11], v[112:115], v[220:223]
	v_mfma_f32_16x16x32_bf16 v[24:27], v[8:11], v[124:127], v[52:55]
	v_mfma_f32_16x16x32_bf16 v[8:11], v[8:11], v[142:145], v[48:51]
	v_mfma_f32_16x16x32_bf16 v[52:55], v[154:157], v[32:35], v[138:141]
	v_mfma_f32_16x16x32_bf16 v[36:39], v[154:157], v[112:115], v[236:239]
	v_mfma_f32_16x16x32_bf16 v[20:23], v[154:157], v[124:127], v[20:23]
	v_mfma_f32_16x16x32_bf16 v[4:7], v[154:157], v[142:145], v[16:19]
	v_mfma_f32_16x16x32_bf16 v[48:51], v[248:251], v[32:35], v[146:149]
	v_mfma_f32_16x16x32_bf16 v[32:35], v[248:251], v[112:115], v[240:243]
	v_mfma_f32_16x16x32_bf16 v[16:19], v[248:251], v[124:127], v[244:247]
	v_mfma_f32_16x16x32_bf16 v[0:3], v[248:251], v[142:145], v[0:3]
	v_lshl_add_u32 v124, s9, 1, v170
	v_mov_b32_e32 v112, v215
	v_lshlrev_b32_e32 v113, 7, v124
	v_ashrrev_i32_e32 v138, 7, v112
	v_lshl_add_u32 v114, v138, 6, v113
	v_lshlrev_b32_e32 v113, 1, v112
	v_and_b32_e32 v113, 0x80, v113
	v_lshl_or_b32 v127, s10, 8, v113
	v_lshrrev_b32_e32 v113, 2, v112
	v_and_b32_e32 v125, 15, v112
	v_and_b32_e32 v113, 8, v113
	v_ashrrev_i32_e32 v115, 2, v127
	v_readlane_b32 s80, v253, 25
	v_ashrrev_i32_e32 v114, 5, v114
	v_bfe_u32 v126, v112, 4, 2
	v_and_or_b32 v112, v112, 16, v113
	v_lshlrev_b32_e32 v156, 6, v125
	v_mov_b32_e32 v157, v153
	v_readlane_b32 s84, v253, 29
	v_readlane_b32 s85, v253, 30
	v_add_u32_e32 v114, v114, v115
	v_lshlrev_b32_e32 v152, 1, v112
	v_lshl_add_u64 v[144:145], s[84:85], 0, v[156:157]
	v_ashrrev_i32_e32 v115, 31, v114
	v_lshl_add_u64 v[112:113], v[144:145], 0, v[152:153]
	v_lshlrev_b64 v[146:147], 13, v[114:115]
	v_or_b32_e32 v114, 1, v114
	v_lshl_add_u64 v[150:151], v[112:113], 0, v[146:147]
	v_ashrrev_i32_e32 v115, 31, v114
	global_load_dwordx4 v[158:161], v[150:151], off
	v_lshlrev_b64 v[148:149], 13, v[114:115]
	v_lshl_add_u64 v[154:155], v[112:113], 0, v[148:149]
	global_load_dwordx4 v[128:131], v[154:155], off
	v_and_b32_e32 v113, 64, v185
	v_xor_b32_e32 v112, 16, v185
	v_add_u32_e32 v113, 64, v113
	v_cmp_lt_i32_e32 vcc, v112, v113
	v_or_b32_e32 v142, v127, v125
	v_lshlrev_b32_e32 v140, 1, v124
	v_cndmask_b32_e32 v112, v185, v112, vcc
	v_lshlrev_b32_e32 v172, 2, v112
	v_xor_b32_e32 v112, 32, v185
	v_cmp_lt_i32_e32 vcc, v112, v113
	v_ashrrev_i32_e32 v141, 31, v140
	v_ashrrev_i32_e32 v139, 31, v138
	v_cndmask_b32_e32 v112, v185, v112, vcc
	v_lshlrev_b32_e32 v173, 2, v112
	v_cmp_eq_u32_e32 vcc, 0, v126
	global_load_dwordx4 v[124:127], v[150:151], off offset:1024
	global_load_dwordx4 v[112:115], v[154:155], off offset:1024
	v_readlane_b32 s81, v253, 26
	v_readlane_b32 s82, v253, 27
	v_readlane_b32 s83, v253, 28
	v_readlane_b32 s86, v253, 31
	v_readlane_b32 s87, v253, 32
	v_readlane_b32 s88, v253, 33
	v_readlane_b32 s89, v253, 34
	v_readlane_b32 s90, v253, 35
	v_readlane_b32 s91, v253, 36
	v_readlane_b32 s92, v253, 37
	v_readlane_b32 s93, v253, 38
	v_readlane_b32 s94, v253, 39
	v_readlane_b32 s95, v253, 40
	s_waitcnt vmcnt(0)
	v_mov_b32_e32 v143, v160
	s_nop 1
	v_permlane16_swap_b32_e32 v158, v143
	v_mov_b32_e32 v164, v161
	s_nop 1
	v_permlane16_swap_b32_e32 v159, v164
	v_mov_b32_e32 v176, v130
	v_mov_b32_e32 v182, v131
	v_and_b32_e32 v131, 0xffff0000, v158
	v_lshlrev_b32_e32 v130, 16, v158
	v_pk_add_f32 v[130:131], v[178:179], v[130:131]
	v_and_b32_e32 v161, 0xffff0000, v159
	v_lshlrev_b32_e32 v160, 16, v159
	v_pk_add_f32 v[162:163], v[180:181], v[160:161]
	v_pk_mul_f32 v[160:161], v[130:131], v[130:131]
	v_cvt_pk_bf16_f32 v178, v130, v131
	v_and_b32_e32 v131, 0xffff0000, v143
	v_lshlrev_b32_e32 v130, 16, v143
	v_pk_mul_f32 v[158:159], v[162:163], v[162:163]
	v_cvt_pk_bf16_f32 v179, v162, v163
	v_pk_add_f32 v[130:131], v[224:225], v[130:131]
	v_and_b32_e32 v163, 0xffff0000, v164
	v_lshlrev_b32_e32 v162, 16, v164
	v_pk_add_f32 v[174:175], v[226:227], v[162:163]
	v_pk_mul_f32 v[164:165], v[130:131], v[130:131]
	v_cvt_pk_bf16_f32 v180, v130, v131
	v_lshl_add_u64 v[130:131], s[84:85], 0, v[146:147]
	v_pk_mul_f32 v[162:163], v[174:175], v[174:175]
	v_cvt_pk_bf16_f32 v181, v174, v175
	v_lshl_add_u64 v[174:175], v[130:131], 0, v[156:157]
	v_permlane16_swap_b32_e32 v128, v176
	v_permlane16_swap_b32_e32 v178, v180
	v_permlane16_swap_b32_e32 v179, v181
	v_lshl_add_u64 v[174:175], v[174:175], 0, v[152:153]
	v_permlane16_swap_b32_e32 v129, v182
	global_store_dwordx4 v[174:175], v[178:181], off
	v_and_b32_e32 v175, 0xffff0000, v128
	v_lshlrev_b32_e32 v174, 16, v128
	v_pk_add_f32 v[120:121], v[120:121], v[174:175]
	v_and_b32_e32 v175, 0xffff0000, v129
	v_lshlrev_b32_e32 v174, 16, v129
	v_pk_add_f32 v[122:123], v[122:123], v[174:175]
	v_pk_mul_f32 v[128:129], v[120:121], v[120:121]
	v_pk_mul_f32 v[174:175], v[122:123], v[122:123]
	v_cvt_pk_bf16_f32 v120, v120, v121
	v_cvt_pk_bf16_f32 v121, v122, v123
	v_and_b32_e32 v123, 0xffff0000, v176
	v_lshlrev_b32_e32 v122, 16, v176
	v_pk_add_f32 v[116:117], v[116:117], v[122:123]
	v_and_b32_e32 v123, 0xffff0000, v182
	v_lshlrev_b32_e32 v122, 16, v182
	v_add_f32_e32 v143, v164, v165
	v_add_f32_e32 v160, v160, v161
	v_pk_add_f32 v[118:119], v[118:119], v[122:123]
	v_pk_mul_f32 v[122:123], v[116:117], v[116:117]
	v_add_f32_e32 v143, v162, v143
	v_add_f32_e32 v158, v158, v160
	v_add_f32_e32 v128, v128, v129
	v_pk_mul_f32 v[178:179], v[118:119], v[118:119]
	v_add_f32_e32 v143, v163, v143
	v_add_f32_e32 v158, v159, v158
	v_add_f32_e32 v128, v174, v128
	v_add_f32_e32 v122, v122, v123
	v_add_f32_e32 v143, v158, v143
	v_add_f32_e32 v128, v175, v128
	v_add_f32_e32 v122, v178, v122
	v_add_f32_e32 v128, v143, v128
	v_add_f32_e32 v122, v179, v122
	v_add_f32_e32 v143, v122, v128
	v_lshl_add_u64 v[128:129], s[84:85], 0, v[148:149]
	v_cvt_pk_bf16_f32 v122, v116, v117
	v_cvt_pk_bf16_f32 v123, v118, v119
	v_lshl_add_u64 v[116:117], v[128:129], 0, v[156:157]
	v_permlane16_swap_b32_e32 v120, v122
	v_permlane16_swap_b32_e32 v121, v123
	v_lshl_add_u64 v[116:117], v[116:117], 0, v[152:153]
	global_store_dwordx4 v[116:117], v[120:123], off
	ds_bpermute_b32 v116, v172, v143
	s_waitcnt lgkmcnt(0)
	v_add_f32_e32 v116, v143, v116
	ds_bpermute_b32 v117, v173, v116
	s_and_saveexec_b64 s[10:11], vcc
	s_cbranch_execz .LBB0_71
; template <int MODE, int NSUB>
; __device__ __forceinline__ void epilogue(const Params& p, int layer, f32x4 (&acc)[4][NSUB], int tm, int tn, int g,
;                                          const float* s_rstd, const int tid_in) {
;     ...
;       ss = red_fq(ss);
;       if (fq == 0) p.part[(long)t * 16 + tm * 2 + wr] = ss;
	v_ashrrev_i32_e32 v143, 31, v142
	v_readlane_b32 s64, v253, 25
	v_lshlrev_b64 v[118:119], 6, v[142:143]
	v_readlane_b32 s70, v253, 31
	v_readlane_b32 s71, v253, 32
	s_waitcnt lgkmcnt(0)
	v_add_f32_e32 v116, v116, v117
	v_readlane_b32 s65, v253, 26
	v_lshl_add_u64 v[118:119], s[70:71], 0, v[118:119]
	v_lshl_add_u64 v[118:119], v[140:141], 2, v[118:119]
	v_lshl_add_u64 v[118:119], v[138:139], 2, v[118:119]
	v_readlane_b32 s66, v253, 27
	v_readlane_b32 s67, v253, 28
	v_readlane_b32 s68, v253, 29
	v_readlane_b32 s69, v253, 30
	v_readlane_b32 s72, v253, 33
	v_readlane_b32 s73, v253, 34
	v_readlane_b32 s74, v253, 35
	v_readlane_b32 s75, v253, 36
	v_readlane_b32 s76, v253, 37
	v_readlane_b32 s77, v253, 38
	v_readlane_b32 s78, v253, 39
	v_readlane_b32 s79, v253, 40
	global_store_dword v[118:119], v116, off

; template <int NK, bool BNT = false> ...
;     ...
; #pragma unroll
;   for (int m = 0; m < 4; ++m)
; #pragma unroll
;     for (int n = 0; n < 8; ++n) acc[m][n] = f32x4{0.f, 0.f, 0.f, 0.f};
;   const int sb0 = tidf * 16;
;   const int sr0 = sb0 >> 6;
;   const unsigned soff = (unsigned)(sr0 * 64 + ((((sb0 >> 4) & 3) ^ (((sr0 >> 3) & 1) << 1)) * 16));
;   const unsigned char* Abase = reinterpret_cast<const unsigned char*>(A);
;   const unsigned char* Bbase = reinterpret_cast<const unsigned char*>(B);
;   auto stage = [&](int kt, int bufc) {
;     unsigned char* sa = smem + bufc * BIG_STAGE;
;     const unsigned char* Ab = Abase + (long)kt * 8192 + soff;
;     const unsigned char* Bb = Bbase + (long)kt * 8192 + soff;
;     glds16(Ab, sa + sb0);
;     glds16(Ab + astride * 2, sa + 8192 + sb0);
;     if constexpr (BNT) {
;       glds16_nt(Bb, sa + 16384 + sb0);
;       glds16_nt(Bb + bstride * 2, sa + 24576 + sb0);
;     } else {
;       glds16(Bb, sa + 16384 + sb0);
;       glds16(Bb + bstride * 2, sa + 24576 + sb0);
;     }
;   };
;     ...
;   stage(0, 0);
;   stage(1, 1);
;   stage(2, 2);
.LBB0_263:
	s_ashr_i32 s12, s9, 31
	s_lshr_b32 s12, s12, 27
	s_add_i32 s12, s9, s12
	s_ashr_i32 s13, s12, 5
	s_and_b32 s12, s12, 0xffe0
	s_sub_i32 s12, s9, s12
	s_bfe_i32 s14, s12, 0x80000
	s_bfe_u32 s14, s14, 0x2000d
	s_add_i32 s14, s12, s14
	s_bfe_i32 s17, s14, 0x80000
	s_and_b32 s14, s14, 0xfffc
	s_sext_i32_i16 s17, s17
	s_sub_i32 s14, s12, s14
	s_lshl_b32 s12, s13, 3
	s_ashr_i32 s13, s17, 2
	s_bfe_i64 s[18:19], s[14:15], 0x80000
	s_add_i32 s12, s12, s13
	s_lshl_b64 s[18:19], s[18:19], 21
	s_add_u32 s20, s10, s18
	s_addc_u32 s21, s11, s19
	s_ashr_i32 s13, s12, 31
	v_readlane_b32 s64, v252, 4
	s_lshl_b64 s[22:23], s[12:13], 21
	v_readlane_b32 s78, v252, 18
	v_readfirstlane_b32 s13, v166
	v_add_u32_e32 v146, 0x2000, v166
	v_readlane_b32 s79, v252, 19
	s_add_u32 s24, s78, s22
	v_lshl_add_u64 v[130:131], s[20:21], 0, v[132:133]
	s_mov_b32 m0, s13
	s_mov_b64 s[20:21], 0x100000
	v_readfirstlane_b32 s13, v146
	v_add_u32_e32 v147, 0x4000, v166
	s_addc_u32 s25, s79, s23
	global_load_lds_dwordx4 v[130:131], off
	v_lshl_add_u64 v[0:1], v[130:131], 0, s[20:21]
	s_mov_b32 m0, s13
	v_readfirstlane_b32 s13, v147
	v_add_u32_e32 v148, 0x6000, v166
	v_lshl_add_u64 v[128:129], s[24:25], 0, v[132:133]
	global_load_lds_dwordx4 v[0:1], off
	s_mov_b32 m0, s13
	v_readfirstlane_b32 s13, v148
	v_add_u32_e32 v149, 0x8000, v166
	global_load_lds_dwordx4 v[128:129], off nt
	v_lshl_add_u64 v[0:1], v[128:129], 0, s[20:21]
	s_mov_b32 m0, s13
	s_mov_b64 s[20:21], 0x2000
	v_readfirstlane_b32 s13, v149
	v_add_u32_e32 v150, 0xa000, v166
	global_load_lds_dwordx4 v[0:1], off nt
	v_lshl_add_u64 v[0:1], v[130:131], 0, s[20:21]
	v_lshl_add_u64 v[2:3], v[128:129], 0, s[20:21]
	s_mov_b32 m0, s13
	s_mov_b64 s[20:21], 0x102000
	v_readfirstlane_b32 s13, v150
	v_add_u32_e32 v151, 0xc000, v166
	global_load_lds_dwordx4 v[0:1], off
	v_lshl_add_u64 v[0:1], v[130:131], 0, s[20:21]
	s_mov_b32 m0, s13
	v_readfirstlane_b32 s13, v151
	v_add_u32_e32 v152, 0xe000, v166
	global_load_lds_dwordx4 v[0:1], off
	s_mov_b32 m0, s13
	v_readfirstlane_b32 s13, v152
	v_add_u32_e32 v154, 0x10000, v166
	global_load_lds_dwordx4 v[2:3], off nt
	v_lshl_add_u64 v[0:1], v[128:129], 0, s[20:21]
	s_mov_b32 m0, s13
	v_readfirstlane_b32 s13, v154
	v_add_u32_e32 v155, 0x12000, v166
	global_load_lds_dwordx4 v[0:1], off nt
	v_lshl_add_u64 v[0:1], v[130:131], 0, s[94:95]
	s_mov_b32 m0, s13
	s_mov_b64 s[20:21], 0x104000
	v_readfirstlane_b32 s13, v155
	v_add_u32_e32 v156, 0x14000, v166
	global_load_lds_dwordx4 v[0:1], off
	v_lshl_add_u64 v[0:1], v[130:131], 0, s[20:21]
	s_mov_b32 m0, s13
	v_readfirstlane_b32 s13, v156
	v_add_u32_e32 v157, 0x16000, v166
	v_lshl_add_u64 v[2:3], v[128:129], 0, s[94:95]
	global_load_lds_dwordx4 v[0:1], off
	s_mov_b32 m0, s13
	v_readfirstlane_b32 s13, v157
	global_load_lds_dwordx4 v[2:3], off nt
	v_lshl_add_u64 v[0:1], v[128:129], 0, s[20:21]
	s_mov_b32 m0, s13
	v_lshl_add_u64 v[138:139], v[134:135], 0, s[18:19]
	global_load_lds_dwordx4 v[0:1], off nt
	v_mov_b32_e32 v0, 0
	v_lshl_add_u64 v[140:141], v[136:137], 0, s[22:23]
	s_mov_b64 s[36:37], 0
	v_mov_b32_e32 v1, v0
	v_mov_b32_e32 v2, v0
	v_mov_b32_e32 v3, v0
	v_mov_b32_e32 v4, v0
	s_waitcnt lgkmcnt(0)
	v_mov_b32_e32 v5, v0
	v_mov_b32_e32 v6, v0
	v_mov_b32_e32 v7, v0
	v_mov_b32_e32 v8, v0
	v_mov_b32_e32 v9, v0
	v_mov_b32_e32 v10, v0
	v_mov_b32_e32 v11, v0
	v_mov_b32_e32 v12, v0
	v_mov_b32_e32 v13, v0
	v_mov_b32_e32 v14, v0
	v_mov_b32_e32 v15, v0
	v_mov_b32_e32 v32, v0
	v_mov_b32_e32 v33, v0
	v_mov_b32_e32 v34, v0
	v_mov_b32_e32 v35, v0
	v_mov_b32_e32 v36, v0
	v_mov_b32_e32 v37, v0
	v_mov_b32_e32 v38, v0
	v_mov_b32_e32 v39, v0
	v_mov_b32_e32 v40, v0
	v_mov_b32_e32 v41, v0
	v_mov_b32_e32 v42, v0
	v_mov_b32_e32 v43, v0
	v_mov_b32_e32 v44, v0
	v_mov_b32_e32 v45, v0
	v_mov_b32_e32 v46, v0
	v_mov_b32_e32 v47, v0
	v_mov_b32_e32 v16, v0
	v_mov_b32_e32 v17, v0
	v_mov_b32_e32 v18, v0
	v_mov_b32_e32 v19, v0
	v_mov_b32_e32 v20, v0
	v_mov_b32_e32 v21, v0
	v_mov_b32_e32 v22, v0
	v_mov_b32_e32 v23, v0
	v_mov_b32_e32 v24, v0
	v_mov_b32_e32 v25, v0
	v_mov_b32_e32 v26, v0
	v_mov_b32_e32 v27, v0
	v_mov_b32_e32 v28, v0
	v_mov_b32_e32 v29, v0
	v_mov_b32_e32 v30, v0
	v_mov_b32_e32 v31, v0
	v_mov_b32_e32 v64, v0
	v_mov_b32_e32 v65, v0
	v_mov_b32_e32 v66, v0
	v_mov_b32_e32 v67, v0
	v_mov_b32_e32 v68, v0
	v_mov_b32_e32 v69, v0
	v_mov_b32_e32 v70, v0
	v_mov_b32_e32 v71, v0
	v_mov_b32_e32 v76, v0
	v_mov_b32_e32 v77, v0
	v_mov_b32_e32 v78, v0
	v_mov_b32_e32 v79, v0
	v_mov_b32_e32 v88, v0
	v_mov_b32_e32 v89, v0
	v_mov_b32_e32 v90, v0
	v_mov_b32_e32 v91, v0
	v_mov_b32_e32 v48, v0
	v_mov_b32_e32 v49, v0
	v_mov_b32_e32 v50, v0
	v_mov_b32_e32 v51, v0
	v_mov_b32_e32 v52, v0
	v_mov_b32_e32 v53, v0
	v_mov_b32_e32 v54, v0
	v_mov_b32_e32 v55, v0
	v_mov_b32_e32 v56, v0
	v_mov_b32_e32 v57, v0
	v_mov_b32_e32 v58, v0
	v_mov_b32_e32 v59, v0
	v_mov_b32_e32 v60, v0
	v_mov_b32_e32 v61, v0
	v_mov_b32_e32 v62, v0
	v_mov_b32_e32 v63, v0
	v_mov_b32_e32 v96, v0
	v_mov_b32_e32 v97, v0
	v_mov_b32_e32 v98, v0
	v_mov_b32_e32 v99, v0
	v_mov_b32_e32 v100, v0
	v_mov_b32_e32 v101, v0
	v_mov_b32_e32 v102, v0
	v_mov_b32_e32 v103, v0
	v_mov_b32_e32 v104, v0
	v_mov_b32_e32 v105, v0
	v_mov_b32_e32 v106, v0
	v_mov_b32_e32 v107, v0
	v_mov_b32_e32 v108, v0
	v_mov_b32_e32 v109, v0
	v_mov_b32_e32 v110, v0
	v_mov_b32_e32 v111, v0
	v_mov_b32_e32 v72, v0
	v_mov_b32_e32 v73, v0
	v_mov_b32_e32 v74, v0
	v_mov_b32_e32 v75, v0
	v_mov_b32_e32 v80, v0
	v_mov_b32_e32 v81, v0
	v_mov_b32_e32 v82, v0
	v_mov_b32_e32 v83, v0
	v_mov_b32_e32 v84, v0
	v_mov_b32_e32 v85, v0
	v_mov_b32_e32 v86, v0
	v_mov_b32_e32 v87, v0
	v_mov_b32_e32 v92, v0
	v_mov_b32_e32 v93, v0
	v_mov_b32_e32 v94, v0
	v_mov_b32_e32 v95, v0
	v_mov_b32_e32 v112, v0
	v_mov_b32_e32 v113, v0
	v_mov_b32_e32 v114, v0
	v_mov_b32_e32 v115, v0
	v_mov_b32_e32 v116, v0
	v_mov_b32_e32 v117, v0
	v_mov_b32_e32 v118, v0
	v_mov_b32_e32 v119, v0
	v_mov_b32_e32 v120, v0
	v_mov_b32_e32 v121, v0
	v_mov_b32_e32 v122, v0
	v_mov_b32_e32 v123, v0
	v_mov_b32_e32 v124, v0
	v_mov_b32_e32 v125, v0
	v_mov_b32_e32 v126, v0
	v_mov_b32_e32 v127, v0
	s_mov_b64 s[18:19], 0x106000
	s_mov_b64 s[20:21], 0x108000
	s_mov_b64 s[22:23], 0x10a000
	s_mov_b64 s[24:25], 0x10c000
	v_readlane_b32 s65, v252, 5
	v_readlane_b32 s66, v252, 6
	v_readlane_b32 s67, v252, 7
	v_readlane_b32 s68, v252, 8
	v_readlane_b32 s69, v252, 9
	v_readlane_b32 s70, v252, 10
	v_readlane_b32 s71, v252, 11
	v_readlane_b32 s72, v252, 12
	v_readlane_b32 s73, v252, 13
	v_readlane_b32 s74, v252, 14
	v_readlane_b32 s75, v252, 15
	v_readlane_b32 s76, v252, 16
	v_readlane_b32 s77, v252, 17
	s_waitcnt vmcnt(8)
	s_barrier
; #define BIG_SYNC(N)                                              \
;   asm volatile("s_waitcnt vmcnt(%0)" ::"n"(N) : "memory");       \
;   __builtin_amdgcn_s_barrier();                                  \
;   asm volatile("" ::: "memory");                                 \
;   __builtin_amdgcn_sched_barrier(0);
; template <int NK, bool BNT = false> ...
;     ...
;   auto kstep = [&](int T, int cur, int nxt, bool do_stage) {
;     const unsigned char* sa = smem + cur * BIG_STAGE;
;     bf16x8 af[4], bfr[4];
; #pragma unroll
;     for (int m = 0; m < 4; ++m) af[m] = *reinterpret_cast<const bf16x8*>(sa + aoff + m * 1024);
; #pragma unroll
;     for (int n = 0; n < 4; ++n) bfr[n] = *reinterpret_cast<const bf16x8*>(sa + boff + n * 1024);
;     __builtin_amdgcn_sched_barrier(0);
;     if (do_stage) stage(T + 3, nxt);
; #pragma unroll
;     for (int m = 0; m < 4; ++m)
; #pragma unroll
;       for (int n = 0; n < 4; ++n) acc[m][n] = __builtin_amdgcn_mfma_f32_16x16x32_bf16(af[m], bfr[n], acc[m][n], 0, 0, 0);
;     if (do_stage) {
; #pragma unroll
;       for (int q = 0; q < NG; ++q) {
;         __builtin_amdgcn_sched_group_barrier(0x008, 3, 0);
;         __builtin_amdgcn_sched_group_barrier(0x010, 1, 0);
;       }
;       __builtin_amdgcn_sched_group_barrier(0x008, 16 - 3 * NG, 0);
;     }
;     __builtin_amdgcn_sched_barrier(0);
; #pragma unroll
;     for (int n = 0; n < 4; ++n) bfr[n] = *reinterpret_cast<const bf16x8*>(sa + boff + (4 + n) * 1024);
; #pragma unroll
;     for (int m = 0; m < 4; ++m)
; #pragma unroll
;       for (int n = 0; n < 4; ++n)
;         acc[m][4 + n] = __builtin_amdgcn_mfma_f32_16x16x32_bf16(af[m], bfr[n], acc[m][4 + n], 0, 0, 0);
;     __builtin_amdgcn_sched_barrier(0);
;   };
;     ...
;   stage(0, 0);
;   stage(1, 1);
;   stage(2, 2);
;   for (int it = 0; it < NK / 4 - 1; ++it) {
;     const int t = it * 4;
;     BIG_SYNC(2 * NG); kstep(t, 0, 3, true);
;     BIG_SYNC(2 * NG); kstep(t + 1, 1, 0, true);
;     BIG_SYNC(2 * NG); kstep(t + 2, 2, 1, true);
;     BIG_SYNC(2 * NG); kstep(t + 3, 3, 2, true);
;   }
	v_add_u32_e32 v162, 0x10000, v167
	v_or_b32_e32 v163, 0x10000, v169
	v_add_u32_e32 v176, 0x18000, v167
	v_or_b32_e32 v179, 0x18000, v169
	v_add_u32_e32 v210, 0x10000, v167
	v_or_b32_e32 v211, 0x10000, v169
	v_add_u32_e32 v212, 0x18000, v167
	v_or_b32_e32 v213, 0x18000, v169
	ds_read_b128 v[216:219], v167
	ds_read_b128 v[220:223], v167 offset:1024
	ds_read_b128 v[224:227], v167 offset:2048
	ds_read_b128 v[228:231], v167 offset:3072
	ds_read_b128 v[232:235], v168 offset:16384
	ds_read_b128 v[236:239], v168 offset:17408
	ds_read_b128 v[240:243], v168 offset:18432
	ds_read_b128 v[244:247], v168 offset:19456
.LBB0_264:
	s_waitcnt lgkmcnt(3)
	v_mfma_f32_16x16x32_bf16 v[124:127], v[216:219], v[232:235], v[124:127]
	v_mfma_f32_16x16x32_bf16 v[108:111], v[220:223], v[232:235], v[108:111]
	v_mfma_f32_16x16x32_bf16 v[88:91], v[224:227], v[232:235], v[88:91]
	s_waitcnt vmcnt(4)
	s_barrier
	v_add_u32_e32 v158, 0x18000, v166
	v_lshl_add_u64 v[144:145], v[138:139], 0, s[36:37]
	v_mfma_f32_16x16x32_bf16 v[44:47], v[228:231], v[232:235], v[44:47]
	v_readfirstlane_b32 s13, v158
	v_add_u32_e32 v159, 0x1a000, v166
	s_waitcnt lgkmcnt(2)
	v_mfma_f32_16x16x32_bf16 v[120:123], v[216:219], v[236:239], v[120:123]
	ds_read_b128 v[232:235], v168 offset:20480
	v_mfma_f32_16x16x32_bf16 v[104:107], v[220:223], v[236:239], v[104:107]
	v_lshl_add_u64 v[160:161], v[144:145], 0, s[60:61]
	s_mov_b32 m0, s13
	v_mfma_f32_16x16x32_bf16 v[76:79], v[224:227], v[236:239], v[76:79]
	v_readfirstlane_b32 s13, v159
	v_mfma_f32_16x16x32_bf16 v[40:43], v[228:231], v[236:239], v[40:43]
	v_lshl_add_u64 v[142:143], v[140:141], 0, s[36:37]
	s_waitcnt lgkmcnt(2)
	v_mfma_f32_16x16x32_bf16 v[116:119], v[216:219], v[240:243], v[116:119]
	ds_read_b128 v[236:239], v168 offset:21504
	v_mfma_f32_16x16x32_bf16 v[100:103], v[220:223], v[240:243], v[100:103]
	v_lshl_add_u64 v[182:183], v[142:143], 0, s[60:61]
	v_mfma_f32_16x16x32_bf16 v[68:71], v[224:227], v[240:243], v[68:71]
	global_load_lds_dwordx4 v[160:161], off
	v_mfma_f32_16x16x32_bf16 v[36:39], v[228:231], v[240:243], v[36:39]
	v_lshl_add_u64 v[160:161], v[144:145], 0, s[18:19]
	s_waitcnt lgkmcnt(2)
	v_mfma_f32_16x16x32_bf16 v[112:115], v[216:219], v[244:247], v[112:115]
	ds_read_b128 v[240:243], v168 offset:22528
	v_mfma_f32_16x16x32_bf16 v[96:99], v[220:223], v[244:247], v[96:99]
	s_mov_b32 m0, s13
	v_mfma_f32_16x16x32_bf16 v[64:67], v[224:227], v[244:247], v[64:67]
	global_load_lds_dwordx4 v[160:161], off
	v_mfma_f32_16x16x32_bf16 v[32:35], v[228:231], v[244:247], v[32:35]
	v_add_u32_e32 v160, 0x1c000, v166
	s_waitcnt lgkmcnt(2)
	v_mfma_f32_16x16x32_bf16 v[92:95], v[216:219], v[232:235], v[92:95]
	ds_read_b128 v[244:247], v168 offset:23552
	v_mfma_f32_16x16x32_bf16 v[60:63], v[220:223], v[232:235], v[60:63]
	ds_read_b128 v[186:189], v167 offset:32768
	v_mfma_f32_16x16x32_bf16 v[28:31], v[224:227], v[232:235], v[28:31]
	ds_read_b128 v[190:193], v167 offset:33792
	v_mfma_f32_16x16x32_bf16 v[12:15], v[228:231], v[232:235], v[12:15]
	ds_read_b128 v[194:197], v167 offset:34816
	s_waitcnt lgkmcnt(5)
	v_mfma_f32_16x16x32_bf16 v[84:87], v[216:219], v[236:239], v[84:87]
	ds_read_b128 v[202:205], v167 offset:35840
	ds_read_b128 v[232:235], v168 offset:49152
	v_mfma_f32_16x16x32_bf16 v[56:59], v[220:223], v[236:239], v[56:59]
	v_add_u32_e32 v161, 0x1e000, v166
	v_mfma_f32_16x16x32_bf16 v[24:27], v[224:227], v[236:239], v[24:27]
	v_readfirstlane_b32 s13, v160
	v_mfma_f32_16x16x32_bf16 v[8:11], v[228:231], v[236:239], v[8:11]
	s_mov_b32 m0, s13
	s_waitcnt lgkmcnt(6)
	v_mfma_f32_16x16x32_bf16 v[80:83], v[216:219], v[240:243], v[80:83]
	ds_read_b128 v[236:239], v168 offset:50176
	v_mfma_f32_16x16x32_bf16 v[52:55], v[220:223], v[240:243], v[52:55]
	v_readfirstlane_b32 s13, v161
	v_mfma_f32_16x16x32_bf16 v[20:23], v[224:227], v[240:243], v[20:23]
	global_load_lds_dwordx4 v[182:183], off nt
	v_mfma_f32_16x16x32_bf16 v[4:7], v[228:231], v[240:243], v[4:7]
	v_lshl_add_u64 v[182:183], v[142:143], 0, s[18:19]
	s_waitcnt lgkmcnt(6)
	v_mfma_f32_16x16x32_bf16 v[72:75], v[216:219], v[244:247], v[72:75]
	ds_read_b128 v[240:243], v168 offset:51200
	v_mfma_f32_16x16x32_bf16 v[48:51], v[220:223], v[244:247], v[48:51]
	s_mov_b32 m0, s13
	v_mfma_f32_16x16x32_bf16 v[16:19], v[224:227], v[244:247], v[16:19]
	global_load_lds_dwordx4 v[182:183], off nt
	v_mfma_f32_16x16x32_bf16 v[0:3], v[228:231], v[244:247], v[0:3]
	ds_read_b128 v[244:247], v168 offset:52224
	s_waitcnt lgkmcnt(3)
	v_mfma_f32_16x16x32_bf16 v[124:127], v[186:189], v[232:235], v[124:127]
	v_mfma_f32_16x16x32_bf16 v[108:111], v[190:193], v[232:235], v[108:111]
	v_mfma_f32_16x16x32_bf16 v[88:91], v[194:197], v[232:235], v[88:91]
	s_waitcnt vmcnt(4)
	s_barrier
; #define BIG_SYNC(N)                                              \
;   asm volatile("s_waitcnt vmcnt(%0)" ::"n"(N) : "memory");       \
;   __builtin_amdgcn_s_barrier();                                  \
;   asm volatile("" ::: "memory");                                 \
;   __builtin_amdgcn_sched_barrier(0);
; template <int NK, bool BNT = false> ...
;     ...
;   auto kstep = [&](int T, int cur, int nxt, bool do_stage) {
;     const unsigned char* sa = smem + cur * BIG_STAGE;
;     bf16x8 af[4], bfr[4];
; #pragma unroll
;     for (int m = 0; m < 4; ++m) af[m] = *reinterpret_cast<const bf16x8*>(sa + aoff + m * 1024);
; #pragma unroll
;     for (int n = 0; n < 4; ++n) bfr[n] = *reinterpret_cast<const bf16x8*>(sa + boff + n * 1024);
;     __builtin_amdgcn_sched_barrier(0);
;     if (do_stage) stage(T + 3, nxt);
; #pragma unroll
;     for (int m = 0; m < 4; ++m)
; #pragma unroll
;       for (int n = 0; n < 4; ++n) acc[m][n] = __builtin_amdgcn_mfma_f32_16x16x32_bf16(af[m], bfr[n], acc[m][n], 0, 0, 0);
;     if (do_stage) {
; #pragma unroll
;       for (int q = 0; q < NG; ++q) {
;         __builtin_amdgcn_sched_group_barrier(0x008, 3, 0);
;         __builtin_amdgcn_sched_group_barrier(0x010, 1, 0);
;       }
;       __builtin_amdgcn_sched_group_barrier(0x008, 16 - 3 * NG, 0);
;     }
;     __builtin_amdgcn_sched_barrier(0);
; #pragma unroll
;     for (int n = 0; n < 4; ++n) bfr[n] = *reinterpret_cast<const bf16x8*>(sa + boff + (4 + n) * 1024);
; #pragma unroll
;     for (int m = 0; m < 4; ++m)
; #pragma unroll
;       for (int n = 0; n < 4; ++n)
;         acc[m][4 + n] = __builtin_amdgcn_mfma_f32_16x16x32_bf16(af[m], bfr[n], acc[m][4 + n], 0, 0, 0);
;     __builtin_amdgcn_sched_barrier(0);
;   };
;     ...
;   stage(0, 0);
;   stage(1, 1);
;   stage(2, 2);
;   for (int it = 0; it < NK / 4 - 1; ++it) {
;     const int t = it * 4;
;     BIG_SYNC(2 * NG); kstep(t, 0, 3, true);
;     BIG_SYNC(2 * NG); kstep(t + 1, 1, 0, true);
;     BIG_SYNC(2 * NG); kstep(t + 2, 2, 1, true);
;     BIG_SYNC(2 * NG); kstep(t + 3, 3, 2, true);
;   }
	v_readfirstlane_b32 s13, v166
	v_mfma_f32_16x16x32_bf16 v[44:47], v[202:205], v[232:235], v[44:47]
	v_lshl_add_u64 v[182:183], v[144:145], 0, s[62:63]
	s_waitcnt lgkmcnt(2)
	v_mfma_f32_16x16x32_bf16 v[120:123], v[186:189], v[236:239], v[120:123]
	ds_read_b128 v[232:235], v168 offset:53248
	v_mfma_f32_16x16x32_bf16 v[104:107], v[190:193], v[236:239], v[104:107]
	s_mov_b32 m0, s13
	v_mfma_f32_16x16x32_bf16 v[76:79], v[194:197], v[236:239], v[76:79]
	v_readfirstlane_b32 s13, v146
	v_mfma_f32_16x16x32_bf16 v[40:43], v[202:205], v[236:239], v[40:43]
	v_lshl_add_u64 v[198:199], v[142:143], 0, s[62:63]
	s_waitcnt lgkmcnt(2)
	v_mfma_f32_16x16x32_bf16 v[116:119], v[186:189], v[240:243], v[116:119]
	ds_read_b128 v[236:239], v168 offset:54272
	v_mfma_f32_16x16x32_bf16 v[100:103], v[190:193], v[240:243], v[100:103]
	global_load_lds_dwordx4 v[182:183], off
	v_mfma_f32_16x16x32_bf16 v[68:71], v[194:197], v[240:243], v[68:71]
	v_lshl_add_u64 v[182:183], v[144:145], 0, s[20:21]
	v_mfma_f32_16x16x32_bf16 v[36:39], v[202:205], v[240:243], v[36:39]
	s_mov_b32 m0, s13
	s_waitcnt lgkmcnt(2)
	v_mfma_f32_16x16x32_bf16 v[112:115], v[186:189], v[244:247], v[112:115]
	ds_read_b128 v[240:243], v168 offset:55296
	v_mfma_f32_16x16x32_bf16 v[96:99], v[190:193], v[244:247], v[96:99]
	v_readfirstlane_b32 s13, v147
	v_mfma_f32_16x16x32_bf16 v[64:67], v[194:197], v[244:247], v[64:67]
	global_load_lds_dwordx4 v[182:183], off
	v_mfma_f32_16x16x32_bf16 v[32:35], v[202:205], v[244:247], v[32:35]
	s_mov_b32 m0, s13
	s_waitcnt lgkmcnt(2)
	v_mfma_f32_16x16x32_bf16 v[92:95], v[186:189], v[232:235], v[92:95]
	ds_read_b128 v[244:247], v168 offset:56320
	v_mfma_f32_16x16x32_bf16 v[60:63], v[190:193], v[232:235], v[60:63]
	ds_read_b128 v[216:219], v210
	v_mfma_f32_16x16x32_bf16 v[28:31], v[194:197], v[232:235], v[28:31]
	ds_read_b128 v[220:223], v210 offset:1024
	v_mfma_f32_16x16x32_bf16 v[12:15], v[202:205], v[232:235], v[12:15]
	ds_read_b128 v[224:227], v210 offset:2048
	s_waitcnt lgkmcnt(5)
	v_mfma_f32_16x16x32_bf16 v[84:87], v[186:189], v[236:239], v[84:87]
	ds_read_b128 v[228:231], v210 offset:3072
	ds_read_b128 v[232:235], v211
	v_mfma_f32_16x16x32_bf16 v[56:59], v[190:193], v[236:239], v[56:59]
	v_readfirstlane_b32 s13, v148
	v_mfma_f32_16x16x32_bf16 v[24:27], v[194:197], v[236:239], v[24:27]
	v_lshl_add_u64 v[182:183], v[142:143], 0, s[20:21]
	v_mfma_f32_16x16x32_bf16 v[8:11], v[202:205], v[236:239], v[8:11]
	global_load_lds_dwordx4 v[198:199], off nt
	s_waitcnt lgkmcnt(6)
	v_mfma_f32_16x16x32_bf16 v[80:83], v[186:189], v[240:243], v[80:83]
	ds_read_b128 v[236:239], v211 offset:1024
	v_mfma_f32_16x16x32_bf16 v[52:55], v[190:193], v[240:243], v[52:55]
	s_mov_b32 m0, s13
	v_mfma_f32_16x16x32_bf16 v[20:23], v[194:197], v[240:243], v[20:23]
	global_load_lds_dwordx4 v[182:183], off nt
	v_mfma_f32_16x16x32_bf16 v[4:7], v[202:205], v[240:243], v[4:7]
	s_waitcnt lgkmcnt(6)
	v_mfma_f32_16x16x32_bf16 v[72:75], v[186:189], v[244:247], v[72:75]
	ds_read_b128 v[240:243], v211 offset:2048
	v_mfma_f32_16x16x32_bf16 v[48:51], v[190:193], v[244:247], v[48:51]
	v_mfma_f32_16x16x32_bf16 v[16:19], v[194:197], v[244:247], v[16:19]
	v_mfma_f32_16x16x32_bf16 v[0:3], v[202:205], v[244:247], v[0:3]
	ds_read_b128 v[244:247], v211 offset:3072
	s_waitcnt lgkmcnt(3)
	v_mfma_f32_16x16x32_bf16 v[124:127], v[216:219], v[232:235], v[124:127]
	v_mfma_f32_16x16x32_bf16 v[108:111], v[220:223], v[232:235], v[108:111]
	v_mfma_f32_16x16x32_bf16 v[88:91], v[224:227], v[232:235], v[88:91]
	s_waitcnt vmcnt(4)
	s_barrier
	v_add_u32_e32 v162, 0x10000, v167
	v_or_b32_e32 v163, 0x10000, v169
	v_mfma_f32_16x16x32_bf16 v[44:47], v[228:231], v[232:235], v[44:47]
	v_add_u32_e32 v164, 0x10400, v169
	v_add_u32_e32 v165, 0x10800, v169
	s_waitcnt lgkmcnt(2)
	v_mfma_f32_16x16x32_bf16 v[120:123], v[216:219], v[236:239], v[120:123]
	ds_read_b128 v[232:235], v211 offset:4096
	v_mfma_f32_16x16x32_bf16 v[104:107], v[220:223], v[236:239], v[104:107]
	v_add_u32_e32 v172, 0x10c00, v169
	v_mfma_f32_16x16x32_bf16 v[76:79], v[224:227], v[236:239], v[76:79]
	v_readfirstlane_b32 s13, v149
	v_mfma_f32_16x16x32_bf16 v[40:43], v[228:231], v[236:239], v[40:43]
	v_lshl_add_u64 v[174:175], v[144:145], 0, s[2:3]
	s_waitcnt lgkmcnt(2)
	v_mfma_f32_16x16x32_bf16 v[116:119], v[216:219], v[240:243], v[116:119]
	ds_read_b128 v[236:239], v211 offset:5120
	v_mfma_f32_16x16x32_bf16 v[100:103], v[220:223], v[240:243], v[100:103]
	s_mov_b32 m0, s13
	v_mfma_f32_16x16x32_bf16 v[68:71], v[224:227], v[240:243], v[68:71]
	v_readfirstlane_b32 s13, v150
	v_mfma_f32_16x16x32_bf16 v[36:39], v[228:231], v[240:243], v[36:39]
	v_lshl_add_u64 v[178:179], v[142:143], 0, s[2:3]
	s_waitcnt lgkmcnt(2)
	v_mfma_f32_16x16x32_bf16 v[112:115], v[216:219], v[244:247], v[112:115]
	ds_read_b128 v[240:243], v211 offset:6144
	v_mfma_f32_16x16x32_bf16 v[96:99], v[220:223], v[244:247], v[96:99]
	global_load_lds_dwordx4 v[174:175], off
	v_mfma_f32_16x16x32_bf16 v[64:67], v[224:227], v[244:247], v[64:67]
	v_lshl_add_u64 v[174:175], v[144:145], 0, s[22:23]
	v_mfma_f32_16x16x32_bf16 v[32:35], v[228:231], v[244:247], v[32:35]
	s_mov_b32 m0, s13
	s_waitcnt lgkmcnt(2)
	v_mfma_f32_16x16x32_bf16 v[92:95], v[216:219], v[232:235], v[92:95]
	ds_read_b128 v[244:247], v211 offset:7168
	v_mfma_f32_16x16x32_bf16 v[60:63], v[220:223], v[232:235], v[60:63]
	ds_read_b128 v[186:189], v210 offset:32768
	v_mfma_f32_16x16x32_bf16 v[28:31], v[224:227], v[232:235], v[28:31]
	ds_read_b128 v[190:193], v210 offset:33792
	v_mfma_f32_16x16x32_bf16 v[12:15], v[228:231], v[232:235], v[12:15]
	ds_read_b128 v[194:197], v210 offset:34816
	s_waitcnt lgkmcnt(5)
; #define BIG_SYNC(N)                                              \
;   asm volatile("s_waitcnt vmcnt(%0)" ::"n"(N) : "memory");       \
;   __builtin_amdgcn_s_barrier();                                  \
;   asm volatile("" ::: "memory");                                 \
;   __builtin_amdgcn_sched_barrier(0);
; template <int NK, bool BNT = false> ...
;     ...
;   auto kstep = [&](int T, int cur, int nxt, bool do_stage) {
;     const unsigned char* sa = smem + cur * BIG_STAGE;
;     bf16x8 af[4], bfr[4];
; #pragma unroll
;     for (int m = 0; m < 4; ++m) af[m] = *reinterpret_cast<const bf16x8*>(sa + aoff + m * 1024);
; #pragma unroll
;     for (int n = 0; n < 4; ++n) bfr[n] = *reinterpret_cast<const bf16x8*>(sa + boff + n * 1024);
;     __builtin_amdgcn_sched_barrier(0);
;     if (do_stage) stage(T + 3, nxt);
; #pragma unroll
;     for (int m = 0; m < 4; ++m)
; #pragma unroll
;       for (int n = 0; n < 4; ++n) acc[m][n] = __builtin_amdgcn_mfma_f32_16x16x32_bf16(af[m], bfr[n], acc[m][n], 0, 0, 0);
;     if (do_stage) {
; #pragma unroll
;       for (int q = 0; q < NG; ++q) {
;         __builtin_amdgcn_sched_group_barrier(0x008, 3, 0);
;         __builtin_amdgcn_sched_group_barrier(0x010, 1, 0);
;       }
;       __builtin_amdgcn_sched_group_barrier(0x008, 16 - 3 * NG, 0);
;     }
;     __builtin_amdgcn_sched_barrier(0);
; #pragma unroll
;     for (int n = 0; n < 4; ++n) bfr[n] = *reinterpret_cast<const bf16x8*>(sa + boff + (4 + n) * 1024);
; #pragma unroll
;     for (int m = 0; m < 4; ++m)
; #pragma unroll
;       for (int n = 0; n < 4; ++n)
;         acc[m][4 + n] = __builtin_amdgcn_mfma_f32_16x16x32_bf16(af[m], bfr[n], acc[m][4 + n], 0, 0, 0);
;     __builtin_amdgcn_sched_barrier(0);
;   };
;     ...
;   stage(0, 0);
;   stage(1, 1);
;   stage(2, 2);
;   for (int it = 0; it < NK / 4 - 1; ++it) {
;     const int t = it * 4;
;     BIG_SYNC(2 * NG); kstep(t, 0, 3, true);
;     BIG_SYNC(2 * NG); kstep(t + 1, 1, 0, true);
;     BIG_SYNC(2 * NG); kstep(t + 2, 2, 1, true);
;     BIG_SYNC(2 * NG); kstep(t + 3, 3, 2, true);
;   }
	v_mfma_f32_16x16x32_bf16 v[84:87], v[216:219], v[236:239], v[84:87]
	ds_read_b128 v[202:205], v210 offset:35840
	ds_read_b128 v[232:235], v211 offset:32768
	v_mfma_f32_16x16x32_bf16 v[56:59], v[220:223], v[236:239], v[56:59]
	v_readfirstlane_b32 s13, v151
	v_mfma_f32_16x16x32_bf16 v[24:27], v[224:227], v[236:239], v[24:27]
	global_load_lds_dwordx4 v[174:175], off
	v_mfma_f32_16x16x32_bf16 v[8:11], v[228:231], v[236:239], v[8:11]
	s_mov_b32 m0, s13
	s_waitcnt lgkmcnt(6)
	v_mfma_f32_16x16x32_bf16 v[80:83], v[216:219], v[240:243], v[80:83]
	ds_read_b128 v[236:239], v211 offset:33792
	v_mfma_f32_16x16x32_bf16 v[52:55], v[220:223], v[240:243], v[52:55]
	v_readfirstlane_b32 s13, v152
	v_mfma_f32_16x16x32_bf16 v[20:23], v[224:227], v[240:243], v[20:23]
	v_lshl_add_u64 v[174:175], v[142:143], 0, s[22:23]
	v_mfma_f32_16x16x32_bf16 v[4:7], v[228:231], v[240:243], v[4:7]
	global_load_lds_dwordx4 v[178:179], off nt
	s_waitcnt lgkmcnt(6)
	v_mfma_f32_16x16x32_bf16 v[72:75], v[216:219], v[244:247], v[72:75]
	ds_read_b128 v[240:243], v211 offset:34816
	v_mfma_f32_16x16x32_bf16 v[48:51], v[220:223], v[244:247], v[48:51]
	s_mov_b32 m0, s13
	v_mfma_f32_16x16x32_bf16 v[16:19], v[224:227], v[244:247], v[16:19]
	global_load_lds_dwordx4 v[174:175], off nt
	v_mfma_f32_16x16x32_bf16 v[0:3], v[228:231], v[244:247], v[0:3]
	ds_read_b128 v[244:247], v211 offset:35840
	v_add_u32_e32 v173, 0x11000, v169
	v_add_u32_e32 v174, 0x11400, v169
	v_add_u32_e32 v175, 0x11800, v169
	v_add_u32_e32 v178, 0x11c00, v169
	s_waitcnt lgkmcnt(3)
	v_mfma_f32_16x16x32_bf16 v[124:127], v[186:189], v[232:235], v[124:127]
	v_mfma_f32_16x16x32_bf16 v[108:111], v[190:193], v[232:235], v[108:111]
	v_mfma_f32_16x16x32_bf16 v[88:91], v[194:197], v[232:235], v[88:91]
	s_waitcnt vmcnt(4)
	s_barrier
	v_add_u32_e32 v176, 0x18000, v167
	v_or_b32_e32 v179, 0x18000, v169
	v_mfma_f32_16x16x32_bf16 v[44:47], v[202:205], v[232:235], v[44:47]
	v_add_u32_e32 v180, 0x18400, v169
	v_add_u32_e32 v181, 0x18800, v169
	s_waitcnt lgkmcnt(2)
	v_mfma_f32_16x16x32_bf16 v[120:123], v[186:189], v[236:239], v[120:123]
	ds_read_b128 v[232:235], v211 offset:36864
	v_mfma_f32_16x16x32_bf16 v[104:107], v[190:193], v[236:239], v[104:107]
	v_add_u32_e32 v182, 0x18c00, v169
	v_mfma_f32_16x16x32_bf16 v[76:79], v[194:197], v[236:239], v[76:79]
	v_readfirstlane_b32 s13, v154
	v_mfma_f32_16x16x32_bf16 v[40:43], v[202:205], v[236:239], v[40:43]
	v_lshl_add_u64 v[248:249], v[144:145], 0, s[54:55]
	s_waitcnt lgkmcnt(2)
	v_mfma_f32_16x16x32_bf16 v[116:119], v[186:189], v[240:243], v[116:119]
	ds_read_b128 v[236:239], v211 offset:37888
	v_mfma_f32_16x16x32_bf16 v[100:103], v[190:193], v[240:243], v[100:103]
	s_mov_b32 m0, s13
	v_mfma_f32_16x16x32_bf16 v[68:71], v[194:197], v[240:243], v[68:71]
	v_readfirstlane_b32 s13, v155
	v_mfma_f32_16x16x32_bf16 v[36:39], v[202:205], v[240:243], v[36:39]
	v_lshl_add_u64 v[144:145], v[144:145], 0, s[24:25]
	s_waitcnt lgkmcnt(2)
	v_mfma_f32_16x16x32_bf16 v[112:115], v[186:189], v[244:247], v[112:115]
	ds_read_b128 v[240:243], v211 offset:38912
	v_mfma_f32_16x16x32_bf16 v[96:99], v[190:193], v[244:247], v[96:99]
	v_lshl_add_u64 v[250:251], v[142:143], 0, s[54:55]
	v_mfma_f32_16x16x32_bf16 v[64:67], v[194:197], v[244:247], v[64:67]
	v_lshl_add_u64 v[142:143], v[142:143], 0, s[24:25]
	v_mfma_f32_16x16x32_bf16 v[32:35], v[202:205], v[244:247], v[32:35]
	global_load_lds_dwordx4 v[248:249], off
	s_waitcnt lgkmcnt(2)
	v_mfma_f32_16x16x32_bf16 v[92:95], v[186:189], v[232:235], v[92:95]
	ds_read_b128 v[244:247], v211 offset:39936
	v_mfma_f32_16x16x32_bf16 v[60:63], v[190:193], v[232:235], v[60:63]
	ds_read_b128 v[216:219], v167
	v_mfma_f32_16x16x32_bf16 v[28:31], v[194:197], v[232:235], v[28:31]
	ds_read_b128 v[220:223], v167 offset:1024
	v_mfma_f32_16x16x32_bf16 v[12:15], v[202:205], v[232:235], v[12:15]
	ds_read_b128 v[224:227], v167 offset:2048
	s_waitcnt lgkmcnt(5)
	v_mfma_f32_16x16x32_bf16 v[84:87], v[186:189], v[236:239], v[84:87]
	ds_read_b128 v[228:231], v167 offset:3072
	ds_read_b128 v[232:235], v168 offset:16384
	v_mfma_f32_16x16x32_bf16 v[56:59], v[190:193], v[236:239], v[56:59]
	s_mov_b32 m0, s13
	v_mfma_f32_16x16x32_bf16 v[24:27], v[194:197], v[236:239], v[24:27]
	v_readfirstlane_b32 s13, v156
	v_mfma_f32_16x16x32_bf16 v[8:11], v[202:205], v[236:239], v[8:11]
	global_load_lds_dwordx4 v[144:145], off
	s_waitcnt lgkmcnt(6)
	v_mfma_f32_16x16x32_bf16 v[80:83], v[186:189], v[240:243], v[80:83]
	ds_read_b128 v[236:239], v168 offset:17408
	v_mfma_f32_16x16x32_bf16 v[52:55], v[190:193], v[240:243], v[52:55]
	s_mov_b32 m0, s13
	v_mfma_f32_16x16x32_bf16 v[20:23], v[194:197], v[240:243], v[20:23]
	v_readfirstlane_b32 s13, v157
	v_mfma_f32_16x16x32_bf16 v[4:7], v[202:205], v[240:243], v[4:7]
	global_load_lds_dwordx4 v[250:251], off nt
	s_waitcnt lgkmcnt(6)
	v_mfma_f32_16x16x32_bf16 v[72:75], v[186:189], v[244:247], v[72:75]
	ds_read_b128 v[240:243], v168 offset:18432
	v_mfma_f32_16x16x32_bf16 v[48:51], v[190:193], v[244:247], v[48:51]
	s_mov_b32 m0, s13
	v_mfma_f32_16x16x32_bf16 v[16:19], v[194:197], v[244:247], v[16:19]
	global_load_lds_dwordx4 v[142:143], off nt
	v_mfma_f32_16x16x32_bf16 v[0:3], v[202:205], v[244:247], v[0:3]
	ds_read_b128 v[244:247], v168 offset:19456
	v_add_u32_e32 v142, 0x19000, v169
	v_add_u32_e32 v143, 0x19400, v169
	v_add_u32_e32 v144, 0x19800, v169
	v_add_u32_e32 v145, 0x19c00, v169
	s_add_u32 s36, s36, 0x8000
	s_addc_u32 s37, s37, 0
	s_cmp_lg_u32 s36, 0xf8000
	s_cbranch_scc1 .LBB0_264
	s_waitcnt lgkmcnt(3)
	v_mfma_f32_16x16x32_bf16 v[124:127], v[216:219], v[232:235], v[124:127]
	v_mfma_f32_16x16x32_bf16 v[108:111], v[220:223], v[232:235], v[108:111]
	v_mfma_f32_16x16x32_bf16 v[88:91], v[224:227], v[232:235], v[88:91]
	s_waitcnt vmcnt(4)
	s_barrier
; #define BIG_SYNC(N)                                              \
;   asm volatile("s_waitcnt vmcnt(%0)" ::"n"(N) : "memory");       \
;   __builtin_amdgcn_s_barrier();                                  \
;   asm volatile("" ::: "memory");                                 \
;   __builtin_amdgcn_sched_barrier(0);
; template <int NK, bool BNT = false> ...
;     ...
;   auto kstep = [&](int T, int cur, int nxt, bool do_stage) {
;     const unsigned char* sa = smem + cur * BIG_STAGE;
;     bf16x8 af[4], bfr[4];
; #pragma unroll
;     for (int m = 0; m < 4; ++m) af[m] = *reinterpret_cast<const bf16x8*>(sa + aoff + m * 1024);
; #pragma unroll
;     for (int n = 0; n < 4; ++n) bfr[n] = *reinterpret_cast<const bf16x8*>(sa + boff + n * 1024);
;     __builtin_amdgcn_sched_barrier(0);
;     if (do_stage) stage(T + 3, nxt);
; #pragma unroll
;     for (int m = 0; m < 4; ++m)
; #pragma unroll
;       for (int n = 0; n < 4; ++n) acc[m][n] = __builtin_amdgcn_mfma_f32_16x16x32_bf16(af[m], bfr[n], acc[m][n], 0, 0, 0);
;     if (do_stage) {
; #pragma unroll
;       for (int q = 0; q < NG; ++q) {
;         __builtin_amdgcn_sched_group_barrier(0x008, 3, 0);
;         __builtin_amdgcn_sched_group_barrier(0x010, 1, 0);
;       }
;       __builtin_amdgcn_sched_group_barrier(0x008, 16 - 3 * NG, 0);
;     }
;     __builtin_amdgcn_sched_barrier(0);
; #pragma unroll
;     for (int n = 0; n < 4; ++n) bfr[n] = *reinterpret_cast<const bf16x8*>(sa + boff + (4 + n) * 1024);
; #pragma unroll
;     for (int m = 0; m < 4; ++m)
; #pragma unroll
;       for (int n = 0; n < 4; ++n)
;         acc[m][4 + n] = __builtin_amdgcn_mfma_f32_16x16x32_bf16(af[m], bfr[n], acc[m][4 + n], 0, 0, 0);
;     __builtin_amdgcn_sched_barrier(0);
;   };
;     ...
;   stage(0, 0);
;   stage(1, 1);
;   stage(2, 2);
;   for (int it = 0; it < NK / 4 - 1; ++it) {
;     const int t = it * 4;
;     BIG_SYNC(2 * NG); kstep(t, 0, 3, true);
;     BIG_SYNC(2 * NG); kstep(t + 1, 1, 0, true);
;     BIG_SYNC(2 * NG); kstep(t + 2, 2, 1, true);
;     BIG_SYNC(2 * NG); kstep(t + 3, 3, 2, true);
;   }
;   BIG_SYNC(2 * NG); kstep(NK - 4, 0, 3, true);
;   BIG_SYNC(2 * NG); kstep(NK - 3, 1, 0, false);
;   BIG_SYNC(NG);     kstep(NK - 2, 2, 0, false);
;   BIG_SYNC(0);      kstep(NK - 1, 3, 0, false);
	s_sext_i32_i8 s13, s14
	v_mfma_f32_16x16x32_bf16 v[44:47], v[228:231], v[232:235], v[44:47]
	s_mov_b64 s[18:19], 0xfe000
	s_waitcnt lgkmcnt(2)
	v_mfma_f32_16x16x32_bf16 v[120:123], v[216:219], v[236:239], v[120:123]
	ds_read_b128 v[232:235], v168 offset:20480
	v_mfma_f32_16x16x32_bf16 v[104:107], v[220:223], v[236:239], v[104:107]
	v_readfirstlane_b32 s14, v158
	v_mfma_f32_16x16x32_bf16 v[76:79], v[224:227], v[236:239], v[76:79]
	v_lshl_add_u64 v[150:151], v[130:131], 0, s[18:19]
	v_mfma_f32_16x16x32_bf16 v[40:43], v[228:231], v[236:239], v[40:43]
	v_lshl_add_u64 v[198:199], v[128:129], 0, s[18:19]
	s_waitcnt lgkmcnt(2)
	v_mfma_f32_16x16x32_bf16 v[116:119], v[216:219], v[240:243], v[116:119]
	ds_read_b128 v[236:239], v168 offset:21504
	v_mfma_f32_16x16x32_bf16 v[100:103], v[220:223], v[240:243], v[100:103]
	s_mov_b32 m0, s14
	v_mfma_f32_16x16x32_bf16 v[68:71], v[224:227], v[240:243], v[68:71]
	s_mov_b64 s[18:19], 0x1fe000
	v_mfma_f32_16x16x32_bf16 v[36:39], v[228:231], v[240:243], v[36:39]
	v_readfirstlane_b32 s14, v159
	s_waitcnt lgkmcnt(2)
	v_mfma_f32_16x16x32_bf16 v[112:115], v[216:219], v[244:247], v[112:115]
	ds_read_b128 v[240:243], v168 offset:22528
	v_mfma_f32_16x16x32_bf16 v[96:99], v[220:223], v[244:247], v[96:99]
	v_lshl_add_u64 v[130:131], v[130:131], 0, s[18:19]
	v_mfma_f32_16x16x32_bf16 v[64:67], v[224:227], v[244:247], v[64:67]
	v_lshl_add_u64 v[128:129], v[128:129], 0, s[18:19]
	v_mfma_f32_16x16x32_bf16 v[32:35], v[228:231], v[244:247], v[32:35]
	global_load_lds_dwordx4 v[150:151], off
	s_waitcnt lgkmcnt(2)
	v_mfma_f32_16x16x32_bf16 v[92:95], v[216:219], v[232:235], v[92:95]
	ds_read_b128 v[244:247], v168 offset:23552
	v_mfma_f32_16x16x32_bf16 v[60:63], v[220:223], v[232:235], v[60:63]
	ds_read_b128 v[186:189], v167 offset:32768
	v_mfma_f32_16x16x32_bf16 v[28:31], v[224:227], v[232:235], v[28:31]
	ds_read_b128 v[190:193], v167 offset:33792
	v_mfma_f32_16x16x32_bf16 v[12:15], v[228:231], v[232:235], v[12:15]
	ds_read_b128 v[194:197], v167 offset:34816
	s_waitcnt lgkmcnt(5)
	v_mfma_f32_16x16x32_bf16 v[84:87], v[216:219], v[236:239], v[84:87]
	ds_read_b128 v[202:205], v167 offset:35840
	ds_read_b128 v[232:235], v168 offset:49152
	v_mfma_f32_16x16x32_bf16 v[56:59], v[220:223], v[236:239], v[56:59]
	s_mov_b32 m0, s14
	v_mfma_f32_16x16x32_bf16 v[24:27], v[224:227], v[236:239], v[24:27]
	v_readfirstlane_b32 s14, v160
	v_mfma_f32_16x16x32_bf16 v[8:11], v[228:231], v[236:239], v[8:11]
	global_load_lds_dwordx4 v[130:131], off
	s_waitcnt lgkmcnt(6)
	v_mfma_f32_16x16x32_bf16 v[80:83], v[216:219], v[240:243], v[80:83]
	ds_read_b128 v[236:239], v168 offset:50176
	v_mfma_f32_16x16x32_bf16 v[52:55], v[220:223], v[240:243], v[52:55]
	s_mov_b32 m0, s14
	v_mfma_f32_16x16x32_bf16 v[20:23], v[224:227], v[240:243], v[20:23]
	v_readfirstlane_b32 s14, v161
	v_mfma_f32_16x16x32_bf16 v[4:7], v[228:231], v[240:243], v[4:7]
	global_load_lds_dwordx4 v[198:199], off nt
	s_waitcnt lgkmcnt(6)
	v_mfma_f32_16x16x32_bf16 v[72:75], v[216:219], v[244:247], v[72:75]
	ds_read_b128 v[240:243], v168 offset:51200
	v_mfma_f32_16x16x32_bf16 v[48:51], v[220:223], v[244:247], v[48:51]
	s_mov_b32 m0, s14
	v_mfma_f32_16x16x32_bf16 v[16:19], v[224:227], v[244:247], v[16:19]
	global_load_lds_dwordx4 v[128:129], off nt
	v_mfma_f32_16x16x32_bf16 v[0:3], v[228:231], v[244:247], v[0:3]
	ds_read_b128 v[244:247], v168 offset:52224
	s_waitcnt lgkmcnt(3)
	v_mfma_f32_16x16x32_bf16 v[124:127], v[186:189], v[232:235], v[124:127]
	v_mfma_f32_16x16x32_bf16 v[108:111], v[190:193], v[232:235], v[108:111]
	v_mfma_f32_16x16x32_bf16 v[88:91], v[194:197], v[232:235], v[88:91]
	v_mfma_f32_16x16x32_bf16 v[44:47], v[202:205], v[232:235], v[44:47]
	s_waitcnt vmcnt(4)
	s_barrier
	s_waitcnt lgkmcnt(2)
	v_mfma_f32_16x16x32_bf16 v[120:123], v[186:189], v[236:239], v[120:123]
	ds_read_b128 v[232:235], v168 offset:53248
	v_mfma_f32_16x16x32_bf16 v[104:107], v[190:193], v[236:239], v[104:107]
	v_mfma_f32_16x16x32_bf16 v[76:79], v[194:197], v[236:239], v[76:79]
	v_mfma_f32_16x16x32_bf16 v[40:43], v[202:205], v[236:239], v[40:43]
	s_waitcnt lgkmcnt(2)
	v_mfma_f32_16x16x32_bf16 v[116:119], v[186:189], v[240:243], v[116:119]
	ds_read_b128 v[236:239], v168 offset:54272
	v_mfma_f32_16x16x32_bf16 v[100:103], v[190:193], v[240:243], v[100:103]
	v_mfma_f32_16x16x32_bf16 v[68:71], v[194:197], v[240:243], v[68:71]
	v_mfma_f32_16x16x32_bf16 v[36:39], v[202:205], v[240:243], v[36:39]
	s_waitcnt lgkmcnt(2)
	v_mfma_f32_16x16x32_bf16 v[112:115], v[186:189], v[244:247], v[112:115]
	ds_read_b128 v[240:243], v168 offset:55296
	v_mfma_f32_16x16x32_bf16 v[96:99], v[190:193], v[244:247], v[96:99]
	v_mfma_f32_16x16x32_bf16 v[64:67], v[194:197], v[244:247], v[64:67]
	v_mfma_f32_16x16x32_bf16 v[32:35], v[202:205], v[244:247], v[32:35]
	s_waitcnt lgkmcnt(2)
	v_mfma_f32_16x16x32_bf16 v[92:95], v[186:189], v[232:235], v[92:95]
	ds_read_b128 v[244:247], v168 offset:56320
	v_mfma_f32_16x16x32_bf16 v[60:63], v[190:193], v[232:235], v[60:63]
	v_mfma_f32_16x16x32_bf16 v[28:31], v[194:197], v[232:235], v[28:31]
	v_mfma_f32_16x16x32_bf16 v[12:15], v[202:205], v[232:235], v[12:15]
	s_waitcnt lgkmcnt(2)
	v_mfma_f32_16x16x32_bf16 v[84:87], v[186:189], v[236:239], v[84:87]
	v_mfma_f32_16x16x32_bf16 v[56:59], v[190:193], v[236:239], v[56:59]
	v_mfma_f32_16x16x32_bf16 v[24:27], v[194:197], v[236:239], v[24:27]
	v_mfma_f32_16x16x32_bf16 v[8:11], v[202:205], v[236:239], v[8:11]
	s_waitcnt lgkmcnt(1)
	v_mfma_f32_16x16x32_bf16 v[80:83], v[186:189], v[240:243], v[80:83]
	v_mfma_f32_16x16x32_bf16 v[52:55], v[190:193], v[240:243], v[52:55]
	v_mfma_f32_16x16x32_bf16 v[20:23], v[194:197], v[240:243], v[20:23]
	v_mfma_f32_16x16x32_bf16 v[4:7], v[202:205], v[240:243], v[4:7]
	s_waitcnt lgkmcnt(0)
	v_mfma_f32_16x16x32_bf16 v[72:75], v[186:189], v[244:247], v[72:75]
	v_mfma_f32_16x16x32_bf16 v[48:51], v[190:193], v[244:247], v[48:51]
	v_mfma_f32_16x16x32_bf16 v[16:19], v[194:197], v[244:247], v[16:19]
	v_mfma_f32_16x16x32_bf16 v[0:3], v[202:205], v[244:247], v[0:3]
	v_mov_b32_e32 v186, 0xf149f2ca
	v_mov_b32_e32 v187, 0x3c0881c4
	v_mov_b32_e32 v188, 0xbab64f3b
	v_mov_b32_e32 v189, 0x24800
	v_mov_b32_e32 v190, 1
	v_mov_b32_e32 v191, 0x24804
	v_mov_b32_e32 v192, 0xfcf
	v_mov_b32_e32 v193, 0x7cf
	v_mov_b32_e32 v194, 0xfdf
	v_mov_b32_e32 v195, 0x7df
	v_mov_b32_e32 v196, 0xfef
	v_mov_b32_e32 v197, 0x7ef
	v_mov_b32_e32 v198, 0xfff
	v_mov_b32_e32 v199, 0x7ff
	v_mov_b32_e32 v200, 0x20000
	v_mov_b32_e32 v201, 0xf8f
	v_mov_b32_e32 v202, 0x78f
	v_mov_b32_e32 v203, 0xf9f
	v_mov_b32_e32 v204, 0x79f
	v_mov_b32_e32 v205, 0xfaf
	v_mov_b32_e32 v210, 0x7f800000
	v_not_b32_e32 v211, 63
	v_not_b32_e32 v212, 31
	v_mov_b32_e32 v213, 0x7fc00000
	s_waitcnt vmcnt(4)
	s_barrier
; #define BIG_SYNC(N)                                              \
;   asm volatile("s_waitcnt vmcnt(%0)" ::"n"(N) : "memory");       \
;   __builtin_amdgcn_s_barrier();                                  \
;   asm volatile("" ::: "memory");                                 \
;   __builtin_amdgcn_sched_barrier(0);
; template <int NK, bool BNT = false> ...
;     ...
;   auto kstep = [&](int T, int cur, int nxt, bool do_stage) {
;     const unsigned char* sa = smem + cur * BIG_STAGE;
;     bf16x8 af[4], bfr[4];
; #pragma unroll
;     for (int m = 0; m < 4; ++m) af[m] = *reinterpret_cast<const bf16x8*>(sa + aoff + m * 1024);
; #pragma unroll
;     for (int n = 0; n < 4; ++n) bfr[n] = *reinterpret_cast<const bf16x8*>(sa + boff + n * 1024);
;     __builtin_amdgcn_sched_barrier(0);
;     if (do_stage) stage(T + 3, nxt);
; #pragma unroll
;     for (int m = 0; m < 4; ++m)
; #pragma unroll
;       for (int n = 0; n < 4; ++n) acc[m][n] = __builtin_amdgcn_mfma_f32_16x16x32_bf16(af[m], bfr[n], acc[m][n], 0, 0, 0);
;     if (do_stage) {
; #pragma unroll
;       for (int q = 0; q < NG; ++q) {
;         __builtin_amdgcn_sched_group_barrier(0x008, 3, 0);
;         __builtin_amdgcn_sched_group_barrier(0x010, 1, 0);
;       }
;       __builtin_amdgcn_sched_group_barrier(0x008, 16 - 3 * NG, 0);
;     }
;     __builtin_amdgcn_sched_barrier(0);
; #pragma unroll
;     for (int n = 0; n < 4; ++n) bfr[n] = *reinterpret_cast<const bf16x8*>(sa + boff + (4 + n) * 1024);
; #pragma unroll
;     for (int m = 0; m < 4; ++m)
; #pragma unroll
;       for (int n = 0; n < 4; ++n)
;         acc[m][4 + n] = __builtin_amdgcn_mfma_f32_16x16x32_bf16(af[m], bfr[n], acc[m][4 + n], 0, 0, 0);
;     __builtin_amdgcn_sched_barrier(0);
;   };
;     ...
;   stage(0, 0);
;   stage(1, 1);
;   stage(2, 2);
;   for (int it = 0; it < NK / 4 - 1; ++it) {
;     const int t = it * 4;
;     BIG_SYNC(2 * NG); kstep(t, 0, 3, true);
;     BIG_SYNC(2 * NG); kstep(t + 1, 1, 0, true);
;     BIG_SYNC(2 * NG); kstep(t + 2, 2, 1, true);
;     BIG_SYNC(2 * NG); kstep(t + 3, 3, 2, true);
;   }
;   BIG_SYNC(2 * NG); kstep(NK - 4, 0, 3, true);
;   BIG_SYNC(2 * NG); kstep(NK - 3, 1, 0, false);
;   BIG_SYNC(NG);     kstep(NK - 2, 2, 0, false);
;   BIG_SYNC(0);      kstep(NK - 1, 3, 0, false);
	ds_read_b128 v[128:131], v162
	ds_read_b128 v[138:141], v162 offset:1024
	ds_read_b128 v[146:149], v162 offset:2048
	ds_read_b128 v[154:157], v162 offset:3072
	ds_read_b128 v[158:161], v163
	ds_read_b128 v[216:219], v164
	ds_read_b128 v[162:165], v165
	ds_read_b128 v[220:223], v172
	s_waitcnt lgkmcnt(0)
	v_mfma_f32_16x16x32_bf16 v[124:127], v[128:131], v[158:161], v[124:127]
	v_mfma_f32_16x16x32_bf16 v[116:119], v[128:131], v[162:165], v[116:119]
	v_mfma_f32_16x16x32_bf16 v[112:115], v[128:131], v[220:223], v[112:115]
	v_mfma_f32_16x16x32_bf16 v[104:107], v[138:141], v[216:219], v[104:107]
	v_mfma_f32_16x16x32_bf16 v[100:103], v[138:141], v[162:165], v[100:103]
	v_mfma_f32_16x16x32_bf16 v[96:99], v[138:141], v[220:223], v[96:99]
	v_mfma_f32_16x16x32_bf16 v[68:71], v[146:149], v[162:165], v[68:71]
	v_mfma_f32_16x16x32_bf16 v[64:67], v[146:149], v[220:223], v[64:67]
	v_mfma_f32_16x16x32_bf16 v[44:47], v[154:157], v[158:161], v[44:47]
	v_mfma_f32_16x16x32_bf16 v[40:43], v[154:157], v[216:219], v[40:43]
	v_mfma_f32_16x16x32_bf16 v[36:39], v[154:157], v[162:165], v[36:39]
	v_mfma_f32_16x16x32_bf16 v[32:35], v[154:157], v[220:223], v[32:35]
	v_mfma_f32_16x16x32_bf16 v[120:123], v[128:131], v[216:219], v[120:123]
	v_mfma_f32_16x16x32_bf16 v[224:227], v[138:141], v[158:161], v[108:111]
	v_mfma_f32_16x16x32_bf16 v[228:231], v[146:149], v[158:161], v[88:91]
	v_mfma_f32_16x16x32_bf16 v[232:235], v[146:149], v[216:219], v[76:79]
	s_nop 2
	ds_read_b128 v[76:79], v173
	ds_read_b128 v[88:91], v174
	s_waitcnt lgkmcnt(0)
	v_mfma_f32_16x16x32_bf16 v[158:161], v[128:131], v[76:79], v[92:95]
	s_nop 2
	ds_read_b128 v[92:95], v178
	v_mfma_f32_16x16x32_bf16 v[162:165], v[128:131], v[88:91], v[84:87]
	s_nop 2
	ds_read_b128 v[84:87], v175
	s_waitcnt lgkmcnt(0)
	v_mfma_f32_16x16x32_bf16 v[172:175], v[128:131], v[84:87], v[80:83]
	v_mfma_f32_16x16x32_bf16 v[128:131], v[128:131], v[92:95], v[72:75]
	v_mfma_f32_16x16x32_bf16 v[216:219], v[138:141], v[76:79], v[60:63]
	v_mfma_f32_16x16x32_bf16 v[220:223], v[138:141], v[88:91], v[56:59]
	v_mfma_f32_16x16x32_bf16 v[52:55], v[138:141], v[84:87], v[52:55]
	v_mfma_f32_16x16x32_bf16 v[48:51], v[138:141], v[92:95], v[48:51]
	v_mfma_f32_16x16x32_bf16 v[138:141], v[146:149], v[76:79], v[28:31]
	v_mfma_f32_16x16x32_bf16 v[236:239], v[146:149], v[88:91], v[24:27]
	v_mfma_f32_16x16x32_bf16 v[20:23], v[146:149], v[84:87], v[20:23]
	v_mfma_f32_16x16x32_bf16 v[16:19], v[146:149], v[92:95], v[16:19]
	v_mfma_f32_16x16x32_bf16 v[146:149], v[154:157], v[76:79], v[12:15]
	v_mfma_f32_16x16x32_bf16 v[0:3], v[154:157], v[92:95], v[0:3]
	v_mfma_f32_16x16x32_bf16 v[240:243], v[154:157], v[88:91], v[8:11]
	v_mfma_f32_16x16x32_bf16 v[244:247], v[154:157], v[84:87], v[4:7]
	s_waitcnt vmcnt(0)
	s_barrier
	s_nop 1
	ds_read_b128 v[4:7], v176
	ds_read_b128 v[8:11], v176 offset:1024
	ds_read_b128 v[154:157], v176 offset:2048
	ds_read_b128 v[12:15], v179
	ds_read_b128 v[24:27], v180
	ds_read_b128 v[28:31], v181
	ds_read_b128 v[56:59], v182
	ds_read_b128 v[248:251], v176 offset:3072
	s_waitcnt lgkmcnt(0)
	v_mfma_f32_16x16x32_bf16 v[108:111], v[4:7], v[24:27], v[120:123]
	v_mfma_f32_16x16x32_bf16 v[92:95], v[4:7], v[28:31], v[116:119]
	v_mfma_f32_16x16x32_bf16 v[76:79], v[4:7], v[56:59], v[112:115]
	v_mfma_f32_16x16x32_bf16 v[104:107], v[8:11], v[24:27], v[104:107]
	v_mfma_f32_16x16x32_bf16 v[88:91], v[8:11], v[28:31], v[100:103]
	v_mfma_f32_16x16x32_bf16 v[72:75], v[8:11], v[56:59], v[96:99]
	v_mfma_f32_16x16x32_bf16 v[100:103], v[154:157], v[24:27], v[232:235]
	v_mfma_f32_16x16x32_bf16 v[84:87], v[154:157], v[28:31], v[68:71]
	v_mfma_f32_16x16x32_bf16 v[68:71], v[154:157], v[56:59], v[64:67]
	v_mfma_f32_16x16x32_bf16 v[116:119], v[248:251], v[12:15], v[44:47]
	v_mfma_f32_16x16x32_bf16 v[96:99], v[248:251], v[24:27], v[40:43]
	v_mfma_f32_16x16x32_bf16 v[80:83], v[248:251], v[28:31], v[36:39]
	v_mfma_f32_16x16x32_bf16 v[64:67], v[248:251], v[56:59], v[32:35]
	v_mfma_f32_16x16x32_bf16 v[178:181], v[4:7], v[12:15], v[124:127]
	v_mfma_f32_16x16x32_bf16 v[224:227], v[8:11], v[12:15], v[224:227]
	v_mfma_f32_16x16x32_bf16 v[120:123], v[154:157], v[12:15], v[228:231]
	ds_read_b128 v[32:35], v142
	ds_read_b128 v[112:115], v143
	ds_read_b128 v[124:127], v144
	ds_read_b128 v[142:145], v145
	s_waitcnt lgkmcnt(0)
; template <int MODE, int NSUB>
; __device__ __forceinline__ void epilogue(const Params& p, int layer, f32x4 (&acc)[4][NSUB], int tm, int tn, int g,
;                                          const float* s_rstd, const int tid_in) {
;     ...
;   } else if constexpr (MODE == EPI_RES) {
;     const int fb = tm * 128 + wr * 64 + fq * 4;
;     const int tb = tn * (NSUB * 32) + wc * (NSUB * 16) + fr;
;     const int fw = tm * 128 + wr * 64 + widen_off(fq);
;     u32x4 curw[2], nxtw[2];
; #pragma unroll
;     for (int mp = 0; mp < 2; ++mp) curw[mp] = *reinterpret_cast<const u32x4*>(p.xb + blk(tb, fw + mp * 32, 32));
; #pragma unroll
;     for (int n = 0; n < NSUB; ++n) {
;       if (n + 1 < NSUB) {
; #pragma unroll
;         for (int mp = 0; mp < 2; ++mp) nxtw[mp] = *reinterpret_cast<const u32x4*>(p.xb + blk(tb + (n + 1) * 16, fw + mp * 32, 32));
;       }
;       bf16x4 cur[4];
;       unwiden_pair(curw[0], cur[0], cur[1]);
;       unwiden_pair(curw[1], cur[2], cur[3]);
;       const int t = tb + n * 16;
;       float ss = 0.f;
; #pragma unroll
;       for (int mp = 0; mp < 2; ++mp) {
;         bf16x4 pk[2];
; #pragma unroll
;         for (int h2 = 0; h2 < 2; ++h2) {
;           const int m = mp * 2 + h2;
;           const float x0 = bf2f((bf16_t)cur[m][0]) + acc[m][n][0], x1 = bf2f((bf16_t)cur[m][1]) + acc[m][n][1];
;           const float x2 = bf2f((bf16_t)cur[m][2]) + acc[m][n][2], x3 = bf2f((bf16_t)cur[m][3]) + acc[m][n][3];
;           ss += x0 * x0 + x1 * x1 + x2 * x2 + x3 * x3;
;           pk[h2] = pack4(x0, x1, x2, x3);
;         }
;         const int f = tm * 128 + wr * 64 + mp * 32 + widen_off(fq);
;         *reinterpret_cast<u32x4*>(p.xb + blk(t, f, 32)) = widen_pair(pk[0], pk[1]);
;       }
;       ss = red_fq(ss);
;       if (fq == 0) p.part[(long)t * 16 + tm * 2 + wr] = ss;
;       curw[0] = nxtw[0];
;       curw[1] = nxtw[1];
;     }
; __global__ void __launch_bounds__(NTHREADS) fwd_megakernel(Params p) {
;     ...
;           for (int id = rvid; id < 4 * CHUNK_TT; id += Greal) {
;             int ftb, ttl;
;             tile_decode(id, 4, ftb, ttl);
;             f32x4 acc[4][8];
;             gemm_big<128, true>(acc, W + (long)ftb * 256 * 4096, 128 * 4096, p.hm + (long)ttl * 256 * 4096, 128 * 4096, smem_all, tid_full);
;             const int ft = ftb * 2 + (widf >> 2);
;             epilogue<EPI_RES, 8>(p, l, acc, ft, chunk * CHUNK_TT + ttl, 0, s_rstd_b, tid_e);
	v_mfma_f32_16x16x32_bf16 v[60:63], v[4:7], v[32:35], v[158:161]
	v_mfma_f32_16x16x32_bf16 v[44:47], v[4:7], v[112:115], v[162:165]
	v_mfma_f32_16x16x32_bf16 v[28:31], v[4:7], v[124:127], v[172:175]
	v_mfma_f32_16x16x32_bf16 v[12:15], v[4:7], v[142:145], v[128:131]
	v_mfma_f32_16x16x32_bf16 v[56:59], v[8:11], v[32:35], v[216:219]
	v_mfma_f32_16x16x32_bf16 v[40:43], v[8:11], v[112:115], v[220:223]
	v_mfma_f32_16x16x32_bf16 v[24:27], v[8:11], v[124:127], v[52:55]
	v_mfma_f32_16x16x32_bf16 v[8:11], v[8:11], v[142:145], v[48:51]
	v_mfma_f32_16x16x32_bf16 v[52:55], v[154:157], v[32:35], v[138:141]
	v_mfma_f32_16x16x32_bf16 v[36:39], v[154:157], v[112:115], v[236:239]
	v_mfma_f32_16x16x32_bf16 v[20:23], v[154:157], v[124:127], v[20:23]
	v_mfma_f32_16x16x32_bf16 v[4:7], v[154:157], v[142:145], v[16:19]
	v_mfma_f32_16x16x32_bf16 v[48:51], v[248:251], v[32:35], v[146:149]
	v_mfma_f32_16x16x32_bf16 v[32:35], v[248:251], v[112:115], v[240:243]
	v_mfma_f32_16x16x32_bf16 v[16:19], v[248:251], v[124:127], v[244:247]
	v_mfma_f32_16x16x32_bf16 v[0:3], v[248:251], v[142:145], v[0:3]
	v_lshl_add_u32 v124, s13, 1, v170
	v_mov_b32_e32 v112, v215
	v_lshlrev_b32_e32 v113, 7, v124
	v_ashrrev_i32_e32 v138, 7, v112
	s_mul_i32 s13, s15, 0x140
	v_lshl_add_u32 v114, v138, 6, v113
	v_lshlrev_b32_e32 v113, 1, v112
	s_add_i32 s12, s12, s13
	v_and_b32_e32 v113, 0x80, v113
	v_lshl_or_b32 v127, s12, 8, v113
	v_lshrrev_b32_e32 v113, 2, v112
	v_and_b32_e32 v125, 15, v112
	v_and_b32_e32 v113, 8, v113
	v_ashrrev_i32_e32 v115, 2, v127
	v_readlane_b32 s80, v253, 25
	v_ashrrev_i32_e32 v114, 5, v114
	v_bfe_u32 v126, v112, 4, 2
	v_and_or_b32 v112, v112, 16, v113
	v_lshlrev_b32_e32 v156, 6, v125
	v_mov_b32_e32 v157, v153
	v_readlane_b32 s84, v253, 29
	v_readlane_b32 s85, v253, 30
	v_add_u32_e32 v114, v114, v115
	v_lshlrev_b32_e32 v152, 1, v112
	v_lshl_add_u64 v[144:145], s[84:85], 0, v[156:157]
	v_ashrrev_i32_e32 v115, 31, v114
	v_lshl_add_u64 v[112:113], v[144:145], 0, v[152:153]
	v_lshlrev_b64 v[146:147], 13, v[114:115]
	v_or_b32_e32 v114, 1, v114
	v_lshl_add_u64 v[150:151], v[112:113], 0, v[146:147]
	v_ashrrev_i32_e32 v115, 31, v114
	global_load_dwordx4 v[158:161], v[150:151], off
	v_lshlrev_b64 v[148:149], 13, v[114:115]
	v_lshl_add_u64 v[154:155], v[112:113], 0, v[148:149]
	global_load_dwordx4 v[128:131], v[154:155], off
	v_and_b32_e32 v113, 64, v185
	v_xor_b32_e32 v112, 16, v185
	v_add_u32_e32 v113, 64, v113
	v_cmp_lt_i32_e32 vcc, v112, v113
	v_or_b32_e32 v142, v127, v125
	v_lshlrev_b32_e32 v140, 1, v124
	v_cndmask_b32_e32 v112, v185, v112, vcc
	v_lshlrev_b32_e32 v172, 2, v112
	v_xor_b32_e32 v112, 32, v185
	v_cmp_lt_i32_e32 vcc, v112, v113
	v_ashrrev_i32_e32 v141, 31, v140
	v_ashrrev_i32_e32 v139, 31, v138
	v_cndmask_b32_e32 v112, v185, v112, vcc
	v_lshlrev_b32_e32 v173, 2, v112
	v_cmp_eq_u32_e32 vcc, 0, v126
	global_load_dwordx4 v[124:127], v[150:151], off offset:1024
	global_load_dwordx4 v[112:115], v[154:155], off offset:1024
	v_readlane_b32 s81, v253, 26
	v_readlane_b32 s82, v253, 27
	v_readlane_b32 s83, v253, 28
	v_readlane_b32 s86, v253, 31
	v_readlane_b32 s87, v253, 32
	v_readlane_b32 s88, v253, 33
	v_readlane_b32 s89, v253, 34
	v_readlane_b32 s90, v253, 35
	v_readlane_b32 s91, v253, 36
	v_readlane_b32 s92, v253, 37
	v_readlane_b32 s93, v253, 38
	v_readlane_b32 s94, v253, 39
	v_readlane_b32 s95, v253, 40
	s_waitcnt vmcnt(0)
	v_mov_b32_e32 v143, v160
	s_nop 1
	v_permlane16_swap_b32_e32 v158, v143
	v_mov_b32_e32 v164, v161
	s_nop 1
	v_permlane16_swap_b32_e32 v159, v164
	v_mov_b32_e32 v176, v130
	v_mov_b32_e32 v182, v131
	v_and_b32_e32 v131, 0xffff0000, v158
	v_lshlrev_b32_e32 v130, 16, v158
	v_pk_add_f32 v[130:131], v[178:179], v[130:131]
	v_and_b32_e32 v161, 0xffff0000, v159
	v_lshlrev_b32_e32 v160, 16, v159
	v_pk_add_f32 v[162:163], v[180:181], v[160:161]
	v_pk_mul_f32 v[160:161], v[130:131], v[130:131]
	v_cvt_pk_bf16_f32 v178, v130, v131
	v_and_b32_e32 v131, 0xffff0000, v143
	v_lshlrev_b32_e32 v130, 16, v143
	v_pk_mul_f32 v[158:159], v[162:163], v[162:163]
	v_cvt_pk_bf16_f32 v179, v162, v163
	v_pk_add_f32 v[130:131], v[224:225], v[130:131]
	v_and_b32_e32 v163, 0xffff0000, v164
	v_lshlrev_b32_e32 v162, 16, v164
	v_pk_add_f32 v[174:175], v[226:227], v[162:163]
	v_pk_mul_f32 v[164:165], v[130:131], v[130:131]
	v_cvt_pk_bf16_f32 v180, v130, v131
	v_lshl_add_u64 v[130:131], s[84:85], 0, v[146:147]
	v_pk_mul_f32 v[162:163], v[174:175], v[174:175]
	v_cvt_pk_bf16_f32 v181, v174, v175
	v_lshl_add_u64 v[174:175], v[130:131], 0, v[156:157]
	v_permlane16_swap_b32_e32 v128, v176
	v_permlane16_swap_b32_e32 v178, v180
	v_permlane16_swap_b32_e32 v179, v181
	v_lshl_add_u64 v[174:175], v[174:175], 0, v[152:153]
	v_permlane16_swap_b32_e32 v129, v182
	global_store_dwordx4 v[174:175], v[178:181], off
	v_and_b32_e32 v175, 0xffff0000, v128
	v_lshlrev_b32_e32 v174, 16, v128
	v_pk_add_f32 v[120:121], v[120:121], v[174:175]
	v_and_b32_e32 v175, 0xffff0000, v129
	v_lshlrev_b32_e32 v174, 16, v129
	v_pk_add_f32 v[122:123], v[122:123], v[174:175]
	v_pk_mul_f32 v[128:129], v[120:121], v[120:121]
	v_pk_mul_f32 v[174:175], v[122:123], v[122:123]
	v_cvt_pk_bf16_f32 v120, v120, v121
	v_cvt_pk_bf16_f32 v121, v122, v123
	v_and_b32_e32 v123, 0xffff0000, v176
	v_lshlrev_b32_e32 v122, 16, v176
	v_pk_add_f32 v[116:117], v[116:117], v[122:123]
	v_and_b32_e32 v123, 0xffff0000, v182
	v_lshlrev_b32_e32 v122, 16, v182
	v_add_f32_e32 v143, v164, v165
	v_add_f32_e32 v160, v160, v161
	v_pk_add_f32 v[118:119], v[118:119], v[122:123]
	v_pk_mul_f32 v[122:123], v[116:117], v[116:117]
	v_add_f32_e32 v143, v162, v143
	v_add_f32_e32 v158, v158, v160
	v_add_f32_e32 v128, v128, v129
	v_pk_mul_f32 v[178:179], v[118:119], v[118:119]
	v_add_f32_e32 v143, v163, v143
	v_add_f32_e32 v158, v159, v158
	v_add_f32_e32 v128, v174, v128
	v_add_f32_e32 v122, v122, v123
	v_add_f32_e32 v143, v158, v143
	v_add_f32_e32 v128, v175, v128
	v_add_f32_e32 v122, v178, v122
	v_add_f32_e32 v128, v143, v128
	v_add_f32_e32 v122, v179, v122
	v_add_f32_e32 v143, v122, v128
	v_lshl_add_u64 v[128:129], s[84:85], 0, v[148:149]
	v_cvt_pk_bf16_f32 v122, v116, v117
	v_cvt_pk_bf16_f32 v123, v118, v119
	v_lshl_add_u64 v[116:117], v[128:129], 0, v[156:157]
	v_permlane16_swap_b32_e32 v120, v122
	v_permlane16_swap_b32_e32 v121, v123
	v_lshl_add_u64 v[116:117], v[116:117], 0, v[152:153]
	global_store_dwordx4 v[116:117], v[120:123], off
	ds_bpermute_b32 v116, v172, v143
	s_waitcnt lgkmcnt(0)
	v_add_f32_e32 v116, v143, v116
	ds_bpermute_b32 v117, v173, v116
	s_and_saveexec_b64 s[12:13], vcc
	s_cbranch_execz .LBB0_267
; template <int MODE, int NSUB>
; __device__ __forceinline__ void epilogue(const Params& p, int layer, f32x4 (&acc)[4][NSUB], int tm, int tn, int g,
;                                          const float* s_rstd, const int tid_in) {
;     ...
;       ss = red_fq(ss);
;       if (fq == 0) p.part[(long)t * 16 + tm * 2 + wr] = ss;
	v_ashrrev_i32_e32 v143, 31, v142
	v_readlane_b32 s64, v253, 25
	v_lshlrev_b64 v[118:119], 6, v[142:143]
	v_readlane_b32 s70, v253, 31
	v_readlane_b32 s71, v253, 32
	s_waitcnt lgkmcnt(0)
	v_add_f32_e32 v116, v116, v117
	v_readlane_b32 s65, v253, 26
	v_lshl_add_u64 v[118:119], s[70:71], 0, v[118:119]
	v_lshl_add_u64 v[118:119], v[140:141], 2, v[118:119]
	v_lshl_add_u64 v[118:119], v[138:139], 2, v[118:119]
	v_readlane_b32 s66, v253, 27
	v_readlane_b32 s67, v253, 28
	v_readlane_b32 s68, v253, 29
	v_readlane_b32 s69, v253, 30
	v_readlane_b32 s72, v253, 33
	v_readlane_b32 s73, v253, 34
	v_readlane_b32 s74, v253, 35
	v_readlane_b32 s75, v253, 36
	v_readlane_b32 s76, v253, 37
	v_readlane_b32 s77, v253, 38
	v_readlane_b32 s78, v253, 39
	v_readlane_b32 s79, v253, 40
	global_store_dword v[118:119], v116, off

; template <int NK, bool BNT = false> ...
;     ...
;   auto kstep = [&](int T, int cur, int nxt, bool do_stage) {
;     const unsigned char* sa = smem + cur * BIG_STAGE;
;     bf16x8 af[4], bfr[4];
; #pragma unroll
;     for (int m = 0; m < 4; ++m) af[m] = *reinterpret_cast<const bf16x8*>(sa + aoff + m * 1024);
; #pragma unroll
;     for (int n = 0; n < 4; ++n) bfr[n] = *reinterpret_cast<const bf16x8*>(sa + boff + n * 1024);
;     __builtin_amdgcn_sched_barrier(0);
;     if (do_stage) stage(T + 3, nxt);
; #pragma unroll
;     for (int m = 0; m < 4; ++m)
; #pragma unroll
;       for (int n = 0; n < 4; ++n) acc[m][n] = __builtin_amdgcn_mfma_f32_16x16x32_bf16(af[m], bfr[n], acc[m][n], 0, 0, 0);
;     if (do_stage) {
; #pragma unroll
;       for (int q = 0; q < NG; ++q) {
;         __builtin_amdgcn_sched_group_barrier(0x008, 3, 0);
;         __builtin_amdgcn_sched_group_barrier(0x010, 1, 0);
;       }
;       __builtin_amdgcn_sched_group_barrier(0x008, 16 - 3 * NG, 0);
;     }
;     __builtin_amdgcn_sched_barrier(0);
; #pragma unroll
;     for (int n = 0; n < 4; ++n) bfr[n] = *reinterpret_cast<const bf16x8*>(sa + boff + (4 + n) * 1024);
; #pragma unroll
;     for (int m = 0; m < 4; ++m)
; #pragma unroll
;       for (int n = 0; n < 4; ++n)
;         acc[m][4 + n] = __builtin_amdgcn_mfma_f32_16x16x32_bf16(af[m], bfr[n], acc[m][4 + n], 0, 0, 0);
;     __builtin_amdgcn_sched_barrier(0);
;   };
;     ...
;   stage(0, 0);
;   stage(1, 1);
;   stage(2, 2);
;   for (int it = 0; it < NK / 4 - 1; ++it) {
;     const int t = it * 4;
;     BIG_SYNC(2 * NG); kstep(t, 0, 3, true);
;     BIG_SYNC(2 * NG); kstep(t + 1, 1, 0, true);
;     BIG_SYNC(2 * NG); kstep(t + 2, 2, 1, true);
;     BIG_SYNC(2 * NG); kstep(t + 3, 3, 2, true);
;   }
; __global__ void __launch_bounds__(NTHREADS) fwd_megakernel(Params p) {
;     ...
;           for (int id = rvid; id < 16 * CHUNK_TT; id += Greal) {
;             int ftb, ttl;
;             tile_decode_fb(id, 16, 4, ftb, ttl);
;             compute_rstd(p.part, 16, 1.0f / 1024.f, (chunk * CHUNK_TT + ttl) * 256, 256, s_rstd_b, tid_full);
;             f32x4 acc[4][8];
;             gemm_big<32>(acc, W + (long)ftb * 256 * 1024, 128 * 1024, p.xb + (long)(chunk * CHUNK_TT + ttl) * 256 * 1024, 128 * 1024, smem_all, tid_full);
.Lmy_up_rsdone:
	s_or_b64 exec, exec, s[100:101]
	s_waitcnt vmcnt(8)
	s_barrier
	v_add_u32_e32 v167, 0x10000, v147
	v_or_b32_e32 v168, 0x10000, v149
	v_add_u32_e32 v176, 0x18000, v147
	v_or_b32_e32 v179, 0x18000, v149
	v_add_u32_e32 v210, 0x10000, v147
	v_or_b32_e32 v211, 0x10000, v149
	v_add_u32_e32 v212, 0x18000, v147
	v_or_b32_e32 v213, 0x18000, v149
	ds_read_b128 v[216:219], v147
	ds_read_b128 v[220:223], v147 offset:1024
	ds_read_b128 v[224:227], v147 offset:2048
	ds_read_b128 v[228:231], v147 offset:3072
	ds_read_b128 v[232:235], v148 offset:16384
	ds_read_b128 v[236:239], v148 offset:17408
	ds_read_b128 v[240:243], v148 offset:18432
	ds_read_b128 v[244:247], v148 offset:19456
.LBB0_290:
	s_waitcnt lgkmcnt(3)
	v_mfma_f32_16x16x32_bf16 v[124:127], v[216:219], v[232:235], v[124:127]
	v_mfma_f32_16x16x32_bf16 v[108:111], v[220:223], v[232:235], v[108:111]
	v_mfma_f32_16x16x32_bf16 v[88:91], v[224:227], v[232:235], v[88:91]
	s_waitcnt vmcnt(4)
	s_barrier
	v_add_u32_e32 v163, 0x18000, v146
	v_lshl_add_u64 v[144:145], v[138:139], 0, s[12:13]
	v_mfma_f32_16x16x32_bf16 v[44:47], v[228:231], v[232:235], v[44:47]
	v_readfirstlane_b32 s11, v163
	v_lshl_add_u64 v[164:165], v[144:145], 0, s[60:61]
	s_waitcnt lgkmcnt(2)
	v_mfma_f32_16x16x32_bf16 v[120:123], v[216:219], v[236:239], v[120:123]
	ds_read_b128 v[232:235], v148 offset:20480
	v_mfma_f32_16x16x32_bf16 v[104:107], v[220:223], v[236:239], v[104:107]
	s_mov_b32 m0, s11
	v_lshl_add_u64 v[142:143], v[140:141], 0, s[12:13]
	v_mfma_f32_16x16x32_bf16 v[76:79], v[224:227], v[236:239], v[76:79]
	v_lshl_add_u64 v[168:169], v[144:145], 0, s[80:81]
	v_mfma_f32_16x16x32_bf16 v[40:43], v[228:231], v[236:239], v[40:43]
	v_lshl_add_u64 v[166:167], v[142:143], 0, s[60:61]
	s_waitcnt lgkmcnt(2)
	v_mfma_f32_16x16x32_bf16 v[116:119], v[216:219], v[240:243], v[116:119]
	ds_read_b128 v[236:239], v148 offset:21504
	v_mfma_f32_16x16x32_bf16 v[100:103], v[220:223], v[240:243], v[100:103]
	global_load_lds_dwordx4 v[164:165], off
	v_mfma_f32_16x16x32_bf16 v[68:71], v[224:227], v[240:243], v[68:71]
	v_add_u32_e32 v164, 0x1a000, v146
	v_mfma_f32_16x16x32_bf16 v[36:39], v[228:231], v[240:243], v[36:39]
	v_add_u32_e32 v165, 0x1c000, v146
	s_waitcnt lgkmcnt(2)
	v_mfma_f32_16x16x32_bf16 v[112:115], v[216:219], v[244:247], v[112:115]
	ds_read_b128 v[240:243], v148 offset:22528
	v_mfma_f32_16x16x32_bf16 v[96:99], v[220:223], v[244:247], v[96:99]
	v_readfirstlane_b32 s11, v164
	v_mfma_f32_16x16x32_bf16 v[64:67], v[224:227], v[244:247], v[64:67]
	s_mov_b32 m0, s11
	v_mfma_f32_16x16x32_bf16 v[32:35], v[228:231], v[244:247], v[32:35]
	v_readfirstlane_b32 s11, v165
	s_waitcnt lgkmcnt(2)
	v_mfma_f32_16x16x32_bf16 v[92:95], v[216:219], v[232:235], v[92:95]
	ds_read_b128 v[244:247], v148 offset:23552
	v_mfma_f32_16x16x32_bf16 v[60:63], v[220:223], v[232:235], v[60:63]
	ds_read_b128 v[186:189], v147 offset:32768
	v_mfma_f32_16x16x32_bf16 v[28:31], v[224:227], v[232:235], v[28:31]
	ds_read_b128 v[190:193], v147 offset:33792
	v_mfma_f32_16x16x32_bf16 v[12:15], v[228:231], v[232:235], v[12:15]
	ds_read_b128 v[194:197], v147 offset:34816
	s_waitcnt lgkmcnt(5)
	v_mfma_f32_16x16x32_bf16 v[84:87], v[216:219], v[236:239], v[84:87]
	ds_read_b128 v[202:205], v147 offset:35840
	ds_read_b128 v[232:235], v148 offset:49152
	v_mfma_f32_16x16x32_bf16 v[56:59], v[220:223], v[236:239], v[56:59]
	global_load_lds_dwordx4 v[168:169], off
	v_mfma_f32_16x16x32_bf16 v[24:27], v[224:227], v[236:239], v[24:27]
	s_mov_b32 m0, s11
	v_mfma_f32_16x16x32_bf16 v[8:11], v[228:231], v[236:239], v[8:11]
	v_lshl_add_u64 v[168:169], v[142:143], 0, s[80:81]
	s_waitcnt lgkmcnt(6)
	v_mfma_f32_16x16x32_bf16 v[80:83], v[216:219], v[240:243], v[80:83]
	ds_read_b128 v[236:239], v148 offset:50176
	v_mfma_f32_16x16x32_bf16 v[52:55], v[220:223], v[240:243], v[52:55]
	global_load_lds_dwordx4 v[166:167], off
	v_mfma_f32_16x16x32_bf16 v[20:23], v[224:227], v[240:243], v[20:23]
	v_add_u32_e32 v166, 0x1e000, v146
	v_mfma_f32_16x16x32_bf16 v[4:7], v[228:231], v[240:243], v[4:7]
	v_readfirstlane_b32 s11, v166
	s_waitcnt lgkmcnt(6)
	v_mfma_f32_16x16x32_bf16 v[72:75], v[216:219], v[244:247], v[72:75]
	ds_read_b128 v[240:243], v148 offset:51200
	v_mfma_f32_16x16x32_bf16 v[48:51], v[220:223], v[244:247], v[48:51]
	s_mov_b32 m0, s11
	v_mfma_f32_16x16x32_bf16 v[16:19], v[224:227], v[244:247], v[16:19]
	global_load_lds_dwordx4 v[168:169], off
	v_mfma_f32_16x16x32_bf16 v[0:3], v[228:231], v[244:247], v[0:3]
	ds_read_b128 v[244:247], v148 offset:52224
	s_waitcnt lgkmcnt(3)
	v_mfma_f32_16x16x32_bf16 v[124:127], v[186:189], v[232:235], v[124:127]
	v_mfma_f32_16x16x32_bf16 v[108:111], v[190:193], v[232:235], v[108:111]
	v_mfma_f32_16x16x32_bf16 v[88:91], v[194:197], v[232:235], v[88:91]
	s_waitcnt vmcnt(4)
	s_barrier
; #define BIG_SYNC(N)                                              \
;   asm volatile("s_waitcnt vmcnt(%0)" ::"n"(N) : "memory");       \
;   __builtin_amdgcn_s_barrier();                                  \
;   asm volatile("" ::: "memory");                                 \
;   __builtin_amdgcn_sched_barrier(0);
; template <int NK, bool BNT = false> ...
;     ...
;   auto kstep = [&](int T, int cur, int nxt, bool do_stage) {
;     const unsigned char* sa = smem + cur * BIG_STAGE;
;     bf16x8 af[4], bfr[4];
; #pragma unroll
;     for (int m = 0; m < 4; ++m) af[m] = *reinterpret_cast<const bf16x8*>(sa + aoff + m * 1024);
; #pragma unroll
;     for (int n = 0; n < 4; ++n) bfr[n] = *reinterpret_cast<const bf16x8*>(sa + boff + n * 1024);
;     __builtin_amdgcn_sched_barrier(0);
;     if (do_stage) stage(T + 3, nxt);
; #pragma unroll
;     for (int m = 0; m < 4; ++m)
; #pragma unroll
;       for (int n = 0; n < 4; ++n) acc[m][n] = __builtin_amdgcn_mfma_f32_16x16x32_bf16(af[m], bfr[n], acc[m][n], 0, 0, 0);
;     if (do_stage) {
; #pragma unroll
;       for (int q = 0; q < NG; ++q) {
;         __builtin_amdgcn_sched_group_barrier(0x008, 3, 0);
;         __builtin_amdgcn_sched_group_barrier(0x010, 1, 0);
;       }
;       __builtin_amdgcn_sched_group_barrier(0x008, 16 - 3 * NG, 0);
;     }
;     __builtin_amdgcn_sched_barrier(0);
; #pragma unroll
;     for (int n = 0; n < 4; ++n) bfr[n] = *reinterpret_cast<const bf16x8*>(sa + boff + (4 + n) * 1024);
; #pragma unroll
;     for (int m = 0; m < 4; ++m)
; #pragma unroll
;       for (int n = 0; n < 4; ++n)
;         acc[m][4 + n] = __builtin_amdgcn_mfma_f32_16x16x32_bf16(af[m], bfr[n], acc[m][4 + n], 0, 0, 0);
;     __builtin_amdgcn_sched_barrier(0);
;   };
;     ...
;   stage(0, 0);
;   stage(1, 1);
;   stage(2, 2);
;   for (int it = 0; it < NK / 4 - 1; ++it) {
;     const int t = it * 4;
;     BIG_SYNC(2 * NG); kstep(t, 0, 3, true);
;     BIG_SYNC(2 * NG); kstep(t + 1, 1, 0, true);
;     BIG_SYNC(2 * NG); kstep(t + 2, 2, 1, true);
;     BIG_SYNC(2 * NG); kstep(t + 3, 3, 2, true);
;   }
	v_readfirstlane_b32 s11, v146
	v_mfma_f32_16x16x32_bf16 v[44:47], v[202:205], v[232:235], v[44:47]
	v_lshl_add_u64 v[168:169], v[144:145], 0, s[62:63]
	s_waitcnt lgkmcnt(2)
	v_mfma_f32_16x16x32_bf16 v[120:123], v[186:189], v[236:239], v[120:123]
	ds_read_b128 v[232:235], v148 offset:53248
	v_mfma_f32_16x16x32_bf16 v[104:107], v[190:193], v[236:239], v[104:107]
	s_mov_b32 m0, s11
	v_mfma_f32_16x16x32_bf16 v[76:79], v[194:197], v[236:239], v[76:79]
	v_readfirstlane_b32 s11, v151
	v_mfma_f32_16x16x32_bf16 v[40:43], v[202:205], v[236:239], v[40:43]
	v_lshl_add_u64 v[182:183], v[142:143], 0, s[62:63]
	s_waitcnt lgkmcnt(2)
	v_mfma_f32_16x16x32_bf16 v[116:119], v[186:189], v[240:243], v[116:119]
	ds_read_b128 v[236:239], v148 offset:54272
	v_mfma_f32_16x16x32_bf16 v[100:103], v[190:193], v[240:243], v[100:103]
	global_load_lds_dwordx4 v[168:169], off
	v_mfma_f32_16x16x32_bf16 v[68:71], v[194:197], v[240:243], v[68:71]
	v_lshl_add_u64 v[168:169], v[144:145], 0, s[0:1]
	v_mfma_f32_16x16x32_bf16 v[36:39], v[202:205], v[240:243], v[36:39]
	s_mov_b32 m0, s11
	s_waitcnt lgkmcnt(2)
	v_mfma_f32_16x16x32_bf16 v[112:115], v[186:189], v[244:247], v[112:115]
	ds_read_b128 v[240:243], v148 offset:55296
	v_mfma_f32_16x16x32_bf16 v[96:99], v[190:193], v[244:247], v[96:99]
	v_readfirstlane_b32 s11, v152
	v_mfma_f32_16x16x32_bf16 v[64:67], v[194:197], v[244:247], v[64:67]
	global_load_lds_dwordx4 v[168:169], off
	v_mfma_f32_16x16x32_bf16 v[32:35], v[202:205], v[244:247], v[32:35]
	s_mov_b32 m0, s11
	s_waitcnt lgkmcnt(2)
	v_mfma_f32_16x16x32_bf16 v[92:95], v[186:189], v[232:235], v[92:95]
	ds_read_b128 v[244:247], v148 offset:56320
	v_mfma_f32_16x16x32_bf16 v[60:63], v[190:193], v[232:235], v[60:63]
	ds_read_b128 v[216:219], v210
	v_mfma_f32_16x16x32_bf16 v[28:31], v[194:197], v[232:235], v[28:31]
	ds_read_b128 v[220:223], v210 offset:1024
	v_mfma_f32_16x16x32_bf16 v[12:15], v[202:205], v[232:235], v[12:15]
	ds_read_b128 v[224:227], v210 offset:2048
	s_waitcnt lgkmcnt(5)
	v_mfma_f32_16x16x32_bf16 v[84:87], v[186:189], v[236:239], v[84:87]
	ds_read_b128 v[228:231], v210 offset:3072
	ds_read_b128 v[232:235], v211
	v_mfma_f32_16x16x32_bf16 v[56:59], v[190:193], v[236:239], v[56:59]
	v_readfirstlane_b32 s11, v154
	v_mfma_f32_16x16x32_bf16 v[24:27], v[194:197], v[236:239], v[24:27]
	v_lshl_add_u64 v[168:169], v[142:143], 0, s[0:1]
	v_mfma_f32_16x16x32_bf16 v[8:11], v[202:205], v[236:239], v[8:11]
	global_load_lds_dwordx4 v[182:183], off
	s_waitcnt lgkmcnt(6)
	v_mfma_f32_16x16x32_bf16 v[80:83], v[186:189], v[240:243], v[80:83]
	ds_read_b128 v[236:239], v211 offset:1024
	v_mfma_f32_16x16x32_bf16 v[52:55], v[190:193], v[240:243], v[52:55]
	s_mov_b32 m0, s11
	v_mfma_f32_16x16x32_bf16 v[20:23], v[194:197], v[240:243], v[20:23]
	global_load_lds_dwordx4 v[168:169], off
	v_mfma_f32_16x16x32_bf16 v[4:7], v[202:205], v[240:243], v[4:7]
	s_waitcnt lgkmcnt(6)
	v_mfma_f32_16x16x32_bf16 v[72:75], v[186:189], v[244:247], v[72:75]
	ds_read_b128 v[240:243], v211 offset:2048
	v_mfma_f32_16x16x32_bf16 v[48:51], v[190:193], v[244:247], v[48:51]
	v_mfma_f32_16x16x32_bf16 v[16:19], v[194:197], v[244:247], v[16:19]
	v_mfma_f32_16x16x32_bf16 v[0:3], v[202:205], v[244:247], v[0:3]
	ds_read_b128 v[244:247], v211 offset:3072
	s_waitcnt lgkmcnt(3)
	v_mfma_f32_16x16x32_bf16 v[124:127], v[216:219], v[232:235], v[124:127]
	v_mfma_f32_16x16x32_bf16 v[108:111], v[220:223], v[232:235], v[108:111]
	v_mfma_f32_16x16x32_bf16 v[88:91], v[224:227], v[232:235], v[88:91]
	s_waitcnt vmcnt(4)
	s_barrier
	v_add_u32_e32 v167, 0x10000, v147
	v_or_b32_e32 v168, 0x10000, v149
	v_mfma_f32_16x16x32_bf16 v[44:47], v[228:231], v[232:235], v[44:47]
	v_add_u32_e32 v169, 0x10400, v149
	v_add_u32_e32 v170, 0x10800, v149
	s_waitcnt lgkmcnt(2)
	v_mfma_f32_16x16x32_bf16 v[120:123], v[216:219], v[236:239], v[120:123]
	ds_read_b128 v[232:235], v211 offset:4096
	v_mfma_f32_16x16x32_bf16 v[104:107], v[220:223], v[236:239], v[104:107]
	v_add_u32_e32 v172, 0x10c00, v149
	v_mfma_f32_16x16x32_bf16 v[76:79], v[224:227], v[236:239], v[76:79]
	v_readfirstlane_b32 s11, v155
	v_mfma_f32_16x16x32_bf16 v[40:43], v[228:231], v[236:239], v[40:43]
	v_lshl_add_u64 v[174:175], v[144:145], 0, s[2:3]
	s_waitcnt lgkmcnt(2)
	v_mfma_f32_16x16x32_bf16 v[116:119], v[216:219], v[240:243], v[116:119]
	ds_read_b128 v[236:239], v211 offset:5120
	v_mfma_f32_16x16x32_bf16 v[100:103], v[220:223], v[240:243], v[100:103]
	s_mov_b32 m0, s11
	v_mfma_f32_16x16x32_bf16 v[68:71], v[224:227], v[240:243], v[68:71]
	v_readfirstlane_b32 s11, v156
	v_mfma_f32_16x16x32_bf16 v[36:39], v[228:231], v[240:243], v[36:39]
	v_lshl_add_u64 v[178:179], v[142:143], 0, s[2:3]
	s_waitcnt lgkmcnt(2)
	v_mfma_f32_16x16x32_bf16 v[112:115], v[216:219], v[244:247], v[112:115]
	ds_read_b128 v[240:243], v211 offset:6144
	v_mfma_f32_16x16x32_bf16 v[96:99], v[220:223], v[244:247], v[96:99]
	global_load_lds_dwordx4 v[174:175], off
	v_mfma_f32_16x16x32_bf16 v[64:67], v[224:227], v[244:247], v[64:67]
	v_lshl_add_u64 v[174:175], v[144:145], 0, s[52:53]
	v_mfma_f32_16x16x32_bf16 v[32:35], v[228:231], v[244:247], v[32:35]
	s_mov_b32 m0, s11
	s_waitcnt lgkmcnt(2)
	v_mfma_f32_16x16x32_bf16 v[92:95], v[216:219], v[232:235], v[92:95]
	ds_read_b128 v[244:247], v211 offset:7168
	v_mfma_f32_16x16x32_bf16 v[60:63], v[220:223], v[232:235], v[60:63]
	ds_read_b128 v[186:189], v210 offset:32768
	v_mfma_f32_16x16x32_bf16 v[28:31], v[224:227], v[232:235], v[28:31]
	ds_read_b128 v[190:193], v210 offset:33792
	v_mfma_f32_16x16x32_bf16 v[12:15], v[228:231], v[232:235], v[12:15]
	ds_read_b128 v[194:197], v210 offset:34816
	s_waitcnt lgkmcnt(5)
; #define BIG_SYNC(N)                                              \
;   asm volatile("s_waitcnt vmcnt(%0)" ::"n"(N) : "memory");       \
;   __builtin_amdgcn_s_barrier();                                  \
;   asm volatile("" ::: "memory");                                 \
;   __builtin_amdgcn_sched_barrier(0);
; template <int NK, bool BNT = false> ...
;     ...
;   auto kstep = [&](int T, int cur, int nxt, bool do_stage) {
;     const unsigned char* sa = smem + cur * BIG_STAGE;
;     bf16x8 af[4], bfr[4];
; #pragma unroll
;     for (int m = 0; m < 4; ++m) af[m] = *reinterpret_cast<const bf16x8*>(sa + aoff + m * 1024);
; #pragma unroll
;     for (int n = 0; n < 4; ++n) bfr[n] = *reinterpret_cast<const bf16x8*>(sa + boff + n * 1024);
;     __builtin_amdgcn_sched_barrier(0);
;     if (do_stage) stage(T + 3, nxt);
; #pragma unroll
;     for (int m = 0; m < 4; ++m)
; #pragma unroll
;       for (int n = 0; n < 4; ++n) acc[m][n] = __builtin_amdgcn_mfma_f32_16x16x32_bf16(af[m], bfr[n], acc[m][n], 0, 0, 0);
;     if (do_stage) {
; #pragma unroll
;       for (int q = 0; q < NG; ++q) {
;         __builtin_amdgcn_sched_group_barrier(0x008, 3, 0);
;         __builtin_amdgcn_sched_group_barrier(0x010, 1, 0);
;       }
;       __builtin_amdgcn_sched_group_barrier(0x008, 16 - 3 * NG, 0);
;     }
;     __builtin_amdgcn_sched_barrier(0);
; #pragma unroll
;     for (int n = 0; n < 4; ++n) bfr[n] = *reinterpret_cast<const bf16x8*>(sa + boff + (4 + n) * 1024);
; #pragma unroll
;     for (int m = 0; m < 4; ++m)
; #pragma unroll
;       for (int n = 0; n < 4; ++n)
;         acc[m][4 + n] = __builtin_amdgcn_mfma_f32_16x16x32_bf16(af[m], bfr[n], acc[m][4 + n], 0, 0, 0);
;     __builtin_amdgcn_sched_barrier(0);
;   };
;     ...
;   stage(0, 0);
;   stage(1, 1);
;   stage(2, 2);
;   for (int it = 0; it < NK / 4 - 1; ++it) {
;     const int t = it * 4;
;     BIG_SYNC(2 * NG); kstep(t, 0, 3, true);
;     BIG_SYNC(2 * NG); kstep(t + 1, 1, 0, true);
;     BIG_SYNC(2 * NG); kstep(t + 2, 2, 1, true);
;     BIG_SYNC(2 * NG); kstep(t + 3, 3, 2, true);
;   }
	v_mfma_f32_16x16x32_bf16 v[84:87], v[216:219], v[236:239], v[84:87]
	ds_read_b128 v[202:205], v210 offset:35840
	ds_read_b128 v[232:235], v211 offset:32768
	v_mfma_f32_16x16x32_bf16 v[56:59], v[220:223], v[236:239], v[56:59]
	v_readfirstlane_b32 s11, v157
	v_mfma_f32_16x16x32_bf16 v[24:27], v[224:227], v[236:239], v[24:27]
	global_load_lds_dwordx4 v[174:175], off
	v_mfma_f32_16x16x32_bf16 v[8:11], v[228:231], v[236:239], v[8:11]
	s_mov_b32 m0, s11
	s_waitcnt lgkmcnt(6)
	v_mfma_f32_16x16x32_bf16 v[80:83], v[216:219], v[240:243], v[80:83]
	ds_read_b128 v[236:239], v211 offset:33792
	v_mfma_f32_16x16x32_bf16 v[52:55], v[220:223], v[240:243], v[52:55]
	v_readfirstlane_b32 s11, v158
	v_mfma_f32_16x16x32_bf16 v[20:23], v[224:227], v[240:243], v[20:23]
	v_lshl_add_u64 v[174:175], v[142:143], 0, s[52:53]
	v_mfma_f32_16x16x32_bf16 v[4:7], v[228:231], v[240:243], v[4:7]
	global_load_lds_dwordx4 v[178:179], off
	s_waitcnt lgkmcnt(6)
	v_mfma_f32_16x16x32_bf16 v[72:75], v[216:219], v[244:247], v[72:75]
	ds_read_b128 v[240:243], v211 offset:34816
	v_mfma_f32_16x16x32_bf16 v[48:51], v[220:223], v[244:247], v[48:51]
	s_mov_b32 m0, s11
	v_mfma_f32_16x16x32_bf16 v[16:19], v[224:227], v[244:247], v[16:19]
	global_load_lds_dwordx4 v[174:175], off
	v_mfma_f32_16x16x32_bf16 v[0:3], v[228:231], v[244:247], v[0:3]
	ds_read_b128 v[244:247], v211 offset:35840
	v_add_u32_e32 v173, 0x11000, v149
	v_add_u32_e32 v174, 0x11400, v149
	v_add_u32_e32 v175, 0x11800, v149
	v_add_u32_e32 v178, 0x11c00, v149
	s_waitcnt lgkmcnt(3)
	v_mfma_f32_16x16x32_bf16 v[124:127], v[186:189], v[232:235], v[124:127]
	v_mfma_f32_16x16x32_bf16 v[108:111], v[190:193], v[232:235], v[108:111]
	v_mfma_f32_16x16x32_bf16 v[88:91], v[194:197], v[232:235], v[88:91]
	s_waitcnt vmcnt(4)
	s_barrier
	v_add_u32_e32 v176, 0x18000, v147
	v_or_b32_e32 v179, 0x18000, v149
	v_mfma_f32_16x16x32_bf16 v[44:47], v[202:205], v[232:235], v[44:47]
	v_add_u32_e32 v180, 0x18400, v149
	v_add_u32_e32 v181, 0x18800, v149
	s_waitcnt lgkmcnt(2)
	v_mfma_f32_16x16x32_bf16 v[120:123], v[186:189], v[236:239], v[120:123]
	ds_read_b128 v[232:235], v211 offset:36864
	v_mfma_f32_16x16x32_bf16 v[104:107], v[190:193], v[236:239], v[104:107]
	v_add_u32_e32 v182, 0x18c00, v149
	v_mfma_f32_16x16x32_bf16 v[76:79], v[194:197], v[236:239], v[76:79]
	v_readfirstlane_b32 s11, v159
	v_mfma_f32_16x16x32_bf16 v[40:43], v[202:205], v[236:239], v[40:43]
	v_lshl_add_u64 v[248:249], v[144:145], 0, s[54:55]
	s_waitcnt lgkmcnt(2)
	v_mfma_f32_16x16x32_bf16 v[116:119], v[186:189], v[240:243], v[116:119]
	ds_read_b128 v[236:239], v211 offset:37888
	v_mfma_f32_16x16x32_bf16 v[100:103], v[190:193], v[240:243], v[100:103]
	s_mov_b32 m0, s11
	v_mfma_f32_16x16x32_bf16 v[68:71], v[194:197], v[240:243], v[68:71]
	v_readfirstlane_b32 s11, v160
	v_mfma_f32_16x16x32_bf16 v[36:39], v[202:205], v[240:243], v[36:39]
	v_lshl_add_u64 v[144:145], v[144:145], 0, s[56:57]
	s_waitcnt lgkmcnt(2)
	v_mfma_f32_16x16x32_bf16 v[112:115], v[186:189], v[244:247], v[112:115]
	ds_read_b128 v[240:243], v211 offset:38912
	v_mfma_f32_16x16x32_bf16 v[96:99], v[190:193], v[244:247], v[96:99]
	v_lshl_add_u64 v[250:251], v[142:143], 0, s[54:55]
	v_mfma_f32_16x16x32_bf16 v[64:67], v[194:197], v[244:247], v[64:67]
	v_lshl_add_u64 v[142:143], v[142:143], 0, s[56:57]
	v_mfma_f32_16x16x32_bf16 v[32:35], v[202:205], v[244:247], v[32:35]
	global_load_lds_dwordx4 v[248:249], off
	s_waitcnt lgkmcnt(2)
	v_mfma_f32_16x16x32_bf16 v[92:95], v[186:189], v[232:235], v[92:95]
	ds_read_b128 v[244:247], v211 offset:39936
	v_mfma_f32_16x16x32_bf16 v[60:63], v[190:193], v[232:235], v[60:63]
	ds_read_b128 v[216:219], v147
	v_mfma_f32_16x16x32_bf16 v[28:31], v[194:197], v[232:235], v[28:31]
	ds_read_b128 v[220:223], v147 offset:1024
	v_mfma_f32_16x16x32_bf16 v[12:15], v[202:205], v[232:235], v[12:15]
	ds_read_b128 v[224:227], v147 offset:2048
	s_waitcnt lgkmcnt(5)
	v_mfma_f32_16x16x32_bf16 v[84:87], v[186:189], v[236:239], v[84:87]
	ds_read_b128 v[228:231], v147 offset:3072
	ds_read_b128 v[232:235], v148 offset:16384
	v_mfma_f32_16x16x32_bf16 v[56:59], v[190:193], v[236:239], v[56:59]
	s_mov_b32 m0, s11
	v_mfma_f32_16x16x32_bf16 v[24:27], v[194:197], v[236:239], v[24:27]
	v_readfirstlane_b32 s11, v161
	v_mfma_f32_16x16x32_bf16 v[8:11], v[202:205], v[236:239], v[8:11]
	global_load_lds_dwordx4 v[144:145], off
	s_waitcnt lgkmcnt(6)
	v_mfma_f32_16x16x32_bf16 v[80:83], v[186:189], v[240:243], v[80:83]
	ds_read_b128 v[236:239], v148 offset:17408
	v_mfma_f32_16x16x32_bf16 v[52:55], v[190:193], v[240:243], v[52:55]
	s_mov_b32 m0, s11
	v_mfma_f32_16x16x32_bf16 v[20:23], v[194:197], v[240:243], v[20:23]
	v_readfirstlane_b32 s11, v162
	v_mfma_f32_16x16x32_bf16 v[4:7], v[202:205], v[240:243], v[4:7]
	global_load_lds_dwordx4 v[250:251], off
	s_waitcnt lgkmcnt(6)
	v_mfma_f32_16x16x32_bf16 v[72:75], v[186:189], v[244:247], v[72:75]
	ds_read_b128 v[240:243], v148 offset:18432
	v_mfma_f32_16x16x32_bf16 v[48:51], v[190:193], v[244:247], v[48:51]
	s_mov_b32 m0, s11
	v_mfma_f32_16x16x32_bf16 v[16:19], v[194:197], v[244:247], v[16:19]
	global_load_lds_dwordx4 v[142:143], off
	v_mfma_f32_16x16x32_bf16 v[0:3], v[202:205], v[244:247], v[0:3]
	ds_read_b128 v[244:247], v148 offset:19456
	v_add_u32_e32 v142, 0x19000, v149
	v_add_u32_e32 v143, 0x19400, v149
	v_add_u32_e32 v144, 0x19800, v149
	v_add_u32_e32 v145, 0x19c00, v149
	s_add_u32 s12, s12, 0x8000
	s_addc_u32 s13, s13, 0
	s_cmp_lg_u32 s12, 0x38000
	s_cbranch_scc1 .LBB0_290
	s_waitcnt lgkmcnt(3)
	v_mfma_f32_16x16x32_bf16 v[124:127], v[216:219], v[232:235], v[124:127]
	v_mfma_f32_16x16x32_bf16 v[108:111], v[220:223], v[232:235], v[108:111]
	v_mfma_f32_16x16x32_bf16 v[88:91], v[224:227], v[232:235], v[88:91]
	s_waitcnt vmcnt(4)
	s_barrier
; #define BIG_SYNC(N)                                              \
;   asm volatile("s_waitcnt vmcnt(%0)" ::"n"(N) : "memory");       \
;   __builtin_amdgcn_s_barrier();                                  \
;   asm volatile("" ::: "memory");                                 \
;   __builtin_amdgcn_sched_barrier(0);
; template <int NK, bool BNT = false> ...
;     ...
;   auto kstep = [&](int T, int cur, int nxt, bool do_stage) {
;     const unsigned char* sa = smem + cur * BIG_STAGE;
;     bf16x8 af[4], bfr[4];
; #pragma unroll
;     for (int m = 0; m < 4; ++m) af[m] = *reinterpret_cast<const bf16x8*>(sa + aoff + m * 1024);
; #pragma unroll
;     for (int n = 0; n < 4; ++n) bfr[n] = *reinterpret_cast<const bf16x8*>(sa + boff + n * 1024);
;     __builtin_amdgcn_sched_barrier(0);
;     if (do_stage) stage(T + 3, nxt);
; #pragma unroll
;     for (int m = 0; m < 4; ++m)
; #pragma unroll
;       for (int n = 0; n < 4; ++n) acc[m][n] = __builtin_amdgcn_mfma_f32_16x16x32_bf16(af[m], bfr[n], acc[m][n], 0, 0, 0);
;     if (do_stage) {
; #pragma unroll
;       for (int q = 0; q < NG; ++q) {
;         __builtin_amdgcn_sched_group_barrier(0x008, 3, 0);
;         __builtin_amdgcn_sched_group_barrier(0x010, 1, 0);
;       }
;       __builtin_amdgcn_sched_group_barrier(0x008, 16 - 3 * NG, 0);
;     }
;     __builtin_amdgcn_sched_barrier(0);
; #pragma unroll
;     for (int n = 0; n < 4; ++n) bfr[n] = *reinterpret_cast<const bf16x8*>(sa + boff + (4 + n) * 1024);
; #pragma unroll
;     for (int m = 0; m < 4; ++m)
; #pragma unroll
;       for (int n = 0; n < 4; ++n)
;         acc[m][4 + n] = __builtin_amdgcn_mfma_f32_16x16x32_bf16(af[m], bfr[n], acc[m][4 + n], 0, 0, 0);
;     __builtin_amdgcn_sched_barrier(0);
;   };
;     ...
;   stage(0, 0);
;   stage(1, 1);
;   stage(2, 2);
;   for (int it = 0; it < NK / 4 - 1; ++it) {
;     const int t = it * 4;
;     BIG_SYNC(2 * NG); kstep(t, 0, 3, true);
;     BIG_SYNC(2 * NG); kstep(t + 1, 1, 0, true);
;     BIG_SYNC(2 * NG); kstep(t + 2, 2, 1, true);
;     BIG_SYNC(2 * NG); kstep(t + 3, 3, 2, true);
;   }
;   BIG_SYNC(2 * NG); kstep(NK - 4, 0, 3, true);
;   BIG_SYNC(2 * NG); kstep(NK - 3, 1, 0, false);
;   BIG_SYNC(NG);     kstep(NK - 2, 2, 0, false);
;   BIG_SYNC(0);      kstep(NK - 1, 3, 0, false);
	s_mov_b64 s[12:13], 0x3e000
	v_mfma_f32_16x16x32_bf16 v[44:47], v[228:231], v[232:235], v[44:47]
	v_readfirstlane_b32 s11, v163
	s_waitcnt lgkmcnt(2)
	v_mfma_f32_16x16x32_bf16 v[120:123], v[216:219], v[236:239], v[120:123]
	ds_read_b128 v[232:235], v148 offset:20480
	v_mfma_f32_16x16x32_bf16 v[104:107], v[220:223], v[236:239], v[104:107]
	v_lshl_add_u64 v[198:199], v[136:137], 0, s[12:13]
	v_mfma_f32_16x16x32_bf16 v[76:79], v[224:227], v[236:239], v[76:79]
	v_lshl_add_u64 v[200:201], v[134:135], 0, s[12:13]
	v_mfma_f32_16x16x32_bf16 v[40:43], v[228:231], v[236:239], v[40:43]
	s_mov_b32 m0, s11
	s_waitcnt lgkmcnt(2)
	v_mfma_f32_16x16x32_bf16 v[116:119], v[216:219], v[240:243], v[116:119]
	ds_read_b128 v[236:239], v148 offset:21504
	v_mfma_f32_16x16x32_bf16 v[100:103], v[220:223], v[240:243], v[100:103]
	s_mov_b64 s[12:13], 0x7e000
	v_mfma_f32_16x16x32_bf16 v[68:71], v[224:227], v[240:243], v[68:71]
	v_readfirstlane_b32 s11, v164
	v_mfma_f32_16x16x32_bf16 v[36:39], v[228:231], v[240:243], v[36:39]
	v_lshl_add_u64 v[136:137], v[136:137], 0, s[12:13]
	s_waitcnt lgkmcnt(2)
	v_mfma_f32_16x16x32_bf16 v[112:115], v[216:219], v[244:247], v[112:115]
	ds_read_b128 v[240:243], v148 offset:22528
	v_mfma_f32_16x16x32_bf16 v[96:99], v[220:223], v[244:247], v[96:99]
	v_lshl_add_u64 v[134:135], v[134:135], 0, s[12:13]
	v_mfma_f32_16x16x32_bf16 v[64:67], v[224:227], v[244:247], v[64:67]
	global_load_lds_dwordx4 v[198:199], off
	v_mfma_f32_16x16x32_bf16 v[32:35], v[228:231], v[244:247], v[32:35]
	s_mov_b32 m0, s11
	s_waitcnt lgkmcnt(2)
	v_mfma_f32_16x16x32_bf16 v[92:95], v[216:219], v[232:235], v[92:95]
	ds_read_b128 v[244:247], v148 offset:23552
	v_mfma_f32_16x16x32_bf16 v[60:63], v[220:223], v[232:235], v[60:63]
	ds_read_b128 v[186:189], v147 offset:32768
	v_mfma_f32_16x16x32_bf16 v[28:31], v[224:227], v[232:235], v[28:31]
	ds_read_b128 v[190:193], v147 offset:33792
	v_mfma_f32_16x16x32_bf16 v[12:15], v[228:231], v[232:235], v[12:15]
	ds_read_b128 v[194:197], v147 offset:34816
	s_waitcnt lgkmcnt(5)
	v_mfma_f32_16x16x32_bf16 v[84:87], v[216:219], v[236:239], v[84:87]
	ds_read_b128 v[202:205], v147 offset:35840
	ds_read_b128 v[232:235], v148 offset:49152
	v_mfma_f32_16x16x32_bf16 v[56:59], v[220:223], v[236:239], v[56:59]
	v_readfirstlane_b32 s11, v165
	v_mfma_f32_16x16x32_bf16 v[24:27], v[224:227], v[236:239], v[24:27]
	global_load_lds_dwordx4 v[136:137], off
	v_mfma_f32_16x16x32_bf16 v[8:11], v[228:231], v[236:239], v[8:11]
	s_mov_b32 m0, s11
	s_waitcnt lgkmcnt(6)
	v_mfma_f32_16x16x32_bf16 v[80:83], v[216:219], v[240:243], v[80:83]
	ds_read_b128 v[236:239], v148 offset:50176
	v_mfma_f32_16x16x32_bf16 v[52:55], v[220:223], v[240:243], v[52:55]
	v_readfirstlane_b32 s11, v166
	v_mfma_f32_16x16x32_bf16 v[20:23], v[224:227], v[240:243], v[20:23]
	global_load_lds_dwordx4 v[200:201], off
	v_mfma_f32_16x16x32_bf16 v[4:7], v[228:231], v[240:243], v[4:7]
	s_mov_b32 m0, s11
	s_waitcnt lgkmcnt(6)
	v_mfma_f32_16x16x32_bf16 v[72:75], v[216:219], v[244:247], v[72:75]
	ds_read_b128 v[240:243], v148 offset:51200
	v_mfma_f32_16x16x32_bf16 v[48:51], v[220:223], v[244:247], v[48:51]
	global_load_lds_dwordx4 v[134:135], off
	v_mfma_f32_16x16x32_bf16 v[16:19], v[224:227], v[244:247], v[16:19]
	v_mfma_f32_16x16x32_bf16 v[0:3], v[228:231], v[244:247], v[0:3]
	ds_read_b128 v[244:247], v148 offset:52224
	s_waitcnt lgkmcnt(3)
	v_mfma_f32_16x16x32_bf16 v[124:127], v[186:189], v[232:235], v[124:127]
	v_mfma_f32_16x16x32_bf16 v[108:111], v[190:193], v[232:235], v[108:111]
	v_mfma_f32_16x16x32_bf16 v[88:91], v[194:197], v[232:235], v[88:91]
	v_mfma_f32_16x16x32_bf16 v[44:47], v[202:205], v[232:235], v[44:47]
	s_waitcnt vmcnt(4)
	s_barrier
	s_waitcnt lgkmcnt(2)
	v_mfma_f32_16x16x32_bf16 v[120:123], v[186:189], v[236:239], v[120:123]
	ds_read_b128 v[232:235], v148 offset:53248
	v_mfma_f32_16x16x32_bf16 v[104:107], v[190:193], v[236:239], v[104:107]
	v_mfma_f32_16x16x32_bf16 v[76:79], v[194:197], v[236:239], v[76:79]
	v_mfma_f32_16x16x32_bf16 v[40:43], v[202:205], v[236:239], v[40:43]
	s_waitcnt lgkmcnt(2)
	v_mfma_f32_16x16x32_bf16 v[116:119], v[186:189], v[240:243], v[116:119]
	ds_read_b128 v[236:239], v148 offset:54272
	v_mfma_f32_16x16x32_bf16 v[100:103], v[190:193], v[240:243], v[100:103]
	v_mfma_f32_16x16x32_bf16 v[68:71], v[194:197], v[240:243], v[68:71]
	v_mfma_f32_16x16x32_bf16 v[36:39], v[202:205], v[240:243], v[36:39]
	s_waitcnt lgkmcnt(2)
	v_mfma_f32_16x16x32_bf16 v[112:115], v[186:189], v[244:247], v[112:115]
	ds_read_b128 v[240:243], v148 offset:55296
	v_mfma_f32_16x16x32_bf16 v[96:99], v[190:193], v[244:247], v[96:99]
	v_mfma_f32_16x16x32_bf16 v[64:67], v[194:197], v[244:247], v[64:67]
	v_mfma_f32_16x16x32_bf16 v[32:35], v[202:205], v[244:247], v[32:35]
	s_waitcnt lgkmcnt(2)
	v_mfma_f32_16x16x32_bf16 v[92:95], v[186:189], v[232:235], v[92:95]
	ds_read_b128 v[244:247], v148 offset:56320
	v_mfma_f32_16x16x32_bf16 v[60:63], v[190:193], v[232:235], v[60:63]
	v_mfma_f32_16x16x32_bf16 v[28:31], v[194:197], v[232:235], v[28:31]
	v_mfma_f32_16x16x32_bf16 v[12:15], v[202:205], v[232:235], v[12:15]
	s_waitcnt lgkmcnt(2)
	v_mfma_f32_16x16x32_bf16 v[84:87], v[186:189], v[236:239], v[84:87]
	v_mfma_f32_16x16x32_bf16 v[56:59], v[190:193], v[236:239], v[56:59]
	v_mfma_f32_16x16x32_bf16 v[24:27], v[194:197], v[236:239], v[24:27]
	v_mfma_f32_16x16x32_bf16 v[8:11], v[202:205], v[236:239], v[8:11]
	s_waitcnt lgkmcnt(1)
	v_mfma_f32_16x16x32_bf16 v[80:83], v[186:189], v[240:243], v[80:83]
	v_mfma_f32_16x16x32_bf16 v[52:55], v[190:193], v[240:243], v[52:55]
	v_mfma_f32_16x16x32_bf16 v[20:23], v[194:197], v[240:243], v[20:23]
	v_mfma_f32_16x16x32_bf16 v[4:7], v[202:205], v[240:243], v[4:7]
	s_waitcnt lgkmcnt(0)
	v_mfma_f32_16x16x32_bf16 v[72:75], v[186:189], v[244:247], v[72:75]
	v_mfma_f32_16x16x32_bf16 v[48:51], v[190:193], v[244:247], v[48:51]
	v_mfma_f32_16x16x32_bf16 v[16:19], v[194:197], v[244:247], v[16:19]
	v_mfma_f32_16x16x32_bf16 v[0:3], v[202:205], v[244:247], v[0:3]
	v_mov_b32_e32 v186, 0xf149f2ca
	v_mov_b32_e32 v187, 0x3c0881c4
	v_mov_b32_e32 v188, 0xbab64f3b
	v_mov_b32_e32 v189, 0x24800
	v_mov_b32_e32 v190, 1
	v_mov_b32_e32 v191, 0x24804
	v_mov_b32_e32 v192, 0xfcf
	v_mov_b32_e32 v193, 0x7cf
	v_mov_b32_e32 v194, 0xfdf
	v_mov_b32_e32 v195, 0x7df
	v_mov_b32_e32 v196, 0xfef
	v_mov_b32_e32 v197, 0x7ef
	v_mov_b32_e32 v198, 0xfff
	v_mov_b32_e32 v199, 0x7ff
	v_mov_b32_e32 v200, 0x20000
	v_mov_b32_e32 v201, 0xf8f
	v_mov_b32_e32 v202, 0x78f
	v_mov_b32_e32 v203, 0xf9f
	v_mov_b32_e32 v204, 0x79f
	v_mov_b32_e32 v205, 0xfaf
	v_mov_b32_e32 v210, 0x7f800000
	v_not_b32_e32 v211, 63
	v_not_b32_e32 v212, 31
	v_mov_b32_e32 v213, 0x7fc00000
	s_waitcnt vmcnt(4)
	s_barrier
; template <int NK, bool BNT = false> ...
;     ...
;   auto kstep = [&](int T, int cur, int nxt, bool do_stage) {
;     const unsigned char* sa = smem + cur * BIG_STAGE;
;     bf16x8 af[4], bfr[4];
; #pragma unroll
;     for (int m = 0; m < 4; ++m) af[m] = *reinterpret_cast<const bf16x8*>(sa + aoff + m * 1024);
; #pragma unroll
;     for (int n = 0; n < 4; ++n) bfr[n] = *reinterpret_cast<const bf16x8*>(sa + boff + n * 1024);
;     __builtin_amdgcn_sched_barrier(0);
;     if (do_stage) stage(T + 3, nxt);
; #pragma unroll
;     for (int m = 0; m < 4; ++m)
; #pragma unroll
;       for (int n = 0; n < 4; ++n) acc[m][n] = __builtin_amdgcn_mfma_f32_16x16x32_bf16(af[m], bfr[n], acc[m][n], 0, 0, 0);
;     if (do_stage) {
; #pragma unroll
;       for (int q = 0; q < NG; ++q) {
;         __builtin_amdgcn_sched_group_barrier(0x008, 3, 0);
;         __builtin_amdgcn_sched_group_barrier(0x010, 1, 0);
;       }
;       __builtin_amdgcn_sched_group_barrier(0x008, 16 - 3 * NG, 0);
;     }
;     __builtin_amdgcn_sched_barrier(0);
; #pragma unroll
;     for (int n = 0; n < 4; ++n) bfr[n] = *reinterpret_cast<const bf16x8*>(sa + boff + (4 + n) * 1024);
; #pragma unroll
;     for (int m = 0; m < 4; ++m)
; #pragma unroll
;       for (int n = 0; n < 4; ++n)
;         acc[m][4 + n] = __builtin_amdgcn_mfma_f32_16x16x32_bf16(af[m], bfr[n], acc[m][4 + n], 0, 0, 0);
;     __builtin_amdgcn_sched_barrier(0);
;   };
;     ...
;   stage(0, 0);
;   stage(1, 1);
;   stage(2, 2);
;   for (int it = 0; it < NK / 4 - 1; ++it) {
;     const int t = it * 4;
;     BIG_SYNC(2 * NG); kstep(t, 0, 3, true);
;     BIG_SYNC(2 * NG); kstep(t + 1, 1, 0, true);
;     BIG_SYNC(2 * NG); kstep(t + 2, 2, 1, true);
;     BIG_SYNC(2 * NG); kstep(t + 3, 3, 2, true);
;   }
;   BIG_SYNC(2 * NG); kstep(NK - 4, 0, 3, true);
;   BIG_SYNC(2 * NG); kstep(NK - 3, 1, 0, false);
;   BIG_SYNC(NG);     kstep(NK - 2, 2, 0, false);
;   BIG_SYNC(0);      kstep(NK - 1, 3, 0, false);
; template <int MODE, int NSUB>
; __device__ __forceinline__ void epilogue(const Params& p, int layer, f32x4 (&acc)[4][NSUB], int tm, int tn, int g,
;                                          const float* s_rstd, const int tid_in) {
;     ...
;   } else if constexpr (MODE == EPI_UP) {
;     const int woff = widen_off(fq);
; #pragma unroll
;     for (int n = 0; n < NSUB; ++n) {
;       const int nl = wc * (NSUB * 16) + n * 16 + fr;
;       const int t = tn * (NSUB * 32) + nl;
	ds_read_b128 v[134:137], v167
	ds_read_b128 v[138:141], v167 offset:1024
	ds_read_b128 v[154:157], v167 offset:2048
	ds_read_b128 v[158:161], v167 offset:3072
	ds_read_b128 v[162:165], v168
	ds_read_b128 v[166:169], v169
	ds_read_b128 v[216:219], v170
	ds_read_b128 v[220:223], v172
	s_waitcnt lgkmcnt(0)
	v_mfma_f32_16x16x32_bf16 v[124:127], v[134:137], v[162:165], v[124:127]
	v_mfma_f32_16x16x32_bf16 v[120:123], v[134:137], v[166:169], v[120:123]
	v_mfma_f32_16x16x32_bf16 v[116:119], v[134:137], v[216:219], v[116:119]
	v_mfma_f32_16x16x32_bf16 v[112:115], v[134:137], v[220:223], v[112:115]
	v_mfma_f32_16x16x32_bf16 v[224:227], v[138:141], v[162:165], v[108:111]
	v_mfma_f32_16x16x32_bf16 v[104:107], v[138:141], v[166:169], v[104:107]
	v_mfma_f32_16x16x32_bf16 v[100:103], v[138:141], v[216:219], v[100:103]
	v_mfma_f32_16x16x32_bf16 v[96:99], v[138:141], v[220:223], v[96:99]
	v_mfma_f32_16x16x32_bf16 v[228:231], v[154:157], v[162:165], v[88:91]
	v_mfma_f32_16x16x32_bf16 v[232:235], v[154:157], v[166:169], v[76:79]
	v_mfma_f32_16x16x32_bf16 v[68:71], v[154:157], v[216:219], v[68:71]
	v_mfma_f32_16x16x32_bf16 v[64:67], v[154:157], v[220:223], v[64:67]
	v_mfma_f32_16x16x32_bf16 v[44:47], v[158:161], v[162:165], v[44:47]
	v_mfma_f32_16x16x32_bf16 v[40:43], v[158:161], v[166:169], v[40:43]
	v_mfma_f32_16x16x32_bf16 v[36:39], v[158:161], v[216:219], v[36:39]
	v_mfma_f32_16x16x32_bf16 v[32:35], v[158:161], v[220:223], v[32:35]
	ds_read_b128 v[76:79], v173
	ds_read_b128 v[88:91], v174
	s_waitcnt lgkmcnt(0)
	v_mfma_f32_16x16x32_bf16 v[162:165], v[134:137], v[76:79], v[92:95]
	s_nop 2
	ds_read_b128 v[92:95], v178
	v_mfma_f32_16x16x32_bf16 v[166:169], v[134:137], v[88:91], v[84:87]
	s_nop 2
	ds_read_b128 v[84:87], v175
	s_waitcnt lgkmcnt(0)
	v_mfma_f32_16x16x32_bf16 v[172:175], v[134:137], v[84:87], v[80:83]
	v_mfma_f32_16x16x32_bf16 v[134:137], v[134:137], v[92:95], v[72:75]
	v_mfma_f32_16x16x32_bf16 v[216:219], v[138:141], v[76:79], v[60:63]
	v_mfma_f32_16x16x32_bf16 v[220:223], v[138:141], v[88:91], v[56:59]
	v_mfma_f32_16x16x32_bf16 v[52:55], v[138:141], v[84:87], v[52:55]
	v_mfma_f32_16x16x32_bf16 v[48:51], v[138:141], v[92:95], v[48:51]
	v_mfma_f32_16x16x32_bf16 v[138:141], v[154:157], v[76:79], v[28:31]
	v_mfma_f32_16x16x32_bf16 v[236:239], v[154:157], v[88:91], v[24:27]
	v_mfma_f32_16x16x32_bf16 v[20:23], v[154:157], v[84:87], v[20:23]
	v_mfma_f32_16x16x32_bf16 v[16:19], v[154:157], v[92:95], v[16:19]
	v_mfma_f32_16x16x32_bf16 v[154:157], v[158:161], v[76:79], v[12:15]
	v_mfma_f32_16x16x32_bf16 v[240:243], v[158:161], v[88:91], v[8:11]
	v_mfma_f32_16x16x32_bf16 v[244:247], v[158:161], v[84:87], v[4:7]
	v_mfma_f32_16x16x32_bf16 v[0:3], v[158:161], v[92:95], v[0:3]
	s_waitcnt vmcnt(0)
	s_barrier
	s_nop 0
	ds_read_b128 v[4:7], v176
	ds_read_b128 v[8:11], v176 offset:1024
	ds_read_b128 v[158:161], v176 offset:2048
	ds_read_b128 v[248:251], v176 offset:3072
	ds_read_b128 v[12:15], v179
	ds_read_b128 v[24:27], v180
	ds_read_b128 v[28:31], v181
	ds_read_b128 v[56:59], v182
	s_waitcnt lgkmcnt(0)
	v_mfma_f32_16x16x32_bf16 v[124:127], v[4:7], v[12:15], v[124:127]
	v_mfma_f32_16x16x32_bf16 v[108:111], v[4:7], v[24:27], v[120:123]
	v_mfma_f32_16x16x32_bf16 v[92:95], v[4:7], v[28:31], v[116:119]
	v_mfma_f32_16x16x32_bf16 v[76:79], v[4:7], v[56:59], v[112:115]
	v_mfma_f32_16x16x32_bf16 v[112:115], v[8:11], v[12:15], v[224:227]
	v_mfma_f32_16x16x32_bf16 v[104:107], v[8:11], v[24:27], v[104:107]
	v_mfma_f32_16x16x32_bf16 v[88:91], v[8:11], v[28:31], v[100:103]
	v_mfma_f32_16x16x32_bf16 v[72:75], v[8:11], v[56:59], v[96:99]
	v_mfma_f32_16x16x32_bf16 v[120:123], v[158:161], v[12:15], v[228:231]
	v_mfma_f32_16x16x32_bf16 v[100:103], v[158:161], v[24:27], v[232:235]
	v_mfma_f32_16x16x32_bf16 v[84:87], v[158:161], v[28:31], v[68:71]
	v_mfma_f32_16x16x32_bf16 v[68:71], v[158:161], v[56:59], v[64:67]
	v_mfma_f32_16x16x32_bf16 v[178:181], v[248:251], v[12:15], v[44:47]
	v_mfma_f32_16x16x32_bf16 v[96:99], v[248:251], v[24:27], v[40:43]
	v_mfma_f32_16x16x32_bf16 v[80:83], v[248:251], v[28:31], v[36:39]
	v_mfma_f32_16x16x32_bf16 v[64:67], v[248:251], v[56:59], v[32:35]
	s_nop 2
	ds_read_b128 v[32:35], v142
	ds_read_b128 v[116:119], v143
	s_waitcnt lgkmcnt(0)
	v_mfma_f32_16x16x32_bf16 v[60:63], v[4:7], v[32:35], v[162:165]
	s_nop 2
	ds_read_b128 v[162:165], v144
	ds_read_b128 v[142:145], v145
	v_mfma_f32_16x16x32_bf16 v[44:47], v[4:7], v[116:119], v[166:169]
	s_waitcnt lgkmcnt(0)
	v_mfma_f32_16x16x32_bf16 v[28:31], v[4:7], v[162:165], v[172:175]
	v_mfma_f32_16x16x32_bf16 v[12:15], v[4:7], v[142:145], v[134:137]
	v_mfma_f32_16x16x32_bf16 v[56:59], v[8:11], v[32:35], v[216:219]
	v_mfma_f32_16x16x32_bf16 v[40:43], v[8:11], v[116:119], v[220:223]
	v_mfma_f32_16x16x32_bf16 v[24:27], v[8:11], v[162:165], v[52:55]
	v_mfma_f32_16x16x32_bf16 v[8:11], v[8:11], v[142:145], v[48:51]
	v_mfma_f32_16x16x32_bf16 v[52:55], v[158:161], v[32:35], v[138:141]
	v_mfma_f32_16x16x32_bf16 v[36:39], v[158:161], v[116:119], v[236:239]
	v_mfma_f32_16x16x32_bf16 v[20:23], v[158:161], v[162:165], v[20:23]
	v_mfma_f32_16x16x32_bf16 v[4:7], v[158:161], v[142:145], v[16:19]
	v_mfma_f32_16x16x32_bf16 v[48:51], v[248:251], v[32:35], v[154:157]
	v_mfma_f32_16x16x32_bf16 v[32:35], v[248:251], v[116:119], v[240:243]
	v_mfma_f32_16x16x32_bf16 v[16:19], v[248:251], v[162:165], v[244:247]
	v_mfma_f32_16x16x32_bf16 v[0:3], v[248:251], v[142:145], v[0:3]
	v_mov_b32_e32 v116, v215
	s_lshl_b32 s10, s10, 8
	v_and_b32_e32 v117, 16, v116
	v_lshrrev_b32_e32 v118, 2, v116
	v_and_or_b32 v136, v118, 8, v117
	v_lshlrev_b32_e32 v117, 1, v116
	v_and_b32_e32 v119, 15, v116
	v_and_b32_e32 v117, 0x80, v117
	v_lshl_or_b32 v134, s15, 8, v117
	v_or_b32_e32 v117, v117, v119
	v_ashrrev_i32_e32 v116, 1, v116
	v_lshlrev_b32_e32 v118, 2, v117
	v_and_b32_e32 v116, 0xffffffc0, v116
	v_add3_u32 v135, s10, v150, v116
	v_or_b32_e32 v116, 0x20000, v118
	ds_read_b32 v137, v116
	v_lshlrev_b32_e32 v152, 6, v119
	v_or_b32_e32 v119, 0x20040, v118
	v_readlane_b32 s64, v252, 4
	ds_read_b32 v119, v119
	s_waitcnt lgkmcnt(0)
; template <int MODE, int NSUB>
; __device__ __forceinline__ void epilogue(const Params& p, int layer, f32x4 (&acc)[4][NSUB], int tm, int tn, int g,
;                                          const float* s_rstd, const int tid_in) {
;     ...
;       for (int mp = 0; mp < 2; ++mp) {
;         bf16x4 pk[2];
; #pragma unroll
;         for (int h2 = 0; h2 < 2; ++h2) {
;           const int m = mp * 2 + h2;
;           float v[4];
; #pragma unroll
;           for (int j = 0; j < 4; ++j) {
;             float a = fmaxf(acc[m][n][j] * rs, 0.f);
;             v[j] = a * a;
;           }
;           pk[h2] = pack4(v[0], v[1], v[2], v[3]);
;         }
;         const int f = tm * 128 + wr * 64 + mp * 32 + woff;
;         __builtin_nontemporal_store(widen_pair(pk[0], pk[1]), reinterpret_cast<u32x4*>(p.hm + blk(t, f, 128)));
	v_mul_f32_e32 v116, v124, v137
	v_mul_f32_e32 v117, v125, v137
	v_mul_f32_e32 v124, v126, v137
	v_mul_f32_e32 v125, v127, v137
	v_mul_f32_e32 v112, v112, v137
	v_mul_f32_e32 v113, v113, v137
	v_max_f32_e32 v124, 0, v124
	v_max_f32_e32 v125, 0, v125
	v_max_f32_e32 v112, 0, v112
	v_max_f32_e32 v113, 0, v113
	v_mul_f32_e32 v114, v114, v137
	v_mul_f32_e32 v115, v115, v137
	v_pk_mul_f32 v[126:127], v[124:125], v[124:125]
	v_pk_mul_f32 v[112:113], v[112:113], v[112:113]
	v_max_f32_e32 v114, 0, v114
	v_max_f32_e32 v115, 0, v115
	v_cvt_pk_bf16_f32 v125, v126, v127
	v_pk_mul_f32 v[114:115], v[114:115], v[114:115]
	v_cvt_pk_bf16_f32 v126, v112, v113
	v_ashrrev_i32_e32 v112, 5, v135
	v_cvt_pk_bf16_f32 v127, v114, v115
	v_add_u32_e32 v114, v112, v134
	v_ashrrev_i32_e32 v115, 31, v114
	v_lshlrev_b64 v[112:113], 13, v[114:115]
	v_mul_f32_e32 v115, v120, v137
	v_max_f32_e32 v120, 0, v115
	v_mul_f32_e32 v115, v121, v137
	v_max_f32_e32 v121, 0, v115
	v_mul_f32_e32 v115, v122, v137
	v_max_f32_e32 v116, 0, v116
	v_max_f32_e32 v117, 0, v117
	v_max_f32_e32 v122, 0, v115
	v_mul_f32_e32 v115, v123, v137
	v_pk_mul_f32 v[116:117], v[116:117], v[116:117]
	v_readlane_b32 s78, v252, 18
	v_readlane_b32 s79, v252, 19
	v_max_f32_e32 v123, 0, v115
	v_cvt_pk_bf16_f32 v124, v116, v117
	v_lshl_add_u64 v[116:117], s[78:79], 0, v[112:113]
	v_pk_mul_f32 v[120:121], v[120:121], v[120:121]
	v_pk_mul_f32 v[122:123], v[122:123], v[122:123]
	v_mul_f32_e32 v115, v178, v137
	v_lshl_add_u64 v[134:135], v[116:117], 0, v[152:153]
	v_lshlrev_b32_e32 v112, 1, v136
	v_mov_b32_e32 v113, v153
	v_cvt_pk_bf16_f32 v120, v120, v121
	v_cvt_pk_bf16_f32 v121, v122, v123
	v_max_f32_e32 v122, 0, v115
	v_mul_f32_e32 v115, v179, v137
	v_permlane16_swap_b32_e32 v124, v126
	v_permlane16_swap_b32_e32 v125, v127
	v_lshl_add_u64 v[134:135], v[134:135], 0, v[112:113]
	v_max_f32_e32 v123, 0, v115
	v_mul_f32_e32 v115, v180, v137
	global_store_dwordx4 v[134:135], v[124:127], off nt
	v_add_u32_e32 v114, 1, v114
	v_mul_f32_e32 v108, v108, v119
	v_max_f32_e32 v124, 0, v115
	v_mul_f32_e32 v115, v181, v137
	v_mul_f32_e32 v109, v109, v119
	v_mul_f32_e32 v110, v110, v119
	v_mul_f32_e32 v111, v111, v119
	v_mul_f32_e32 v104, v104, v119
	v_mul_f32_e32 v105, v105, v119
	v_max_f32_e32 v125, 0, v115
	v_ashrrev_i32_e32 v115, 31, v114
	v_max_f32_e32 v108, 0, v108
	v_max_f32_e32 v109, 0, v109
	v_max_f32_e32 v110, 0, v110
	v_max_f32_e32 v111, 0, v111
	v_max_f32_e32 v104, 0, v104
	v_max_f32_e32 v105, 0, v105
	v_mul_f32_e32 v100, v100, v119
	v_mul_f32_e32 v101, v101, v119
	v_mul_f32_e32 v102, v102, v119
	v_mul_f32_e32 v103, v103, v119
	v_mul_f32_e32 v96, v96, v119
	v_mul_f32_e32 v97, v97, v119
	v_mul_f32_e32 v98, v98, v119
	v_mul_f32_e32 v99, v99, v119
	v_lshlrev_b64 v[114:115], 13, v[114:115]
	v_pk_mul_f32 v[108:109], v[108:109], v[108:109]
	v_pk_mul_f32 v[110:111], v[110:111], v[110:111]
	v_pk_mul_f32 v[104:105], v[104:105], v[104:105]
	v_max_f32_e32 v100, 0, v100
	v_max_f32_e32 v101, 0, v101
	v_max_f32_e32 v102, 0, v102
	v_max_f32_e32 v103, 0, v103
	v_max_f32_e32 v96, 0, v96
	v_max_f32_e32 v97, 0, v97
	v_max_f32_e32 v98, 0, v98
	v_max_f32_e32 v99, 0, v99
	v_lshl_add_u64 v[114:115], s[78:79], 0, v[114:115]
	v_cvt_pk_bf16_f32 v108, v108, v109
	v_cvt_pk_bf16_f32 v109, v110, v111
	v_cvt_pk_bf16_f32 v110, v104, v105
	v_or_b32_e32 v104, 0x400, v152
	v_mov_b32_e32 v105, v153
	v_pk_mul_f32 v[100:101], v[100:101], v[100:101]
	v_pk_mul_f32 v[102:103], v[102:103], v[102:103]
	v_pk_mul_f32 v[96:97], v[96:97], v[96:97]
	v_pk_mul_f32 v[98:99], v[98:99], v[98:99]
	v_cvt_pk_bf16_f32 v100, v100, v101
	v_cvt_pk_bf16_f32 v101, v102, v103
	v_cvt_pk_bf16_f32 v102, v96, v97
	v_cvt_pk_bf16_f32 v103, v98, v99
	v_lshl_add_u64 v[96:97], v[114:115], 0, v[104:105]
	v_permlane16_swap_b32_e32 v100, v102
	v_permlane16_swap_b32_e32 v101, v103
	v_lshl_add_u64 v[96:97], v[96:97], 0, v[112:113]
	global_store_dwordx4 v[96:97], v[100:103], off nt
	v_or_b32_e32 v96, 0x20080, v118
	ds_read_b32 v96, v96
	v_mul_f32_e32 v106, v106, v119
	v_mul_f32_e32 v107, v107, v119
	v_pk_mul_f32 v[122:123], v[122:123], v[122:123]
	v_pk_mul_f32 v[124:125], v[124:125], v[124:125]
	s_waitcnt lgkmcnt(0)
	v_mul_f32_e32 v92, v92, v96
	v_mul_f32_e32 v93, v93, v96
	v_mul_f32_e32 v94, v94, v96
	v_mul_f32_e32 v95, v95, v96
	v_mul_f32_e32 v88, v88, v96
	v_mul_f32_e32 v89, v89, v96
	v_max_f32_e32 v92, 0, v92
	v_max_f32_e32 v93, 0, v93
	v_max_f32_e32 v94, 0, v94
	v_max_f32_e32 v95, 0, v95
	v_max_f32_e32 v88, 0, v88
	v_max_f32_e32 v89, 0, v89
	v_mul_f32_e32 v84, v84, v96
	v_mul_f32_e32 v85, v85, v96
	v_mul_f32_e32 v86, v86, v96
	v_mul_f32_e32 v87, v87, v96
	v_mul_f32_e32 v80, v80, v96
	v_mul_f32_e32 v81, v81, v96
	v_mul_f32_e32 v82, v82, v96
	v_mul_f32_e32 v83, v83, v96
	v_pk_mul_f32 v[92:93], v[92:93], v[92:93]
	v_pk_mul_f32 v[94:95], v[94:95], v[94:95]
	v_pk_mul_f32 v[88:89], v[88:89], v[88:89]
	v_max_f32_e32 v84, 0, v84
	v_max_f32_e32 v85, 0, v85
	v_max_f32_e32 v86, 0, v86
	v_max_f32_e32 v87, 0, v87
	v_max_f32_e32 v80, 0, v80
	v_max_f32_e32 v81, 0, v81
	v_max_f32_e32 v82, 0, v82
	v_max_f32_e32 v83, 0, v83
	v_cvt_pk_bf16_f32 v92, v92, v93
	v_cvt_pk_bf16_f32 v93, v94, v95
	v_cvt_pk_bf16_f32 v94, v88, v89
	v_or_b32_e32 v88, 0x800, v152
	v_mov_b32_e32 v89, v153
	v_pk_mul_f32 v[84:85], v[84:85], v[84:85]
	v_pk_mul_f32 v[86:87], v[86:87], v[86:87]
	v_pk_mul_f32 v[80:81], v[80:81], v[80:81]
	v_pk_mul_f32 v[82:83], v[82:83], v[82:83]
	v_cvt_pk_bf16_f32 v84, v84, v85
	v_cvt_pk_bf16_f32 v85, v86, v87
	v_cvt_pk_bf16_f32 v86, v80, v81
	v_cvt_pk_bf16_f32 v87, v82, v83
	v_lshl_add_u64 v[80:81], v[114:115], 0, v[88:89]
	v_permlane16_swap_b32_e32 v84, v86
	v_permlane16_swap_b32_e32 v85, v87
	v_lshl_add_u64 v[80:81], v[80:81], 0, v[112:113]
	global_store_dwordx4 v[80:81], v[84:87], off nt
	v_or_b32_e32 v80, 0x200c0, v118
	ds_read_b32 v80, v80
	v_mul_f32_e32 v90, v90, v96
	v_mul_f32_e32 v91, v91, v96
	v_max_f32_e32 v106, 0, v106
	v_max_f32_e32 v107, 0, v107
	s_waitcnt lgkmcnt(0)
; template <int MODE, int NSUB>
; __device__ __forceinline__ void epilogue(const Params& p, int layer, f32x4 (&acc)[4][NSUB], int tm, int tn, int g,
;                                          const float* s_rstd, const int tid_in) {
;     ...
;       for (int mp = 0; mp < 2; ++mp) {
;         bf16x4 pk[2];
; #pragma unroll
;         for (int h2 = 0; h2 < 2; ++h2) {
;           const int m = mp * 2 + h2;
;           float v[4];
; #pragma unroll
;           for (int j = 0; j < 4; ++j) {
;             float a = fmaxf(acc[m][n][j] * rs, 0.f);
;             v[j] = a * a;
;           }
;           pk[h2] = pack4(v[0], v[1], v[2], v[3]);
;         }
;         const int f = tm * 128 + wr * 64 + mp * 32 + woff;
;         __builtin_nontemporal_store(widen_pair(pk[0], pk[1]), reinterpret_cast<u32x4*>(p.hm + blk(t, f, 128)));
	v_mul_f32_e32 v76, v76, v80
	v_mul_f32_e32 v77, v77, v80
	v_mul_f32_e32 v78, v78, v80
	v_mul_f32_e32 v79, v79, v80
	v_mul_f32_e32 v72, v72, v80
	v_mul_f32_e32 v73, v73, v80
	v_max_f32_e32 v76, 0, v76
	v_max_f32_e32 v77, 0, v77
	v_max_f32_e32 v78, 0, v78
	v_max_f32_e32 v79, 0, v79
	v_max_f32_e32 v72, 0, v72
	v_max_f32_e32 v73, 0, v73
	v_mul_f32_e32 v68, v68, v80
	v_mul_f32_e32 v69, v69, v80
	v_mul_f32_e32 v70, v70, v80
	v_mul_f32_e32 v71, v71, v80
	v_mul_f32_e32 v64, v64, v80
	v_mul_f32_e32 v65, v65, v80
	v_mul_f32_e32 v66, v66, v80
	v_mul_f32_e32 v67, v67, v80
	v_pk_mul_f32 v[76:77], v[76:77], v[76:77]
	v_pk_mul_f32 v[78:79], v[78:79], v[78:79]
	v_pk_mul_f32 v[72:73], v[72:73], v[72:73]
	v_max_f32_e32 v68, 0, v68
	v_max_f32_e32 v69, 0, v69
	v_max_f32_e32 v70, 0, v70
	v_max_f32_e32 v71, 0, v71
	v_max_f32_e32 v64, 0, v64
	v_max_f32_e32 v65, 0, v65
	v_max_f32_e32 v66, 0, v66
	v_max_f32_e32 v67, 0, v67
	v_cvt_pk_bf16_f32 v76, v76, v77
	v_cvt_pk_bf16_f32 v77, v78, v79
	v_cvt_pk_bf16_f32 v78, v72, v73
	v_or_b32_e32 v72, 0xc00, v152
	v_mov_b32_e32 v73, v153
	v_pk_mul_f32 v[68:69], v[68:69], v[68:69]
	v_pk_mul_f32 v[70:71], v[70:71], v[70:71]
	v_pk_mul_f32 v[64:65], v[64:65], v[64:65]
	v_pk_mul_f32 v[66:67], v[66:67], v[66:67]
	v_cvt_pk_bf16_f32 v68, v68, v69
	v_cvt_pk_bf16_f32 v69, v70, v71
	v_cvt_pk_bf16_f32 v70, v64, v65
	v_cvt_pk_bf16_f32 v71, v66, v67
	v_lshl_add_u64 v[64:65], v[114:115], 0, v[72:73]
	v_permlane16_swap_b32_e32 v68, v70
	v_permlane16_swap_b32_e32 v69, v71
	v_lshl_add_u64 v[64:65], v[64:65], 0, v[112:113]
	global_store_dwordx4 v[64:65], v[68:71], off nt
	v_or_b32_e32 v64, 0x20100, v118
	ds_read_b32 v64, v64
	v_mul_f32_e32 v74, v74, v80
	v_mul_f32_e32 v75, v75, v80
	v_max_f32_e32 v90, 0, v90
	v_max_f32_e32 v91, 0, v91
	s_waitcnt lgkmcnt(0)
	v_mul_f32_e32 v60, v60, v64
	v_mul_f32_e32 v61, v61, v64
	v_mul_f32_e32 v62, v62, v64
	v_mul_f32_e32 v63, v63, v64
	v_mul_f32_e32 v56, v56, v64
	v_mul_f32_e32 v57, v57, v64
	v_max_f32_e32 v60, 0, v60
	v_max_f32_e32 v61, 0, v61
	v_max_f32_e32 v62, 0, v62
	v_max_f32_e32 v63, 0, v63
	v_max_f32_e32 v56, 0, v56
	v_max_f32_e32 v57, 0, v57
	v_mul_f32_e32 v52, v52, v64
	v_mul_f32_e32 v53, v53, v64
	v_mul_f32_e32 v54, v54, v64
	v_mul_f32_e32 v55, v55, v64
	v_mul_f32_e32 v48, v48, v64
	v_mul_f32_e32 v49, v49, v64
	v_mul_f32_e32 v50, v50, v64
	v_mul_f32_e32 v51, v51, v64
	v_pk_mul_f32 v[60:61], v[60:61], v[60:61]
	v_pk_mul_f32 v[62:63], v[62:63], v[62:63]
	v_pk_mul_f32 v[56:57], v[56:57], v[56:57]
	v_max_f32_e32 v52, 0, v52
	v_max_f32_e32 v53, 0, v53
	v_max_f32_e32 v54, 0, v54
	v_max_f32_e32 v55, 0, v55
	v_max_f32_e32 v48, 0, v48
	v_max_f32_e32 v49, 0, v49
	v_max_f32_e32 v50, 0, v50
	v_max_f32_e32 v51, 0, v51
	v_cvt_pk_bf16_f32 v60, v60, v61
	v_cvt_pk_bf16_f32 v61, v62, v63
	v_cvt_pk_bf16_f32 v62, v56, v57
	v_or_b32_e32 v56, 0x1000, v152
	v_mov_b32_e32 v57, v153
	v_pk_mul_f32 v[52:53], v[52:53], v[52:53]
	v_pk_mul_f32 v[54:55], v[54:55], v[54:55]
	v_pk_mul_f32 v[48:49], v[48:49], v[48:49]
	v_pk_mul_f32 v[50:51], v[50:51], v[50:51]
	v_cvt_pk_bf16_f32 v52, v52, v53
	v_cvt_pk_bf16_f32 v53, v54, v55
	v_cvt_pk_bf16_f32 v54, v48, v49
	v_cvt_pk_bf16_f32 v55, v50, v51
	v_lshl_add_u64 v[48:49], v[114:115], 0, v[56:57]
	v_permlane16_swap_b32_e32 v52, v54
	v_permlane16_swap_b32_e32 v53, v55
	v_lshl_add_u64 v[48:49], v[48:49], 0, v[112:113]
	global_store_dwordx4 v[48:49], v[52:55], off nt
	v_or_b32_e32 v48, 0x20140, v118
	ds_read_b32 v48, v48
	v_mul_f32_e32 v58, v58, v64
	v_mul_f32_e32 v59, v59, v64
	v_max_f32_e32 v74, 0, v74
	v_max_f32_e32 v75, 0, v75
	s_waitcnt lgkmcnt(0)
	v_mul_f32_e32 v44, v44, v48
	v_mul_f32_e32 v45, v45, v48
	v_mul_f32_e32 v46, v46, v48
	v_mul_f32_e32 v47, v47, v48
	v_mul_f32_e32 v40, v40, v48
	v_mul_f32_e32 v41, v41, v48
	v_max_f32_e32 v44, 0, v44
	v_max_f32_e32 v45, 0, v45
	v_max_f32_e32 v46, 0, v46
	v_max_f32_e32 v47, 0, v47
	v_max_f32_e32 v40, 0, v40
	v_max_f32_e32 v41, 0, v41
	v_mul_f32_e32 v36, v36, v48
	v_mul_f32_e32 v37, v37, v48
	v_mul_f32_e32 v38, v38, v48
	v_mul_f32_e32 v39, v39, v48
	v_mul_f32_e32 v32, v32, v48
	v_mul_f32_e32 v33, v33, v48
	v_mul_f32_e32 v34, v34, v48
	v_mul_f32_e32 v35, v35, v48
	v_pk_mul_f32 v[44:45], v[44:45], v[44:45]
	v_pk_mul_f32 v[46:47], v[46:47], v[46:47]
	v_pk_mul_f32 v[40:41], v[40:41], v[40:41]
	v_max_f32_e32 v36, 0, v36
	v_max_f32_e32 v37, 0, v37
	v_max_f32_e32 v38, 0, v38
	v_max_f32_e32 v39, 0, v39
	v_max_f32_e32 v32, 0, v32
	v_max_f32_e32 v33, 0, v33
	v_max_f32_e32 v34, 0, v34
	v_max_f32_e32 v35, 0, v35
	v_cvt_pk_bf16_f32 v44, v44, v45
	v_cvt_pk_bf16_f32 v45, v46, v47
	v_cvt_pk_bf16_f32 v46, v40, v41
	v_or_b32_e32 v40, 0x1400, v152
	v_mov_b32_e32 v41, v153
	v_pk_mul_f32 v[36:37], v[36:37], v[36:37]
	v_pk_mul_f32 v[38:39], v[38:39], v[38:39]
	v_pk_mul_f32 v[32:33], v[32:33], v[32:33]
	v_pk_mul_f32 v[34:35], v[34:35], v[34:35]
	v_cvt_pk_bf16_f32 v36, v36, v37
	v_cvt_pk_bf16_f32 v37, v38, v39
	v_cvt_pk_bf16_f32 v38, v32, v33
	v_cvt_pk_bf16_f32 v39, v34, v35
	v_lshl_add_u64 v[32:33], v[114:115], 0, v[40:41]
	v_permlane16_swap_b32_e32 v36, v38
	v_permlane16_swap_b32_e32 v37, v39
	v_lshl_add_u64 v[32:33], v[32:33], 0, v[112:113]
	global_store_dwordx4 v[32:33], v[36:39], off nt
	v_or_b32_e32 v32, 0x20180, v118
	ds_read_b32 v32, v32
	v_mul_f32_e32 v42, v42, v48
	v_mul_f32_e32 v43, v43, v48
	v_max_f32_e32 v58, 0, v58
	v_max_f32_e32 v59, 0, v59
	s_waitcnt lgkmcnt(0)
; template <int MODE, int NSUB>
; __device__ __forceinline__ void epilogue(const Params& p, int layer, f32x4 (&acc)[4][NSUB], int tm, int tn, int g,
;                                          const float* s_rstd, const int tid_in) {
;     ...
;       for (int mp = 0; mp < 2; ++mp) {
;         bf16x4 pk[2];
; #pragma unroll
;         for (int h2 = 0; h2 < 2; ++h2) {
;           const int m = mp * 2 + h2;
;           float v[4];
; #pragma unroll
;           for (int j = 0; j < 4; ++j) {
;             float a = fmaxf(acc[m][n][j] * rs, 0.f);
;             v[j] = a * a;
;           }
;           pk[h2] = pack4(v[0], v[1], v[2], v[3]);
;         }
;         const int f = tm * 128 + wr * 64 + mp * 32 + woff;
;         __builtin_nontemporal_store(widen_pair(pk[0], pk[1]), reinterpret_cast<u32x4*>(p.hm + blk(t, f, 128)));
;       }
;     }
; __global__ void __launch_bounds__(NTHREADS) fwd_megakernel(Params p) {
;     ...
;           for (int id = rvid; id < 16 * CHUNK_TT; id += Greal) {
;             int ftb, ttl;
;             tile_decode_fb(id, 16, 4, ftb, ttl);
;             compute_rstd(p.part, 16, 1.0f / 1024.f, (chunk * CHUNK_TT + ttl) * 256, 256, s_rstd_b, tid_full);
;             f32x4 acc[4][8];
;             gemm_big<32>(acc, W + (long)ftb * 256 * 1024, 128 * 1024, p.xb + (long)(chunk * CHUNK_TT + ttl) * 256 * 1024, 128 * 1024, smem_all, tid_full);
;             const int ft = ftb * 2 + (widf >> 2);
;             epilogue<EPI_UP, 8>(p, l, acc, ft, ttl, 0, s_rstd_b, tid_e);
;             __syncthreads();
;           }
	v_mul_f32_e32 v28, v28, v32
	v_mul_f32_e32 v29, v29, v32
	v_mul_f32_e32 v30, v30, v32
	v_mul_f32_e32 v31, v31, v32
	v_mul_f32_e32 v24, v24, v32
	v_mul_f32_e32 v25, v25, v32
	v_max_f32_e32 v28, 0, v28
	v_max_f32_e32 v29, 0, v29
	v_max_f32_e32 v30, 0, v30
	v_max_f32_e32 v31, 0, v31
	v_max_f32_e32 v24, 0, v24
	v_max_f32_e32 v25, 0, v25
	v_mul_f32_e32 v20, v20, v32
	v_mul_f32_e32 v21, v21, v32
	v_mul_f32_e32 v22, v22, v32
	v_mul_f32_e32 v23, v23, v32
	v_mul_f32_e32 v16, v16, v32
	v_mul_f32_e32 v17, v17, v32
	v_mul_f32_e32 v18, v18, v32
	v_mul_f32_e32 v19, v19, v32
	v_pk_mul_f32 v[28:29], v[28:29], v[28:29]
	v_pk_mul_f32 v[30:31], v[30:31], v[30:31]
	v_pk_mul_f32 v[24:25], v[24:25], v[24:25]
	v_max_f32_e32 v20, 0, v20
	v_max_f32_e32 v21, 0, v21
	v_max_f32_e32 v22, 0, v22
	v_max_f32_e32 v23, 0, v23
	v_max_f32_e32 v16, 0, v16
	v_max_f32_e32 v17, 0, v17
	v_max_f32_e32 v18, 0, v18
	v_max_f32_e32 v19, 0, v19
	v_cvt_pk_bf16_f32 v28, v28, v29
	v_cvt_pk_bf16_f32 v29, v30, v31
	v_cvt_pk_bf16_f32 v30, v24, v25
	v_or_b32_e32 v24, 0x1800, v152
	v_mov_b32_e32 v25, v153
	v_pk_mul_f32 v[20:21], v[20:21], v[20:21]
	v_pk_mul_f32 v[22:23], v[22:23], v[22:23]
	v_pk_mul_f32 v[16:17], v[16:17], v[16:17]
	v_pk_mul_f32 v[18:19], v[18:19], v[18:19]
	v_cvt_pk_bf16_f32 v20, v20, v21
	v_cvt_pk_bf16_f32 v21, v22, v23
	v_cvt_pk_bf16_f32 v22, v16, v17
	v_cvt_pk_bf16_f32 v23, v18, v19
	v_lshl_add_u64 v[16:17], v[114:115], 0, v[24:25]
	v_permlane16_swap_b32_e32 v20, v22
	v_permlane16_swap_b32_e32 v21, v23
	v_lshl_add_u64 v[16:17], v[16:17], 0, v[112:113]
	global_store_dwordx4 v[16:17], v[20:23], off nt
	v_or_b32_e32 v16, 0x201c0, v118
	ds_read_b32 v16, v16
	v_mul_f32_e32 v26, v26, v32
	v_mul_f32_e32 v27, v27, v32
	v_max_f32_e32 v42, 0, v42
	v_max_f32_e32 v43, 0, v43
	s_waitcnt lgkmcnt(0)
	v_mul_f32_e32 v12, v12, v16
	v_mul_f32_e32 v13, v13, v16
	v_mul_f32_e32 v14, v14, v16
	v_mul_f32_e32 v15, v15, v16
	v_mul_f32_e32 v8, v8, v16
	v_mul_f32_e32 v9, v9, v16
	v_mul_f32_e32 v10, v10, v16
	v_mul_f32_e32 v11, v11, v16
	v_mul_f32_e32 v4, v4, v16
	v_mul_f32_e32 v5, v5, v16
	v_mul_f32_e32 v6, v6, v16
	v_mul_f32_e32 v7, v7, v16
	v_mul_f32_e32 v0, v0, v16
	v_mul_f32_e32 v1, v1, v16
	v_mul_f32_e32 v2, v2, v16
	v_mul_f32_e32 v3, v3, v16
	v_max_f32_e32 v26, 0, v26
	v_max_f32_e32 v27, 0, v27
	v_max_f32_e32 v12, 0, v12
	v_max_f32_e32 v13, 0, v13
	v_max_f32_e32 v14, 0, v14
	v_max_f32_e32 v15, 0, v15
	v_max_f32_e32 v8, 0, v8
	v_max_f32_e32 v9, 0, v9
	v_max_f32_e32 v10, 0, v10
	v_max_f32_e32 v11, 0, v11
	v_max_f32_e32 v4, 0, v4
	v_max_f32_e32 v5, 0, v5
	v_max_f32_e32 v6, 0, v6
	v_max_f32_e32 v7, 0, v7
	v_max_f32_e32 v0, 0, v0
	v_max_f32_e32 v1, 0, v1
	v_max_f32_e32 v2, 0, v2
	v_max_f32_e32 v3, 0, v3
	v_cvt_pk_bf16_f32 v122, v122, v123
	v_cvt_pk_bf16_f32 v123, v124, v125
	v_lshl_add_u64 v[124:125], v[114:115], 0, v[152:153]
	v_pk_mul_f32 v[106:107], v[106:107], v[106:107]
	v_pk_mul_f32 v[90:91], v[90:91], v[90:91]
	v_pk_mul_f32 v[74:75], v[74:75], v[74:75]
	v_pk_mul_f32 v[58:59], v[58:59], v[58:59]
	v_pk_mul_f32 v[42:43], v[42:43], v[42:43]
	v_pk_mul_f32 v[26:27], v[26:27], v[26:27]
	v_pk_mul_f32 v[12:13], v[12:13], v[12:13]
	v_pk_mul_f32 v[14:15], v[14:15], v[14:15]
	v_pk_mul_f32 v[8:9], v[8:9], v[8:9]
	v_pk_mul_f32 v[10:11], v[10:11], v[10:11]
	v_or_b32_e32 v152, 0x1c00, v152
	v_pk_mul_f32 v[4:5], v[4:5], v[4:5]
	v_pk_mul_f32 v[6:7], v[6:7], v[6:7]
	v_pk_mul_f32 v[0:1], v[0:1], v[0:1]
	v_pk_mul_f32 v[2:3], v[2:3], v[2:3]
	v_cvt_pk_bf16_f32 v111, v106, v107
	v_lshl_add_u64 v[106:107], v[116:117], 0, v[104:105]
	v_cvt_pk_bf16_f32 v95, v90, v91
	v_lshl_add_u64 v[90:91], v[116:117], 0, v[88:89]
	v_cvt_pk_bf16_f32 v79, v74, v75
	v_lshl_add_u64 v[74:75], v[116:117], 0, v[72:73]
	v_cvt_pk_bf16_f32 v63, v58, v59
	v_lshl_add_u64 v[58:59], v[116:117], 0, v[56:57]
	v_cvt_pk_bf16_f32 v47, v42, v43
	v_lshl_add_u64 v[42:43], v[116:117], 0, v[40:41]
	v_cvt_pk_bf16_f32 v31, v26, v27
	v_lshl_add_u64 v[26:27], v[116:117], 0, v[24:25]
	v_cvt_pk_bf16_f32 v12, v12, v13
	v_cvt_pk_bf16_f32 v13, v14, v15
	v_cvt_pk_bf16_f32 v14, v8, v9
	v_cvt_pk_bf16_f32 v15, v10, v11
	v_lshl_add_u64 v[8:9], v[116:117], 0, v[152:153]
	v_cvt_pk_bf16_f32 v4, v4, v5
	v_cvt_pk_bf16_f32 v5, v6, v7
	v_cvt_pk_bf16_f32 v6, v0, v1
	v_cvt_pk_bf16_f32 v7, v2, v3
	v_lshl_add_u64 v[0:1], v[114:115], 0, v[152:153]
	s_add_i32 s9, s9, s26
	v_permlane16_swap_b32_e32 v120, v122
	v_permlane16_swap_b32_e32 v121, v123
	v_lshl_add_u64 v[124:125], v[124:125], 0, v[112:113]
	v_permlane16_swap_b32_e32 v108, v110
	v_permlane16_swap_b32_e32 v109, v111
	v_lshl_add_u64 v[106:107], v[106:107], 0, v[112:113]
	v_permlane16_swap_b32_e32 v92, v94
	v_permlane16_swap_b32_e32 v93, v95
	v_lshl_add_u64 v[90:91], v[90:91], 0, v[112:113]
	v_permlane16_swap_b32_e32 v76, v78
	v_permlane16_swap_b32_e32 v77, v79
	v_lshl_add_u64 v[74:75], v[74:75], 0, v[112:113]
	v_permlane16_swap_b32_e32 v60, v62
	v_permlane16_swap_b32_e32 v61, v63
	v_lshl_add_u64 v[58:59], v[58:59], 0, v[112:113]
	v_permlane16_swap_b32_e32 v44, v46
	v_permlane16_swap_b32_e32 v45, v47
	v_lshl_add_u64 v[42:43], v[42:43], 0, v[112:113]
	v_permlane16_swap_b32_e32 v28, v30
	v_permlane16_swap_b32_e32 v29, v31
	v_lshl_add_u64 v[26:27], v[26:27], 0, v[112:113]
	v_permlane16_swap_b32_e32 v12, v14
	v_permlane16_swap_b32_e32 v13, v15
	v_lshl_add_u64 v[8:9], v[8:9], 0, v[112:113]
	v_permlane16_swap_b32_e32 v4, v6
	v_permlane16_swap_b32_e32 v5, v7
	v_lshl_add_u64 v[0:1], v[0:1], 0, v[112:113]
	s_cmpk_gt_i32 s9, 0x13ff
	v_readlane_b32 s65, v252, 5
	v_readlane_b32 s66, v252, 6
	v_readlane_b32 s67, v252, 7
	v_readlane_b32 s68, v252, 8
	v_readlane_b32 s69, v252, 9
	v_readlane_b32 s70, v252, 10
	v_readlane_b32 s71, v252, 11
	v_readlane_b32 s72, v252, 12
	v_readlane_b32 s73, v252, 13
	v_readlane_b32 s74, v252, 14
	v_readlane_b32 s75, v252, 15
	v_readlane_b32 s76, v252, 16
	v_readlane_b32 s77, v252, 17
	global_store_dwordx4 v[124:125], v[120:123], off nt
	global_store_dwordx4 v[106:107], v[108:111], off nt
	global_store_dwordx4 v[90:91], v[92:95], off nt
	global_store_dwordx4 v[74:75], v[76:79], off nt
	global_store_dwordx4 v[58:59], v[60:63], off nt
	global_store_dwordx4 v[42:43], v[44:47], off nt
	global_store_dwordx4 v[26:27], v[28:31], off nt
	global_store_dwordx4 v[8:9], v[12:15], off nt
	global_store_dwordx4 v[0:1], v[4:7], off nt
	s_barrier
	s_cbranch_scc0 .LBB0_287

; template <int NK, bool BNT = false> ...
;     ...
;   auto kstep = [&](int T, int cur, int nxt, bool do_stage) {
;     const unsigned char* sa = smem + cur * BIG_STAGE;
;     bf16x8 af[4], bfr[4];
; #pragma unroll
;     for (int m = 0; m < 4; ++m) af[m] = *reinterpret_cast<const bf16x8*>(sa + aoff + m * 1024);
; #pragma unroll
;     for (int n = 0; n < 4; ++n) bfr[n] = *reinterpret_cast<const bf16x8*>(sa + boff + n * 1024);
;     __builtin_amdgcn_sched_barrier(0);
;     if (do_stage) stage(T + 3, nxt);
; #pragma unroll
;     for (int m = 0; m < 4; ++m)
; #pragma unroll
;       for (int n = 0; n < 4; ++n) acc[m][n] = __builtin_amdgcn_mfma_f32_16x16x32_bf16(af[m], bfr[n], acc[m][n], 0, 0, 0);
;     if (do_stage) {
; #pragma unroll
;       for (int q = 0; q < NG; ++q) {
;         __builtin_amdgcn_sched_group_barrier(0x008, 3, 0);
;         __builtin_amdgcn_sched_group_barrier(0x010, 1, 0);
;       }
;       __builtin_amdgcn_sched_group_barrier(0x008, 16 - 3 * NG, 0);
;     }
;     __builtin_amdgcn_sched_barrier(0);
; #pragma unroll
;     for (int n = 0; n < 4; ++n) bfr[n] = *reinterpret_cast<const bf16x8*>(sa + boff + (4 + n) * 1024);
; #pragma unroll
;     for (int m = 0; m < 4; ++m)
; #pragma unroll
;       for (int n = 0; n < 4; ++n)
;         acc[m][4 + n] = __builtin_amdgcn_mfma_f32_16x16x32_bf16(af[m], bfr[n], acc[m][4 + n], 0, 0, 0);
;     __builtin_amdgcn_sched_barrier(0);
;   };
;     ...
;   stage(0, 0);
;   stage(1, 1);
;   stage(2, 2);
;   for (int it = 0; it < NK / 4 - 1; ++it) {
;     const int t = it * 4;
;     BIG_SYNC(2 * NG); kstep(t, 0, 3, true);
;     BIG_SYNC(2 * NG); kstep(t + 1, 1, 0, true);
;     BIG_SYNC(2 * NG); kstep(t + 2, 2, 1, true);
;     BIG_SYNC(2 * NG); kstep(t + 3, 3, 2, true);
;   }
; __global__ void __launch_bounds__(NTHREADS) fwd_megakernel(Params p) {
;     ...
;           for (int id = rvid; id < 4 * 320; id += Greal) {
;             int ftb, ttl;
;             tile_decode(id, 4, ftb, ttl);
;             compute_rstd(p.part, 16, 1.0f / 1024.f, ttl * 256, 256, s_rstd_b, tid_full);
;             f32x4 acc[4][8];
;             gemm_big<32>(acc, W + (long)ftb * 256 * 1024, 128 * 1024, p.xb + (long)ttl * 256 * 1024, 128 * 1024, smem_all, tid_full);
.Lmy_g1_rsdone:
	s_or_b64 exec, exec, s[100:101]
	s_waitcnt vmcnt(8)
	s_barrier
	v_add_u32_e32 v167, 0x10000, v148
	v_or_b32_e32 v168, 0x10000, v150
	v_add_u32_e32 v176, 0x18000, v148
	v_or_b32_e32 v179, 0x18000, v150
	v_add_u32_e32 v210, 0x10000, v148
	v_or_b32_e32 v211, 0x10000, v150
	v_add_u32_e32 v212, 0x18000, v148
	v_or_b32_e32 v213, 0x18000, v150
	ds_read_b128 v[216:219], v148
	ds_read_b128 v[220:223], v148 offset:1024
	ds_read_b128 v[224:227], v148 offset:2048
	ds_read_b128 v[228:231], v148 offset:3072
	ds_read_b128 v[232:235], v149 offset:16384
	ds_read_b128 v[236:239], v149 offset:17408
	ds_read_b128 v[240:243], v149 offset:18432
	ds_read_b128 v[244:247], v149 offset:19456
.LBB0_302:
	s_waitcnt lgkmcnt(3)
	v_mfma_f32_16x16x32_bf16 v[56:59], v[216:219], v[232:235], v[56:59]
	v_mfma_f32_16x16x32_bf16 v[100:103], v[220:223], v[232:235], v[100:103]
	v_mfma_f32_16x16x32_bf16 v[104:107], v[224:227], v[232:235], v[104:107]
	s_waitcnt vmcnt(4)
	s_barrier
	v_add_u32_e32 v163, 0x18000, v147
	v_lshl_add_u64 v[144:145], v[138:139], 0, s[6:7]
	v_mfma_f32_16x16x32_bf16 v[112:115], v[228:231], v[232:235], v[112:115]
	v_readfirstlane_b32 s5, v163
	v_lshl_add_u64 v[164:165], v[144:145], 0, s[60:61]
	s_waitcnt lgkmcnt(2)
	v_mfma_f32_16x16x32_bf16 v[64:67], v[216:219], v[236:239], v[64:67]
	ds_read_b128 v[232:235], v149 offset:20480
	v_mfma_f32_16x16x32_bf16 v[80:83], v[220:223], v[236:239], v[80:83]
	s_mov_b32 m0, s5
	v_lshl_add_u64 v[142:143], v[140:141], 0, s[6:7]
	v_mfma_f32_16x16x32_bf16 v[96:99], v[224:227], v[236:239], v[96:99]
	v_lshl_add_u64 v[168:169], v[144:145], 0, s[80:81]
	v_mfma_f32_16x16x32_bf16 v[116:119], v[228:231], v[236:239], v[116:119]
	v_lshl_add_u64 v[166:167], v[142:143], 0, s[60:61]
	s_waitcnt lgkmcnt(2)
	v_mfma_f32_16x16x32_bf16 v[52:55], v[216:219], v[240:243], v[52:55]
	ds_read_b128 v[236:239], v149 offset:21504
	v_mfma_f32_16x16x32_bf16 v[68:71], v[220:223], v[240:243], v[68:71]
	global_load_lds_dwordx4 v[164:165], off
	v_mfma_f32_16x16x32_bf16 v[108:111], v[224:227], v[240:243], v[108:111]
	v_add_u32_e32 v164, 0x1a000, v147
	v_mfma_f32_16x16x32_bf16 v[120:123], v[228:231], v[240:243], v[120:123]
	v_add_u32_e32 v165, 0x1c000, v147
	s_waitcnt lgkmcnt(2)
	v_mfma_f32_16x16x32_bf16 v[48:51], v[216:219], v[244:247], v[48:51]
	ds_read_b128 v[240:243], v149 offset:22528
	v_mfma_f32_16x16x32_bf16 v[72:75], v[220:223], v[244:247], v[72:75]
	v_readfirstlane_b32 s5, v164
	v_mfma_f32_16x16x32_bf16 v[88:91], v[224:227], v[244:247], v[88:91]
	s_mov_b32 m0, s5
	v_mfma_f32_16x16x32_bf16 v[124:127], v[228:231], v[244:247], v[124:127]
	v_readfirstlane_b32 s5, v165
	s_waitcnt lgkmcnt(2)
	v_mfma_f32_16x16x32_bf16 v[0:3], v[216:219], v[232:235], v[0:3]
	ds_read_b128 v[244:247], v149 offset:23552
	v_mfma_f32_16x16x32_bf16 v[16:19], v[220:223], v[232:235], v[16:19]
	ds_read_b128 v[186:189], v148 offset:32768
	v_mfma_f32_16x16x32_bf16 v[32:35], v[224:227], v[232:235], v[32:35]
	ds_read_b128 v[190:193], v148 offset:33792
	v_mfma_f32_16x16x32_bf16 v[60:63], v[228:231], v[232:235], v[60:63]
	ds_read_b128 v[194:197], v148 offset:34816
	s_waitcnt lgkmcnt(5)
	v_mfma_f32_16x16x32_bf16 v[4:7], v[216:219], v[236:239], v[4:7]
	ds_read_b128 v[202:205], v148 offset:35840
	ds_read_b128 v[232:235], v149 offset:49152
	v_mfma_f32_16x16x32_bf16 v[20:23], v[220:223], v[236:239], v[20:23]
	global_load_lds_dwordx4 v[168:169], off
	v_mfma_f32_16x16x32_bf16 v[36:39], v[224:227], v[236:239], v[36:39]
	s_mov_b32 m0, s5
	v_mfma_f32_16x16x32_bf16 v[76:79], v[228:231], v[236:239], v[76:79]
	v_lshl_add_u64 v[168:169], v[142:143], 0, s[80:81]
	s_waitcnt lgkmcnt(6)
	v_mfma_f32_16x16x32_bf16 v[8:11], v[216:219], v[240:243], v[8:11]
	ds_read_b128 v[236:239], v149 offset:50176
	v_mfma_f32_16x16x32_bf16 v[24:27], v[220:223], v[240:243], v[24:27]
	global_load_lds_dwordx4 v[166:167], off
	v_mfma_f32_16x16x32_bf16 v[40:43], v[224:227], v[240:243], v[40:43]
	v_add_u32_e32 v166, 0x1e000, v147
	v_mfma_f32_16x16x32_bf16 v[84:87], v[228:231], v[240:243], v[84:87]
	v_readfirstlane_b32 s5, v166
	s_waitcnt lgkmcnt(6)
	v_mfma_f32_16x16x32_bf16 v[12:15], v[216:219], v[244:247], v[12:15]
	ds_read_b128 v[240:243], v149 offset:51200
	v_mfma_f32_16x16x32_bf16 v[28:31], v[220:223], v[244:247], v[28:31]
	s_mov_b32 m0, s5
	v_mfma_f32_16x16x32_bf16 v[44:47], v[224:227], v[244:247], v[44:47]
	global_load_lds_dwordx4 v[168:169], off
	v_mfma_f32_16x16x32_bf16 v[92:95], v[228:231], v[244:247], v[92:95]
	ds_read_b128 v[244:247], v149 offset:52224
	s_waitcnt lgkmcnt(3)
	v_mfma_f32_16x16x32_bf16 v[56:59], v[186:189], v[232:235], v[56:59]
	v_mfma_f32_16x16x32_bf16 v[100:103], v[190:193], v[232:235], v[100:103]
	v_mfma_f32_16x16x32_bf16 v[104:107], v[194:197], v[232:235], v[104:107]
	s_waitcnt vmcnt(4)
	s_barrier
; template <int NK, bool BNT = false> ...
;     ...
;   auto kstep = [&](int T, int cur, int nxt, bool do_stage) {
;     const unsigned char* sa = smem + cur * BIG_STAGE;
;     bf16x8 af[4], bfr[4];
; #pragma unroll
;     for (int m = 0; m < 4; ++m) af[m] = *reinterpret_cast<const bf16x8*>(sa + aoff + m * 1024);
; #pragma unroll
;     for (int n = 0; n < 4; ++n) bfr[n] = *reinterpret_cast<const bf16x8*>(sa + boff + n * 1024);
;     __builtin_amdgcn_sched_barrier(0);
;     if (do_stage) stage(T + 3, nxt);
; #pragma unroll
;     for (int m = 0; m < 4; ++m)
; #pragma unroll
;       for (int n = 0; n < 4; ++n) acc[m][n] = __builtin_amdgcn_mfma_f32_16x16x32_bf16(af[m], bfr[n], acc[m][n], 0, 0, 0);
;     if (do_stage) {
; #pragma unroll
;       for (int q = 0; q < NG; ++q) {
;         __builtin_amdgcn_sched_group_barrier(0x008, 3, 0);
;         __builtin_amdgcn_sched_group_barrier(0x010, 1, 0);
;       }
;       __builtin_amdgcn_sched_group_barrier(0x008, 16 - 3 * NG, 0);
;     }
;     __builtin_amdgcn_sched_barrier(0);
; #pragma unroll
;     for (int n = 0; n < 4; ++n) bfr[n] = *reinterpret_cast<const bf16x8*>(sa + boff + (4 + n) * 1024);
; #pragma unroll
;     for (int m = 0; m < 4; ++m)
; #pragma unroll
;       for (int n = 0; n < 4; ++n)
;         acc[m][4 + n] = __builtin_amdgcn_mfma_f32_16x16x32_bf16(af[m], bfr[n], acc[m][4 + n], 0, 0, 0);
;     __builtin_amdgcn_sched_barrier(0);
	v_readfirstlane_b32 s5, v147
	v_mfma_f32_16x16x32_bf16 v[112:115], v[202:205], v[232:235], v[112:115]
	v_lshl_add_u64 v[168:169], v[144:145], 0, s[62:63]
	s_waitcnt lgkmcnt(2)
	v_mfma_f32_16x16x32_bf16 v[64:67], v[186:189], v[236:239], v[64:67]
	ds_read_b128 v[232:235], v149 offset:53248
	v_mfma_f32_16x16x32_bf16 v[80:83], v[190:193], v[236:239], v[80:83]
	s_mov_b32 m0, s5
	v_mfma_f32_16x16x32_bf16 v[96:99], v[194:197], v[236:239], v[96:99]
	v_readfirstlane_b32 s5, v146
	v_mfma_f32_16x16x32_bf16 v[116:119], v[202:205], v[236:239], v[116:119]
	v_lshl_add_u64 v[182:183], v[142:143], 0, s[62:63]
	s_waitcnt lgkmcnt(2)
	v_mfma_f32_16x16x32_bf16 v[52:55], v[186:189], v[240:243], v[52:55]
	ds_read_b128 v[236:239], v149 offset:54272
	v_mfma_f32_16x16x32_bf16 v[68:71], v[190:193], v[240:243], v[68:71]
	global_load_lds_dwordx4 v[168:169], off
	v_mfma_f32_16x16x32_bf16 v[108:111], v[194:197], v[240:243], v[108:111]
	v_lshl_add_u64 v[168:169], v[144:145], 0, s[0:1]
	v_mfma_f32_16x16x32_bf16 v[120:123], v[202:205], v[240:243], v[120:123]
	s_mov_b32 m0, s5
	s_waitcnt lgkmcnt(2)
	v_mfma_f32_16x16x32_bf16 v[48:51], v[186:189], v[244:247], v[48:51]
	ds_read_b128 v[240:243], v149 offset:55296
	v_mfma_f32_16x16x32_bf16 v[72:75], v[190:193], v[244:247], v[72:75]
	v_readfirstlane_b32 s5, v152
	v_mfma_f32_16x16x32_bf16 v[88:91], v[194:197], v[244:247], v[88:91]
	global_load_lds_dwordx4 v[168:169], off
	v_mfma_f32_16x16x32_bf16 v[124:127], v[202:205], v[244:247], v[124:127]
	s_mov_b32 m0, s5
	s_waitcnt lgkmcnt(2)
	v_mfma_f32_16x16x32_bf16 v[0:3], v[186:189], v[232:235], v[0:3]
	ds_read_b128 v[244:247], v149 offset:56320
	v_mfma_f32_16x16x32_bf16 v[16:19], v[190:193], v[232:235], v[16:19]
	ds_read_b128 v[216:219], v210
	v_mfma_f32_16x16x32_bf16 v[32:35], v[194:197], v[232:235], v[32:35]
	ds_read_b128 v[220:223], v210 offset:1024
	v_mfma_f32_16x16x32_bf16 v[60:63], v[202:205], v[232:235], v[60:63]
	ds_read_b128 v[224:227], v210 offset:2048
	s_waitcnt lgkmcnt(5)
	v_mfma_f32_16x16x32_bf16 v[4:7], v[186:189], v[236:239], v[4:7]
	ds_read_b128 v[228:231], v210 offset:3072
	ds_read_b128 v[232:235], v211
	v_mfma_f32_16x16x32_bf16 v[20:23], v[190:193], v[236:239], v[20:23]
	v_readfirstlane_b32 s5, v154
	v_mfma_f32_16x16x32_bf16 v[36:39], v[194:197], v[236:239], v[36:39]
	v_lshl_add_u64 v[168:169], v[142:143], 0, s[0:1]
	v_mfma_f32_16x16x32_bf16 v[76:79], v[202:205], v[236:239], v[76:79]
	global_load_lds_dwordx4 v[182:183], off
	s_waitcnt lgkmcnt(6)
	v_mfma_f32_16x16x32_bf16 v[8:11], v[186:189], v[240:243], v[8:11]
	ds_read_b128 v[236:239], v211 offset:1024
	v_mfma_f32_16x16x32_bf16 v[24:27], v[190:193], v[240:243], v[24:27]
	s_mov_b32 m0, s5
	v_mfma_f32_16x16x32_bf16 v[40:43], v[194:197], v[240:243], v[40:43]
	global_load_lds_dwordx4 v[168:169], off
	v_mfma_f32_16x16x32_bf16 v[84:87], v[202:205], v[240:243], v[84:87]
	s_waitcnt lgkmcnt(6)
	v_mfma_f32_16x16x32_bf16 v[12:15], v[186:189], v[244:247], v[12:15]
	ds_read_b128 v[240:243], v211 offset:2048
	v_mfma_f32_16x16x32_bf16 v[28:31], v[190:193], v[244:247], v[28:31]
	v_mfma_f32_16x16x32_bf16 v[44:47], v[194:197], v[244:247], v[44:47]
	v_mfma_f32_16x16x32_bf16 v[92:95], v[202:205], v[244:247], v[92:95]
	ds_read_b128 v[244:247], v211 offset:3072
	s_waitcnt lgkmcnt(3)
	v_mfma_f32_16x16x32_bf16 v[56:59], v[216:219], v[232:235], v[56:59]
	v_mfma_f32_16x16x32_bf16 v[100:103], v[220:223], v[232:235], v[100:103]
	v_mfma_f32_16x16x32_bf16 v[104:107], v[224:227], v[232:235], v[104:107]
	s_waitcnt vmcnt(4)
	s_barrier
	v_add_u32_e32 v167, 0x10000, v148
	v_or_b32_e32 v168, 0x10000, v150
	v_mfma_f32_16x16x32_bf16 v[112:115], v[228:231], v[232:235], v[112:115]
	v_add_u32_e32 v169, 0x10400, v150
	v_add_u32_e32 v170, 0x10800, v150
	s_waitcnt lgkmcnt(2)
	v_mfma_f32_16x16x32_bf16 v[64:67], v[216:219], v[236:239], v[64:67]
	ds_read_b128 v[232:235], v211 offset:4096
	v_mfma_f32_16x16x32_bf16 v[80:83], v[220:223], v[236:239], v[80:83]
	v_add_u32_e32 v172, 0x10c00, v150
	v_mfma_f32_16x16x32_bf16 v[96:99], v[224:227], v[236:239], v[96:99]
	v_readfirstlane_b32 s5, v155
	v_mfma_f32_16x16x32_bf16 v[116:119], v[228:231], v[236:239], v[116:119]
	v_lshl_add_u64 v[174:175], v[144:145], 0, s[2:3]
	s_waitcnt lgkmcnt(2)
	v_mfma_f32_16x16x32_bf16 v[52:55], v[216:219], v[240:243], v[52:55]
	ds_read_b128 v[236:239], v211 offset:5120
	v_mfma_f32_16x16x32_bf16 v[68:71], v[220:223], v[240:243], v[68:71]
	s_mov_b32 m0, s5
	v_mfma_f32_16x16x32_bf16 v[108:111], v[224:227], v[240:243], v[108:111]
	v_readfirstlane_b32 s5, v156
	v_mfma_f32_16x16x32_bf16 v[120:123], v[228:231], v[240:243], v[120:123]
	v_lshl_add_u64 v[178:179], v[142:143], 0, s[2:3]
	s_waitcnt lgkmcnt(2)
	v_mfma_f32_16x16x32_bf16 v[48:51], v[216:219], v[244:247], v[48:51]
	ds_read_b128 v[240:243], v211 offset:6144
	v_mfma_f32_16x16x32_bf16 v[72:75], v[220:223], v[244:247], v[72:75]
	global_load_lds_dwordx4 v[174:175], off
	v_mfma_f32_16x16x32_bf16 v[88:91], v[224:227], v[244:247], v[88:91]
	v_lshl_add_u64 v[174:175], v[144:145], 0, s[52:53]
	v_mfma_f32_16x16x32_bf16 v[124:127], v[228:231], v[244:247], v[124:127]
	s_mov_b32 m0, s5
	s_waitcnt lgkmcnt(2)
	v_mfma_f32_16x16x32_bf16 v[0:3], v[216:219], v[232:235], v[0:3]
	ds_read_b128 v[244:247], v211 offset:7168
	v_mfma_f32_16x16x32_bf16 v[16:19], v[220:223], v[232:235], v[16:19]
	ds_read_b128 v[186:189], v210 offset:32768
	v_mfma_f32_16x16x32_bf16 v[32:35], v[224:227], v[232:235], v[32:35]
	ds_read_b128 v[190:193], v210 offset:33792
	v_mfma_f32_16x16x32_bf16 v[60:63], v[228:231], v[232:235], v[60:63]
	ds_read_b128 v[194:197], v210 offset:34816
	s_waitcnt lgkmcnt(5)
; #define BIG_SYNC(N)                                              \
;   asm volatile("s_waitcnt vmcnt(%0)" ::"n"(N) : "memory");       \
;   __builtin_amdgcn_s_barrier();                                  \
;   asm volatile("" ::: "memory");                                 \
;   __builtin_amdgcn_sched_barrier(0);
; template <int NK, bool BNT = false> ...
;     ...
;   auto kstep = [&](int T, int cur, int nxt, bool do_stage) {
;     const unsigned char* sa = smem + cur * BIG_STAGE;
;     bf16x8 af[4], bfr[4];
; #pragma unroll
;     for (int m = 0; m < 4; ++m) af[m] = *reinterpret_cast<const bf16x8*>(sa + aoff + m * 1024);
; #pragma unroll
;     for (int n = 0; n < 4; ++n) bfr[n] = *reinterpret_cast<const bf16x8*>(sa + boff + n * 1024);
;     __builtin_amdgcn_sched_barrier(0);
;     if (do_stage) stage(T + 3, nxt);
; #pragma unroll
;     for (int m = 0; m < 4; ++m)
; #pragma unroll
;       for (int n = 0; n < 4; ++n) acc[m][n] = __builtin_amdgcn_mfma_f32_16x16x32_bf16(af[m], bfr[n], acc[m][n], 0, 0, 0);
;     if (do_stage) {
; #pragma unroll
;       for (int q = 0; q < NG; ++q) {
;         __builtin_amdgcn_sched_group_barrier(0x008, 3, 0);
;         __builtin_amdgcn_sched_group_barrier(0x010, 1, 0);
;       }
;       __builtin_amdgcn_sched_group_barrier(0x008, 16 - 3 * NG, 0);
;     }
;     __builtin_amdgcn_sched_barrier(0);
; #pragma unroll
;     for (int n = 0; n < 4; ++n) bfr[n] = *reinterpret_cast<const bf16x8*>(sa + boff + (4 + n) * 1024);
; #pragma unroll
;     for (int m = 0; m < 4; ++m)
; #pragma unroll
;       for (int n = 0; n < 4; ++n)
;         acc[m][4 + n] = __builtin_amdgcn_mfma_f32_16x16x32_bf16(af[m], bfr[n], acc[m][4 + n], 0, 0, 0);
;     __builtin_amdgcn_sched_barrier(0);
;   };
;     ...
;   stage(0, 0);
;   stage(1, 1);
;   stage(2, 2);
;   for (int it = 0; it < NK / 4 - 1; ++it) {
;     const int t = it * 4;
;     BIG_SYNC(2 * NG); kstep(t, 0, 3, true);
;     BIG_SYNC(2 * NG); kstep(t + 1, 1, 0, true);
;     BIG_SYNC(2 * NG); kstep(t + 2, 2, 1, true);
;     BIG_SYNC(2 * NG); kstep(t + 3, 3, 2, true);
;   }
	v_mfma_f32_16x16x32_bf16 v[4:7], v[216:219], v[236:239], v[4:7]
	ds_read_b128 v[202:205], v210 offset:35840
	ds_read_b128 v[232:235], v211 offset:32768
	v_mfma_f32_16x16x32_bf16 v[20:23], v[220:223], v[236:239], v[20:23]
	v_readfirstlane_b32 s5, v157
	v_mfma_f32_16x16x32_bf16 v[36:39], v[224:227], v[236:239], v[36:39]
	global_load_lds_dwordx4 v[174:175], off
	v_mfma_f32_16x16x32_bf16 v[76:79], v[228:231], v[236:239], v[76:79]
	s_mov_b32 m0, s5
	s_waitcnt lgkmcnt(6)
	v_mfma_f32_16x16x32_bf16 v[8:11], v[216:219], v[240:243], v[8:11]
	ds_read_b128 v[236:239], v211 offset:33792
	v_mfma_f32_16x16x32_bf16 v[24:27], v[220:223], v[240:243], v[24:27]
	v_readfirstlane_b32 s5, v158
	v_mfma_f32_16x16x32_bf16 v[40:43], v[224:227], v[240:243], v[40:43]
	v_lshl_add_u64 v[174:175], v[142:143], 0, s[52:53]
	v_mfma_f32_16x16x32_bf16 v[84:87], v[228:231], v[240:243], v[84:87]
	global_load_lds_dwordx4 v[178:179], off
	s_waitcnt lgkmcnt(6)
	v_mfma_f32_16x16x32_bf16 v[12:15], v[216:219], v[244:247], v[12:15]
	ds_read_b128 v[240:243], v211 offset:34816
	v_mfma_f32_16x16x32_bf16 v[28:31], v[220:223], v[244:247], v[28:31]
	s_mov_b32 m0, s5
	v_mfma_f32_16x16x32_bf16 v[44:47], v[224:227], v[244:247], v[44:47]
	global_load_lds_dwordx4 v[174:175], off
	v_mfma_f32_16x16x32_bf16 v[92:95], v[228:231], v[244:247], v[92:95]
	ds_read_b128 v[244:247], v211 offset:35840
	v_add_u32_e32 v173, 0x11000, v150
	v_add_u32_e32 v174, 0x11400, v150
	v_add_u32_e32 v175, 0x11800, v150
	v_add_u32_e32 v178, 0x11c00, v150
	s_waitcnt lgkmcnt(3)
	v_mfma_f32_16x16x32_bf16 v[56:59], v[186:189], v[232:235], v[56:59]
	v_mfma_f32_16x16x32_bf16 v[100:103], v[190:193], v[232:235], v[100:103]
	v_mfma_f32_16x16x32_bf16 v[104:107], v[194:197], v[232:235], v[104:107]
	s_waitcnt vmcnt(4)
	s_barrier
	v_add_u32_e32 v176, 0x18000, v148
	v_or_b32_e32 v179, 0x18000, v150
	v_mfma_f32_16x16x32_bf16 v[112:115], v[202:205], v[232:235], v[112:115]
	v_add_u32_e32 v180, 0x18400, v150
	v_add_u32_e32 v181, 0x18800, v150
	s_waitcnt lgkmcnt(2)
	v_mfma_f32_16x16x32_bf16 v[64:67], v[186:189], v[236:239], v[64:67]
	ds_read_b128 v[232:235], v211 offset:36864
	v_mfma_f32_16x16x32_bf16 v[80:83], v[190:193], v[236:239], v[80:83]
	v_add_u32_e32 v182, 0x18c00, v150
	v_mfma_f32_16x16x32_bf16 v[96:99], v[194:197], v[236:239], v[96:99]
	v_readfirstlane_b32 s5, v159
	v_mfma_f32_16x16x32_bf16 v[116:119], v[202:205], v[236:239], v[116:119]
	v_lshl_add_u64 v[248:249], v[144:145], 0, s[54:55]
	s_waitcnt lgkmcnt(2)
	v_mfma_f32_16x16x32_bf16 v[52:55], v[186:189], v[240:243], v[52:55]
	ds_read_b128 v[236:239], v211 offset:37888
	v_mfma_f32_16x16x32_bf16 v[68:71], v[190:193], v[240:243], v[68:71]
	s_mov_b32 m0, s5
	v_mfma_f32_16x16x32_bf16 v[108:111], v[194:197], v[240:243], v[108:111]
	v_readfirstlane_b32 s5, v160
	v_mfma_f32_16x16x32_bf16 v[120:123], v[202:205], v[240:243], v[120:123]
	v_lshl_add_u64 v[144:145], v[144:145], 0, s[56:57]
	s_waitcnt lgkmcnt(2)
	v_mfma_f32_16x16x32_bf16 v[48:51], v[186:189], v[244:247], v[48:51]
	ds_read_b128 v[240:243], v211 offset:38912
	v_mfma_f32_16x16x32_bf16 v[72:75], v[190:193], v[244:247], v[72:75]
	v_lshl_add_u64 v[250:251], v[142:143], 0, s[54:55]
	v_mfma_f32_16x16x32_bf16 v[88:91], v[194:197], v[244:247], v[88:91]
	v_lshl_add_u64 v[142:143], v[142:143], 0, s[56:57]
	v_mfma_f32_16x16x32_bf16 v[124:127], v[202:205], v[244:247], v[124:127]
	global_load_lds_dwordx4 v[248:249], off
	s_waitcnt lgkmcnt(2)
	v_mfma_f32_16x16x32_bf16 v[0:3], v[186:189], v[232:235], v[0:3]
	ds_read_b128 v[244:247], v211 offset:39936
	v_mfma_f32_16x16x32_bf16 v[16:19], v[190:193], v[232:235], v[16:19]
	ds_read_b128 v[216:219], v148
	v_mfma_f32_16x16x32_bf16 v[32:35], v[194:197], v[232:235], v[32:35]
	ds_read_b128 v[220:223], v148 offset:1024
	v_mfma_f32_16x16x32_bf16 v[60:63], v[202:205], v[232:235], v[60:63]
	ds_read_b128 v[224:227], v148 offset:2048
	s_waitcnt lgkmcnt(5)
	v_mfma_f32_16x16x32_bf16 v[4:7], v[186:189], v[236:239], v[4:7]
	ds_read_b128 v[228:231], v148 offset:3072
	ds_read_b128 v[232:235], v149 offset:16384
	v_mfma_f32_16x16x32_bf16 v[20:23], v[190:193], v[236:239], v[20:23]
	s_mov_b32 m0, s5
	v_mfma_f32_16x16x32_bf16 v[36:39], v[194:197], v[236:239], v[36:39]
	v_readfirstlane_b32 s5, v161
	v_mfma_f32_16x16x32_bf16 v[76:79], v[202:205], v[236:239], v[76:79]
	global_load_lds_dwordx4 v[144:145], off
	s_waitcnt lgkmcnt(6)
	v_mfma_f32_16x16x32_bf16 v[8:11], v[186:189], v[240:243], v[8:11]
	ds_read_b128 v[236:239], v149 offset:17408
	v_mfma_f32_16x16x32_bf16 v[24:27], v[190:193], v[240:243], v[24:27]
	s_mov_b32 m0, s5
	v_mfma_f32_16x16x32_bf16 v[40:43], v[194:197], v[240:243], v[40:43]
	v_readfirstlane_b32 s5, v162
	v_mfma_f32_16x16x32_bf16 v[84:87], v[202:205], v[240:243], v[84:87]
	global_load_lds_dwordx4 v[250:251], off
	s_waitcnt lgkmcnt(6)
	v_mfma_f32_16x16x32_bf16 v[12:15], v[186:189], v[244:247], v[12:15]
	ds_read_b128 v[240:243], v149 offset:18432
	v_mfma_f32_16x16x32_bf16 v[28:31], v[190:193], v[244:247], v[28:31]
	s_mov_b32 m0, s5
	v_mfma_f32_16x16x32_bf16 v[44:47], v[194:197], v[244:247], v[44:47]
	global_load_lds_dwordx4 v[142:143], off
	v_mfma_f32_16x16x32_bf16 v[92:95], v[202:205], v[244:247], v[92:95]
	ds_read_b128 v[244:247], v149 offset:19456
	v_add_u32_e32 v142, 0x19000, v150
	v_add_u32_e32 v143, 0x19400, v150
	v_add_u32_e32 v144, 0x19800, v150
	v_add_u32_e32 v145, 0x19c00, v150
	s_add_u32 s6, s6, 0x8000
	s_addc_u32 s7, s7, 0
	s_cmp_lg_u32 s6, 0x38000
	s_cbranch_scc1 .LBB0_302
	s_waitcnt lgkmcnt(3)
	v_mfma_f32_16x16x32_bf16 v[56:59], v[216:219], v[232:235], v[56:59]
	v_mfma_f32_16x16x32_bf16 v[100:103], v[220:223], v[232:235], v[100:103]
	v_mfma_f32_16x16x32_bf16 v[104:107], v[224:227], v[232:235], v[104:107]
	s_waitcnt vmcnt(4)
	s_barrier
; #define BIG_SYNC(N)                                              \
;   asm volatile("s_waitcnt vmcnt(%0)" ::"n"(N) : "memory");       \
;   __builtin_amdgcn_s_barrier();                                  \
;   asm volatile("" ::: "memory");                                 \
;   __builtin_amdgcn_sched_barrier(0);
; template <int NK, bool BNT = false> ...
;     ...
;   auto kstep = [&](int T, int cur, int nxt, bool do_stage) {
;     const unsigned char* sa = smem + cur * BIG_STAGE;
;     bf16x8 af[4], bfr[4];
; #pragma unroll
;     for (int m = 0; m < 4; ++m) af[m] = *reinterpret_cast<const bf16x8*>(sa + aoff + m * 1024);
; #pragma unroll
;     for (int n = 0; n < 4; ++n) bfr[n] = *reinterpret_cast<const bf16x8*>(sa + boff + n * 1024);
;     __builtin_amdgcn_sched_barrier(0);
;     if (do_stage) stage(T + 3, nxt);
; #pragma unroll
;     for (int m = 0; m < 4; ++m)
; #pragma unroll
;       for (int n = 0; n < 4; ++n) acc[m][n] = __builtin_amdgcn_mfma_f32_16x16x32_bf16(af[m], bfr[n], acc[m][n], 0, 0, 0);
;     if (do_stage) {
; #pragma unroll
;       for (int q = 0; q < NG; ++q) {
;         __builtin_amdgcn_sched_group_barrier(0x008, 3, 0);
;         __builtin_amdgcn_sched_group_barrier(0x010, 1, 0);
;       }
;       __builtin_amdgcn_sched_group_barrier(0x008, 16 - 3 * NG, 0);
;     }
;     __builtin_amdgcn_sched_barrier(0);
; #pragma unroll
;     for (int n = 0; n < 4; ++n) bfr[n] = *reinterpret_cast<const bf16x8*>(sa + boff + (4 + n) * 1024);
; #pragma unroll
;     for (int m = 0; m < 4; ++m)
; #pragma unroll
;       for (int n = 0; n < 4; ++n)
;         acc[m][4 + n] = __builtin_amdgcn_mfma_f32_16x16x32_bf16(af[m], bfr[n], acc[m][4 + n], 0, 0, 0);
;     __builtin_amdgcn_sched_barrier(0);
;   };
;     ...
;   stage(0, 0);
;   stage(1, 1);
;   stage(2, 2);
;   for (int it = 0; it < NK / 4 - 1; ++it) {
;     const int t = it * 4;
;     BIG_SYNC(2 * NG); kstep(t, 0, 3, true);
;     BIG_SYNC(2 * NG); kstep(t + 1, 1, 0, true);
;     BIG_SYNC(2 * NG); kstep(t + 2, 2, 1, true);
;     BIG_SYNC(2 * NG); kstep(t + 3, 3, 2, true);
;   }
;   BIG_SYNC(2 * NG); kstep(NK - 4, 0, 3, true);
;   BIG_SYNC(2 * NG); kstep(NK - 3, 1, 0, false);
;   BIG_SYNC(NG);     kstep(NK - 2, 2, 0, false);
;   BIG_SYNC(0);      kstep(NK - 1, 3, 0, false);
	s_sext_i32_i8 s4, s4
	v_mfma_f32_16x16x32_bf16 v[112:115], v[228:231], v[232:235], v[112:115]
	s_mov_b64 s[6:7], 0x3e000
	s_waitcnt lgkmcnt(2)
	v_mfma_f32_16x16x32_bf16 v[64:67], v[216:219], v[236:239], v[64:67]
	ds_read_b128 v[232:235], v149 offset:20480
	v_mfma_f32_16x16x32_bf16 v[80:83], v[220:223], v[236:239], v[80:83]
	v_readfirstlane_b32 s5, v163
	v_mfma_f32_16x16x32_bf16 v[96:99], v[224:227], v[236:239], v[96:99]
	v_lshl_add_u64 v[198:199], v[136:137], 0, s[6:7]
	v_mfma_f32_16x16x32_bf16 v[116:119], v[228:231], v[236:239], v[116:119]
	v_lshl_add_u64 v[200:201], v[134:135], 0, s[6:7]
	s_waitcnt lgkmcnt(2)
	v_mfma_f32_16x16x32_bf16 v[52:55], v[216:219], v[240:243], v[52:55]
	ds_read_b128 v[236:239], v149 offset:21504
	v_mfma_f32_16x16x32_bf16 v[68:71], v[220:223], v[240:243], v[68:71]
	s_mov_b32 m0, s5
	v_mfma_f32_16x16x32_bf16 v[108:111], v[224:227], v[240:243], v[108:111]
	s_mov_b64 s[6:7], 0x7e000
	v_mfma_f32_16x16x32_bf16 v[120:123], v[228:231], v[240:243], v[120:123]
	v_readfirstlane_b32 s5, v164
	s_waitcnt lgkmcnt(2)
	v_mfma_f32_16x16x32_bf16 v[48:51], v[216:219], v[244:247], v[48:51]
	ds_read_b128 v[240:243], v149 offset:22528
	v_mfma_f32_16x16x32_bf16 v[72:75], v[220:223], v[244:247], v[72:75]
	v_lshl_add_u64 v[136:137], v[136:137], 0, s[6:7]
	v_mfma_f32_16x16x32_bf16 v[88:91], v[224:227], v[244:247], v[88:91]
	v_lshl_add_u64 v[134:135], v[134:135], 0, s[6:7]
	v_mfma_f32_16x16x32_bf16 v[124:127], v[228:231], v[244:247], v[124:127]
	global_load_lds_dwordx4 v[198:199], off
	s_waitcnt lgkmcnt(2)
	v_mfma_f32_16x16x32_bf16 v[0:3], v[216:219], v[232:235], v[0:3]
	ds_read_b128 v[244:247], v149 offset:23552
	v_mfma_f32_16x16x32_bf16 v[16:19], v[220:223], v[232:235], v[16:19]
	ds_read_b128 v[186:189], v148 offset:32768
	v_mfma_f32_16x16x32_bf16 v[32:35], v[224:227], v[232:235], v[32:35]
	ds_read_b128 v[190:193], v148 offset:33792
	v_mfma_f32_16x16x32_bf16 v[60:63], v[228:231], v[232:235], v[60:63]
	ds_read_b128 v[194:197], v148 offset:34816
	s_waitcnt lgkmcnt(5)
	v_mfma_f32_16x16x32_bf16 v[4:7], v[216:219], v[236:239], v[4:7]
	ds_read_b128 v[202:205], v148 offset:35840
	ds_read_b128 v[232:235], v149 offset:49152
	v_mfma_f32_16x16x32_bf16 v[20:23], v[220:223], v[236:239], v[20:23]
	s_mov_b32 m0, s5
	v_mfma_f32_16x16x32_bf16 v[36:39], v[224:227], v[236:239], v[36:39]
	v_readfirstlane_b32 s5, v165
	v_mfma_f32_16x16x32_bf16 v[76:79], v[228:231], v[236:239], v[76:79]
	global_load_lds_dwordx4 v[136:137], off
	s_waitcnt lgkmcnt(6)
	v_mfma_f32_16x16x32_bf16 v[8:11], v[216:219], v[240:243], v[8:11]
	ds_read_b128 v[236:239], v149 offset:50176
	v_mfma_f32_16x16x32_bf16 v[24:27], v[220:223], v[240:243], v[24:27]
	s_mov_b32 m0, s5
	v_mfma_f32_16x16x32_bf16 v[40:43], v[224:227], v[240:243], v[40:43]
	v_readfirstlane_b32 s5, v166
	v_mfma_f32_16x16x32_bf16 v[84:87], v[228:231], v[240:243], v[84:87]
	global_load_lds_dwordx4 v[200:201], off
	s_waitcnt lgkmcnt(6)
	v_mfma_f32_16x16x32_bf16 v[12:15], v[216:219], v[244:247], v[12:15]
	ds_read_b128 v[240:243], v149 offset:51200
	v_mfma_f32_16x16x32_bf16 v[28:31], v[220:223], v[244:247], v[28:31]
	s_mov_b32 m0, s5
	v_mfma_f32_16x16x32_bf16 v[44:47], v[224:227], v[244:247], v[44:47]
	global_load_lds_dwordx4 v[134:135], off
	v_mfma_f32_16x16x32_bf16 v[92:95], v[228:231], v[244:247], v[92:95]
	ds_read_b128 v[244:247], v149 offset:52224
	s_waitcnt lgkmcnt(3)
	v_mfma_f32_16x16x32_bf16 v[56:59], v[186:189], v[232:235], v[56:59]
	v_mfma_f32_16x16x32_bf16 v[100:103], v[190:193], v[232:235], v[100:103]
	v_mfma_f32_16x16x32_bf16 v[104:107], v[194:197], v[232:235], v[104:107]
	v_mfma_f32_16x16x32_bf16 v[112:115], v[202:205], v[232:235], v[112:115]
	s_waitcnt vmcnt(4)
	s_barrier
	s_waitcnt lgkmcnt(2)
	v_mfma_f32_16x16x32_bf16 v[64:67], v[186:189], v[236:239], v[64:67]
	ds_read_b128 v[232:235], v149 offset:53248
	v_mfma_f32_16x16x32_bf16 v[80:83], v[190:193], v[236:239], v[80:83]
	v_mfma_f32_16x16x32_bf16 v[96:99], v[194:197], v[236:239], v[96:99]
	v_mfma_f32_16x16x32_bf16 v[116:119], v[202:205], v[236:239], v[116:119]
	s_waitcnt lgkmcnt(2)
	v_mfma_f32_16x16x32_bf16 v[52:55], v[186:189], v[240:243], v[52:55]
	ds_read_b128 v[236:239], v149 offset:54272
	v_mfma_f32_16x16x32_bf16 v[68:71], v[190:193], v[240:243], v[68:71]
	v_mfma_f32_16x16x32_bf16 v[108:111], v[194:197], v[240:243], v[108:111]
	v_mfma_f32_16x16x32_bf16 v[120:123], v[202:205], v[240:243], v[120:123]
	s_waitcnt lgkmcnt(2)
	v_mfma_f32_16x16x32_bf16 v[48:51], v[186:189], v[244:247], v[48:51]
	ds_read_b128 v[240:243], v149 offset:55296
	v_mfma_f32_16x16x32_bf16 v[72:75], v[190:193], v[244:247], v[72:75]
	v_mfma_f32_16x16x32_bf16 v[88:91], v[194:197], v[244:247], v[88:91]
	v_mfma_f32_16x16x32_bf16 v[124:127], v[202:205], v[244:247], v[124:127]
	s_waitcnt lgkmcnt(2)
	v_mfma_f32_16x16x32_bf16 v[0:3], v[186:189], v[232:235], v[0:3]
	ds_read_b128 v[244:247], v149 offset:56320
	v_mfma_f32_16x16x32_bf16 v[16:19], v[190:193], v[232:235], v[16:19]
	v_mfma_f32_16x16x32_bf16 v[32:35], v[194:197], v[232:235], v[32:35]
	v_mfma_f32_16x16x32_bf16 v[60:63], v[202:205], v[232:235], v[60:63]
	s_waitcnt lgkmcnt(2)
	v_mfma_f32_16x16x32_bf16 v[4:7], v[186:189], v[236:239], v[4:7]
	v_mfma_f32_16x16x32_bf16 v[20:23], v[190:193], v[236:239], v[20:23]
	v_mfma_f32_16x16x32_bf16 v[36:39], v[194:197], v[236:239], v[36:39]
	v_mfma_f32_16x16x32_bf16 v[76:79], v[202:205], v[236:239], v[76:79]
	s_waitcnt lgkmcnt(1)
	v_mfma_f32_16x16x32_bf16 v[8:11], v[186:189], v[240:243], v[8:11]
	v_mfma_f32_16x16x32_bf16 v[24:27], v[190:193], v[240:243], v[24:27]
	v_mfma_f32_16x16x32_bf16 v[40:43], v[194:197], v[240:243], v[40:43]
	v_mfma_f32_16x16x32_bf16 v[84:87], v[202:205], v[240:243], v[84:87]
	s_waitcnt lgkmcnt(0)
	v_mfma_f32_16x16x32_bf16 v[12:15], v[186:189], v[244:247], v[12:15]
	v_mfma_f32_16x16x32_bf16 v[28:31], v[190:193], v[244:247], v[28:31]
	v_mfma_f32_16x16x32_bf16 v[44:47], v[194:197], v[244:247], v[44:47]
	v_mfma_f32_16x16x32_bf16 v[92:95], v[202:205], v[244:247], v[92:95]
	v_mov_b32_e32 v186, 0xf149f2ca
	v_mov_b32_e32 v187, 0x3c0881c4
	v_mov_b32_e32 v188, 0xbab64f3b
	v_mov_b32_e32 v189, 0x24800
	v_mov_b32_e32 v190, 1
	v_mov_b32_e32 v191, 0x24804
	v_mov_b32_e32 v192, 0xfcf
	v_mov_b32_e32 v193, 0x7cf
	v_mov_b32_e32 v194, 0xfdf
	v_mov_b32_e32 v195, 0x7df
	v_mov_b32_e32 v196, 0xfef
	v_mov_b32_e32 v197, 0x7ef
	v_mov_b32_e32 v198, 0xfff
	v_mov_b32_e32 v199, 0x7ff
	v_mov_b32_e32 v200, 0x20000
	v_mov_b32_e32 v201, 0xf8f
	v_mov_b32_e32 v202, 0x78f
	v_mov_b32_e32 v203, 0xf9f
	v_mov_b32_e32 v204, 0x79f
	v_mov_b32_e32 v205, 0xfaf
	v_mov_b32_e32 v210, 0x7f800000
	v_not_b32_e32 v211, 63
	v_not_b32_e32 v212, 31
	v_mov_b32_e32 v213, 0x7fc00000
	s_waitcnt vmcnt(4)
	s_barrier
; #define BIG_SYNC(N)                                              \
;   asm volatile("s_waitcnt vmcnt(%0)" ::"n"(N) : "memory");       \
;   __builtin_amdgcn_s_barrier();                                  \
;   asm volatile("" ::: "memory");                                 \
;   __builtin_amdgcn_sched_barrier(0);
; template <int NK, bool BNT = false> ...
;     ...
;   BIG_SYNC(2 * NG); kstep(NK - 4, 0, 3, true);
;   BIG_SYNC(2 * NG); kstep(NK - 3, 1, 0, false);
;   BIG_SYNC(NG);     kstep(NK - 2, 2, 0, false);
;   BIG_SYNC(0);      kstep(NK - 1, 3, 0, false);
; template <int MODE, int NSUB>
; __device__ __forceinline__ void epilogue(const Params& p, int layer, f32x4 (&acc)[4][NSUB], int tm, int tn, int g,
;                                          const float* s_rstd, const int tid_in) {
;     ...
;   const int lane = tid & 63, wid = tid >> 6, wr = wid >> 1, wc = wid & 1, fr = lane & 15, fq = lane >> 4;
;   if constexpr (MODE == EPI_G1) {
;     const int ft = tm;
; #pragma unroll
;     for (int n = 0; n < NSUB; ++n) {
;       const int nl = wc * (NSUB * 16) + n * 16 + fr;
;       const int t = tn * (NSUB * 32) + nl;
;       const float rs = s_rstd[nl];
;       if (ft < 2) {
; #pragma unroll
;         for (int m = 0; m < 4; ++m) {
;           int gg = ft * 8 + wr * 4 + m;
;           bf16x4 v = pack4(acc[m][n][0] * rs, acc[m][n][1] * rs, acc[m][n][2] * rs, acc[m][n][3] * rs);
;           *reinterpret_cast<bf16x4*>(p.ug + (long)gg * NT * 16 + blk(t >> 5, (t & 31) * 16 + fq * 4, 16)) = v;
;         }
;       } else if (ft < 4) {
	ds_read_b128 v[134:137], v167
	ds_read_b128 v[138:141], v167 offset:1024
	ds_read_b128 v[154:157], v167 offset:2048
	ds_read_b128 v[158:161], v167 offset:3072
	ds_read_b128 v[162:165], v168
	ds_read_b128 v[166:169], v169
	ds_read_b128 v[216:219], v170
	ds_read_b128 v[220:223], v172
	s_waitcnt lgkmcnt(0)
	v_mfma_f32_16x16x32_bf16 v[56:59], v[134:137], v[162:165], v[56:59]
	v_mfma_f32_16x16x32_bf16 v[64:67], v[134:137], v[166:169], v[64:67]
	v_mfma_f32_16x16x32_bf16 v[52:55], v[134:137], v[216:219], v[52:55]
	v_mfma_f32_16x16x32_bf16 v[48:51], v[134:137], v[220:223], v[48:51]
	v_mfma_f32_16x16x32_bf16 v[100:103], v[138:141], v[162:165], v[100:103]
	v_mfma_f32_16x16x32_bf16 v[80:83], v[138:141], v[166:169], v[80:83]
	v_mfma_f32_16x16x32_bf16 v[68:71], v[138:141], v[216:219], v[68:71]
	v_mfma_f32_16x16x32_bf16 v[72:75], v[138:141], v[220:223], v[72:75]
	v_mfma_f32_16x16x32_bf16 v[96:99], v[154:157], v[166:169], v[96:99]
	v_mfma_f32_16x16x32_bf16 v[112:115], v[158:161], v[162:165], v[112:115]
	v_mfma_f32_16x16x32_bf16 v[224:227], v[154:157], v[162:165], v[104:107]
	v_mfma_f32_16x16x32_bf16 v[228:231], v[154:157], v[216:219], v[108:111]
	v_mfma_f32_16x16x32_bf16 v[232:235], v[154:157], v[220:223], v[88:91]
	v_mfma_f32_16x16x32_bf16 v[162:165], v[158:161], v[166:169], v[116:119]
	v_mfma_f32_16x16x32_bf16 v[166:169], v[158:161], v[216:219], v[120:123]
	v_mfma_f32_16x16x32_bf16 v[216:219], v[158:161], v[220:223], v[124:127]
	ds_read_b128 v[88:91], v173
	ds_read_b128 v[104:107], v174
	ds_read_b128 v[108:111], v175
	ds_read_b128 v[116:119], v178
	s_waitcnt lgkmcnt(0)
	v_mfma_f32_16x16x32_bf16 v[0:3], v[134:137], v[88:91], v[0:3]
	v_mfma_f32_16x16x32_bf16 v[4:7], v[134:137], v[104:107], v[4:7]
	v_mfma_f32_16x16x32_bf16 v[8:11], v[134:137], v[108:111], v[8:11]
	v_mfma_f32_16x16x32_bf16 v[12:15], v[134:137], v[116:119], v[12:15]
	v_mfma_f32_16x16x32_bf16 v[16:19], v[138:141], v[88:91], v[16:19]
	v_mfma_f32_16x16x32_bf16 v[20:23], v[138:141], v[104:107], v[20:23]
	v_mfma_f32_16x16x32_bf16 v[24:27], v[138:141], v[108:111], v[24:27]
	v_mfma_f32_16x16x32_bf16 v[134:137], v[138:141], v[116:119], v[28:31]
	v_mfma_f32_16x16x32_bf16 v[32:35], v[154:157], v[88:91], v[32:35]
	v_mfma_f32_16x16x32_bf16 v[36:39], v[154:157], v[104:107], v[36:39]
	v_mfma_f32_16x16x32_bf16 v[138:141], v[154:157], v[108:111], v[40:43]
	v_mfma_f32_16x16x32_bf16 v[154:157], v[154:157], v[116:119], v[44:47]
	v_mfma_f32_16x16x32_bf16 v[172:175], v[158:161], v[88:91], v[60:63]
	v_mfma_f32_16x16x32_bf16 v[220:223], v[158:161], v[104:107], v[76:79]
	v_mfma_f32_16x16x32_bf16 v[236:239], v[158:161], v[108:111], v[84:87]
	v_mfma_f32_16x16x32_bf16 v[158:161], v[158:161], v[116:119], v[92:95]
	s_waitcnt vmcnt(0)
	s_barrier
	ds_read_b128 v[40:43], v176
	ds_read_b128 v[28:31], v179
	ds_read_b128 v[44:47], v180
	ds_read_b128 v[60:63], v181
	ds_read_b128 v[240:243], v176 offset:1024
	ds_read_b128 v[244:247], v176 offset:2048
	ds_read_b128 v[248:251], v176 offset:3072
	ds_read_b128 v[178:181], v182
	s_waitcnt lgkmcnt(0)
	v_mfma_f32_16x16x32_bf16 v[124:127], v[40:43], v[28:31], v[56:59]
	v_mfma_f32_16x16x32_bf16 v[108:111], v[40:43], v[44:47], v[64:67]
	v_mfma_f32_16x16x32_bf16 v[92:95], v[40:43], v[60:63], v[52:55]
	v_mfma_f32_16x16x32_bf16 v[76:79], v[40:43], v[178:181], v[48:51]
	v_mfma_f32_16x16x32_bf16 v[120:123], v[240:243], v[28:31], v[100:103]
	v_mfma_f32_16x16x32_bf16 v[104:107], v[240:243], v[44:47], v[80:83]
	v_mfma_f32_16x16x32_bf16 v[88:91], v[240:243], v[60:63], v[68:71]
	v_mfma_f32_16x16x32_bf16 v[72:75], v[240:243], v[178:181], v[72:75]
	v_mfma_f32_16x16x32_bf16 v[116:119], v[244:247], v[28:31], v[224:227]
	v_mfma_f32_16x16x32_bf16 v[100:103], v[244:247], v[44:47], v[96:99]
	v_mfma_f32_16x16x32_bf16 v[84:87], v[244:247], v[60:63], v[228:231]
	v_mfma_f32_16x16x32_bf16 v[68:71], v[244:247], v[178:181], v[232:235]
	v_mfma_f32_16x16x32_bf16 v[112:115], v[248:251], v[28:31], v[112:115]
	v_mfma_f32_16x16x32_bf16 v[96:99], v[248:251], v[44:47], v[162:165]
	v_mfma_f32_16x16x32_bf16 v[80:83], v[248:251], v[60:63], v[166:169]
	v_mfma_f32_16x16x32_bf16 v[64:67], v[248:251], v[178:181], v[216:219]
	ds_read_b128 v[48:51], v142
	ds_read_b128 v[162:165], v143
	s_waitcnt lgkmcnt(0)
	v_mfma_f32_16x16x32_bf16 v[60:63], v[40:43], v[48:51], v[0:3]
	s_nop 2
	ds_read_b128 v[0:3], v144
	ds_read_b128 v[142:145], v145
	v_mfma_f32_16x16x32_bf16 v[44:47], v[40:43], v[162:165], v[4:7]
	s_waitcnt lgkmcnt(0)
	v_mfma_f32_16x16x32_bf16 v[28:31], v[40:43], v[0:3], v[8:11]
	v_mfma_f32_16x16x32_bf16 v[12:15], v[40:43], v[142:145], v[12:15]
	v_mfma_f32_16x16x32_bf16 v[56:59], v[240:243], v[48:51], v[16:19]
	v_mfma_f32_16x16x32_bf16 v[40:43], v[240:243], v[162:165], v[20:23]
	v_mfma_f32_16x16x32_bf16 v[24:27], v[240:243], v[0:3], v[24:27]
	v_mfma_f32_16x16x32_bf16 v[8:11], v[240:243], v[142:145], v[134:137]
	v_mfma_f32_16x16x32_bf16 v[52:55], v[244:247], v[48:51], v[32:35]
	v_mfma_f32_16x16x32_bf16 v[36:39], v[244:247], v[162:165], v[36:39]
	v_mfma_f32_16x16x32_bf16 v[20:23], v[244:247], v[0:3], v[138:141]
	v_mfma_f32_16x16x32_bf16 v[4:7], v[244:247], v[142:145], v[154:157]
	v_mfma_f32_16x16x32_bf16 v[48:51], v[248:251], v[48:51], v[172:175]
	v_mfma_f32_16x16x32_bf16 v[32:35], v[248:251], v[162:165], v[220:223]
	v_mfma_f32_16x16x32_bf16 v[16:19], v[248:251], v[0:3], v[236:239]
	v_mfma_f32_16x16x32_bf16 v[0:3], v[248:251], v[142:145], v[158:161]
	v_mov_b32_e32 v141, v215
	v_lshl_add_u32 v142, s4, 1, v151
	v_and_b32_e32 v140, 15, v141
	v_lshlrev_b32_e32 v134, 1, v141
	v_and_or_b32 v155, v134, s34, v140
	v_lshl_or_b32 v139, v155, 2, v200
	v_and_b32_e32 v134, 16, v141
	v_lshrrev_b32_e32 v138, 2, v141
	ds_read_b32 v146, v139
	v_ashrrev_i32_e32 v136, 7, v141
	v_and_or_b32 v134, v138, 8, v134
	v_lshlrev_b32_e32 v138, 7, v142
	v_lshl_add_u32 v138, v136, 6, v138
	v_bfe_u32 v137, v141, 4, 2
	v_add_u32_e32 v154, 0xfffffe00, v138
	v_or_b32_e32 v138, v138, v134
	v_cmp_lt_i32_e64 s[14:15], 1, v142
	v_cmp_lt_u32_e64 s[12:13], 3, v142
	v_cmp_lt_u32_e64 s[10:11], 5, v142
	v_cmp_ne_u32_e64 s[8:9], 6, v142
	v_cmp_gt_u32_e64 s[6:7], s34, v141
	v_lshlrev_b32_e32 v135, 2, v137
	v_cmp_eq_u32_e64 s[4:5], 0, v137
	v_ashrrev_i32_e32 v137, 31, v136
	v_lshlrev_b32_e32 v152, 1, v142
	v_add_u32_e32 v138, 0xffffff00, v138
	v_or_b32_e32 v144, s48, v155
	s_and_saveexec_b64 s[18:19], s[14:15]
	s_xor_b64 s[36:37], exec, s[18:19]
	s_cbranch_execz .LBB0_323
; __device__ __forceinline__ int widen_off(int fq) { return ((fq & 1) << 4) + ((fq >> 1) << 3); }
; template <int MODE, int NSUB>
; __device__ __forceinline__ void epilogue(const Params& p, int layer, f32x4 (&acc)[4][NSUB], int tm, int tn, int g,
;                                          const float* s_rstd, const int tid_in) {
;     ...
;         if (wr == 0) {
;           const int pos = tok_pos(t);
;           float o1[4], o2[4];
; #pragma unroll
;           for (int j = 0; j < 4; ++j) {
;             float2 cs = p.rope[pos * 16 + fq * 4 + j];
;             float x1 = acc[0][n][j] * rs, x2 = acc[1][n][j] * rs;
;             o1[j] = x1 * cs.x - x2 * cs.y;
;             o2[j] = x1 * cs.y + x2 * cs.x;
;           }
;           const u32x4 w = widen_pair(pack4(o1[0], o1[1], o1[2], o1[3]), pack4(o2[0], o2[1], o2[2], o2[3]));
; #pragma unroll
;           for (int hh = 0; hh < 8; ++hh)
;             __builtin_nontemporal_store(w, reinterpret_cast<u32x4*>(p.Kb + ((long)hh * NT + t) * 96 + 64 + widen_off(fq)));
;         }
	s_and_saveexec_b64 s[18:19], s[12:13]
	s_xor_b64 s[38:39], exec, s[18:19]
	s_cbranch_execz .LBB0_320
	s_and_saveexec_b64 s[18:19], s[10:11]
	s_xor_b64 s[40:41], exec, s[18:19]
	s_cbranch_execz .LBB0_315
	s_and_saveexec_b64 s[18:19], s[8:9]
	s_xor_b64 s[42:43], exec, s[18:19]
	s_cbranch_execz .LBB0_310
	s_and_saveexec_b64 s[44:45], s[6:7]
	s_cbranch_execz .LBB0_309
	s_mov_b32 s17, 0x10000
	v_cmp_gt_i32_e32 vcc, s17, v144
	v_lshlrev_b32_e32 v113, 3, v135
	v_readlane_b32 s64, v254, 51
	v_cndmask_b32_e32 v112, v201, v202, vcc
	v_and_b32_e32 v112, v112, v144
	v_lshl_or_b32 v116, v112, 7, v113
	v_readlane_b32 s70, v254, 57
	v_readlane_b32 s71, v254, 58
	s_nop 4
	global_load_dwordx4 v[112:115], v116, s[70:71] offset:16
	s_nop 0
	global_load_dwordx4 v[116:119], v116, s[70:71]
	v_mov_b32_e32 v161, v121
	v_mov_b32_e32 v121, v125
	v_mov_b32_e32 v160, v124
	s_waitcnt lgkmcnt(0)
	v_pk_mul_f32 v[120:121], v[120:121], v[146:147] op_sel_hi:[1,0]
	v_pk_mul_f32 v[160:161], v[160:161], v[146:147] op_sel_hi:[1,0]
	v_readlane_b32 s65, v254, 52
	v_readlane_b32 s66, v254, 53
	v_readlane_b32 s67, v254, 54
	v_readlane_b32 s68, v254, 55
	v_readlane_b32 s69, v254, 56
	v_readlane_b32 s72, v254, 59
	v_readlane_b32 s73, v254, 60
	v_readlane_b32 s74, v254, 61
	v_readlane_b32 s75, v254, 62
	v_readlane_b32 s76, v254, 63
	v_readlane_b32 s77, v252, 0
	v_readlane_b32 s78, v252, 1
	v_readlane_b32 s79, v252, 2
	v_readlane_b32 s64, v252, 4
	v_readlane_b32 s68, v252, 8
	v_readlane_b32 s69, v252, 9
	s_movk_i32 s17, 0xc0
	v_readlane_b32 s65, v252, 5
	v_readlane_b32 s66, v252, 6
	v_readlane_b32 s67, v252, 7
	v_readlane_b32 s70, v252, 10
	v_readlane_b32 s71, v252, 11
	v_readlane_b32 s72, v252, 12
	v_readlane_b32 s73, v252, 13
	v_readlane_b32 s74, v252, 14
	v_readlane_b32 s75, v252, 15
	v_readlane_b32 s76, v252, 16
	v_readlane_b32 s77, v252, 17
	v_readlane_b32 s78, v252, 18
	v_readlane_b32 s79, v252, 19
	s_waitcnt vmcnt(0)
	v_mov_b32_e32 v159, v114
	v_mov_b32_e32 v124, v116
	v_mov_b32_e32 v125, v119
	v_mov_b32_e32 v156, v117
	v_mov_b32_e32 v157, v118
	v_pk_mul_f32 v[124:125], v[120:121], v[124:125]
	v_mov_b32_e32 v163, v118
	v_pk_fma_f32 v[124:125], v[160:161], v[156:157], v[124:125]
	v_mov_b32_e32 v157, v121
	v_mov_b32_e32 v121, v161
	v_mov_b32_e32 v118, v117
	v_mov_b32_e32 v162, v116
	v_pk_mul_f32 v[116:117], v[120:121], v[118:119]
	v_mov_b32_e32 v118, v126
	v_mov_b32_e32 v119, v123
	v_mov_b32_e32 v123, v127
	v_mov_b32_e32 v156, v160
	v_pk_mul_f32 v[118:119], v[118:119], v[146:147] op_sel_hi:[1,0]
	v_pk_mul_f32 v[120:121], v[122:123], v[146:147] op_sel_hi:[1,0]
	v_mov_b32_e32 v122, v112
	v_mov_b32_e32 v123, v115
	v_pk_fma_f32 v[116:117], v[156:157], v[162:163], v[116:117] neg_lo:[0,0,1] neg_hi:[0,0,1]
	v_pk_mul_f32 v[122:123], v[120:121], v[122:123]
	v_mov_b32_e32 v127, v121
	v_mov_b32_e32 v157, v114
	v_mov_b32_e32 v121, v119
	v_mov_b32_e32 v114, v113
	v_mov_b32_e32 v158, v113
	v_mov_b32_e32 v126, v118
	v_mov_b32_e32 v156, v112
	v_pk_mul_f32 v[112:113], v[120:121], v[114:115]
	v_pk_fma_f32 v[122:123], v[118:119], v[158:159], v[122:123]
	v_pk_fma_f32 v[114:115], v[126:127], v[156:157], v[112:113] neg_lo:[0,0,1] neg_hi:[0,0,1]
	v_cvt_pk_bf16_f32 v112, v116, v117
	v_mov_b64_e32 v[116:117], s[68:69]
	v_mad_i64_i32 v[116:117], s[18:19], v144, s17, v[116:117]
	v_lshlrev_b32_e32 v118, 1, v134
	v_mov_b32_e32 v119, v153
	v_lshl_add_u64 v[116:117], v[116:117], 0, v[118:119]
	s_mov_b32 s17, 0xf00000
	v_cvt_pk_bf16_f32 v113, v114, v115
	v_cvt_pk_bf16_f32 v114, v124, v125
	v_cvt_pk_bf16_f32 v115, v122, v123
	v_add_co_u32_e32 v118, vcc, s17, v116
	v_permlane16_swap_b32_e32 v112, v114
	v_permlane16_swap_b32_e32 v113, v115
	v_addc_co_u32_e32 v119, vcc, 0, v117, vcc
	s_mov_b32 s17, 0x1e00000
	global_store_dwordx4 v[118:119], v[112:115], off offset:128 nt
	v_add_co_u32_e32 v118, vcc, s17, v116
	s_mov_b32 s17, 0x2d00000
	s_nop 0
	v_addc_co_u32_e32 v119, vcc, 0, v117, vcc
	global_store_dwordx4 v[118:119], v[112:115], off offset:128 nt
	v_add_co_u32_e32 v118, vcc, s17, v116
	global_store_dwordx4 v[116:117], v[112:115], off offset:128 nt
	s_nop 0
	v_addc_co_u32_e32 v119, vcc, 0, v117, vcc
	global_store_dwordx4 v[118:119], v[112:115], off offset:128 nt
	v_add_co_u32_e32 v118, vcc, 0x3c00000, v116
	s_nop 1
	v_addc_co_u32_e32 v119, vcc, 0, v117, vcc
	global_store_dwordx4 v[118:119], v[112:115], off offset:128 nt
	v_add_co_u32_e32 v118, vcc, 0x4b00000, v116
	s_nop 1
	v_addc_co_u32_e32 v119, vcc, 0, v117, vcc
	global_store_dwordx4 v[118:119], v[112:115], off offset:128 nt
	v_add_co_u32_e32 v118, vcc, 0x5a00000, v116
	s_nop 1
	v_addc_co_u32_e32 v119, vcc, 0, v117, vcc
	v_add_co_u32_e32 v116, vcc, 0x6900000, v116
	global_store_dwordx4 v[118:119], v[112:115], off offset:128 nt
	s_nop 0
	v_addc_co_u32_e32 v117, vcc, 0, v117, vcc
	global_store_dwordx4 v[116:117], v[112:115], off offset:128 nt
